# half-tile pairing (row halves, reduced A staging) in the partial last round of resid and up GEMMs; transposes moved off the paired WGs
# speedup vs baseline: 1.0790x; 1.0362x over previous
; #define LAS __attribute__((address_space(3)))
; __device__ __forceinline__ unsigned xb_add(unsigned* p, unsigned v) { return __hip_atomic_fetch_add(p, v, __ATOMIC_RELAXED, __HIP_MEMORY_SCOPE_AGENT); }
; __device__ __forceinline__ unsigned xb_xcc_id() { return (unsigned)__builtin_amdgcn_s_getreg((3 << 11) | 20) & 0xFu; }
; __device__ __forceinline__ XcdBarrier xcd_barrier_post(unsigned* bar, volatile LAS unsigned* st) {
;     XcdBarrier b; b.bar = bar; b.x = xb_xcc_id(); b.st = st;
;     if (threadIdx.x == 0) (void)xb_add(&bar[XB_XCNT(b.x)], 1u);
;     return b;
; __global__ void __launch_bounds__(NTHREADS) mega_fwd(P p) {
;     ...
;     volatile LAS unsigned* MISC = (volatile LAS unsigned*)(LDSL + LDS_MISC);
;     if (threadIdx.x < 16) MISC[threadIdx.x] = 0u;
;     __syncthreads();
;     XcdBarrier bar = xcd_barrier_post((unsigned*)p.ws, MISC);
_Z8mega_fwd1P:
	s_mov_b32 s100, 0
	s_mov_b32 s101, 0
	s_mov_b64 s[92:93], s[0:1]
	s_load_dwordx4 s[36:39], s[0:1], 0xa8
	s_nop 0
	s_load_dword s1, s[0:1], 0xb8
	s_mov_b32 s90, s2
	s_add_u32 s2, s92, 0xb0
	v_and_b32_e32 v184, 0x3ff, v0
	s_addc_u32 s3, s93, 0
	v_cmp_gt_u32_e32 vcc, 16, v184
	s_and_saveexec_b64 s[4:5], vcc
	v_lshl_add_u32 v1, v184, 2, 0
	v_add_u32_e32 v1, 0x26000, v1
	v_mov_b32_e32 v2, 0
	ds_write_b32 v1, v2
	s_or_b64 exec, exec, s[4:5]
	s_waitcnt lgkmcnt(0)
	s_barrier
	s_getreg_b32 s0, hwreg(HW_REG_XCC_ID, 0, 4)
	s_and_b32 s0, s0, 15
	s_mov_b32 s12, 0
	v_cmp_ne_u32_e64 s[6:7], 0, v184
	v_cmp_eq_u32_e64 s[8:9], 0, v184
	s_mov_b64 s[4:5], exec
	s_nop 0
	v_writelane_b32 v253, s8, 0
	s_nop 1
	v_writelane_b32 v253, s9, 1
	s_and_b64 s[8:9], s[4:5], s[8:9]
	s_mov_b64 exec, s[8:9]
	s_cbranch_execz .LBB0_5
	s_mov_b64 s[8:9], exec
	v_mbcnt_lo_u32_b32 v1, s8, 0
	v_mbcnt_hi_u32_b32 v1, s9, v1
	v_cmp_eq_u32_e32 vcc, 0, v1
	s_and_b64 s[10:11], exec, vcc
	s_mov_b64 exec, s[10:11]
	s_cbranch_execz .LBB0_5
	s_lshl_b32 s10, s0, 8
	s_bcnt1_i32_b64 s8, s[8:9]
	v_mov_b32_e32 v1, s10
	v_mov_b32_e32 v2, s8
	global_atomic_add v1, v2, s[36:37] offset:1024

;     __host__ __device__ bool next(int i, Unit& u) const {
;         const long L = (long)i * G + c; if (L >= nwg) return false;
;         int wgid = (int)L; { const int q = nwg / NXCD, r = nwg % NXCD, xcd = wgid % NXCD, off = wgid / NXCD; wgid = (xcd < r ? xcd * (q + 1) : r * (q + 1) + (xcd - r) * q) + off; }
;         const int nig = WGM * nN, gid = wgid / nig, fm = gid * WGM, gsz = (nM - fm) < WGM ? (nM - fm) : WGM;
;         u.pm = fm + ((wgid % nig) % gsz); u.pn = (wgid % nig) / gsz; return true;
; template <class Epi, class Sched, bool ALIGN_EPI = false, bool SP2 = false>
; __device__ __forceinline__ void gemm_phase(PG8_LAS unsigned char* lds, const Gemm g, const Sched& S, const Epi& E) {
;     ...
; #pragma unroll
;         for (int a = 0; a < 2; ++a)
; #pragma unroll
;             for (int b = 0; b < 2; ++b)
; #pragma unroll
;                 for (int m = 0; m < 4; ++m)
; #pragma unroll
;                     for (int n = 0; n < 2; ++n) acc[a][b][m][n] = (f32x4){0.f, 0.f, 0.f, 0.f};
.LBB0_160:
	s_mov_b32 s101, s100
	s_add_i32 s86, s86, 1
	s_mul_i32 s6, s86, s39
	s_mul_hi_u32 s7, s86, s38
	s_add_i32 s7, s7, s6
	s_mul_i32 s6, s86, s38
	s_add_u32 s22, s6, s90
	s_addc_u32 s23, s7, s91
	s_sub_i32 s72, s22, s90
	s_sub_i32 s73, s10, s72
	s_mov_b32 s100, 0
	s_cmp_lt_i32 s73, 1
	s_cbranch_scc1 .Lhu_done
	s_lshl_b32 s74, s73, 1
	s_cmp_gt_u32 s74, s38
	s_cbranch_scc1 .Lhu_done
	s_cmp_lt_u32 s90, s73
	s_cbranch_scc0 .Lhu_second
	s_mov_b32 s100, 1
	s_branch .Lhu_done
.Lhu_second:
	s_cmp_lt_u32 s90, s74
	s_cbranch_scc0 .Lhu_done
	s_sub_u32 s22, s22, s73
	s_subb_u32 s23, s23, 0
	s_mov_b32 s100, 2
.Lhu_done:
	v_mov_b64_e32 v[2:3], s[10:11]
	v_cmp_ge_i64_e32 vcc, s[22:23], v[2:3]
	v_cmp_lt_i64_e64 s[6:7], s[22:23], v[2:3]
	s_cbranch_vccnz .LBB0_162
	s_ashr_i32 s18, s22, 31
	s_lshr_b32 s18, s18, 29
	s_add_i32 s18, s22, s18
	s_ashr_i32 s19, s18, 3
	s_and_b32 s18, s18, -8
	s_sub_i32 s18, s22, s18
	s_cmp_lt_i32 s18, 0
	s_cselect_b32 s20, s77, s76
	s_mul_i32 s18, s20, s18
	s_add_i32 s18, s18, s19
	s_mul_hi_i32 s19, s18, 0x2e8ba2e9
	s_lshr_b32 s20, s19, 31
	s_ashr_i32 s19, s19, 4
	s_add_i32 s19, s19, s20
	s_lshl_b32 s20, s19, 2
	s_sub_i32 s21, s45, s20
	s_min_i32 s21, s21, 4
	s_abs_i32 s22, s21
	v_cvt_f32_u32_e32 v2, s22
	s_sub_i32 s24, 0, s22
	s_mulk_i32 s19, 0x58
	s_sub_i32 s19, s18, s19
	v_rcp_iflag_f32_e32 v2, v2
	s_abs_i32 s18, s19
	s_xor_b32 s23, s19, s21
	s_ashr_i32 s23, s23, 31
	v_mul_f32_e32 v2, 0x4f7ffffe, v2
	v_cvt_u32_f32_e32 v2, v2
	s_nop 0
	v_readfirstlane_b32 s25, v2
	s_mul_i32 s24, s24, s25
	s_mul_hi_u32 s24, s25, s24
	s_add_i32 s25, s25, s24
	s_mul_hi_u32 s24, s18, s25
	s_mul_i32 s25, s24, s22
	s_sub_i32 s18, s18, s25
	s_add_i32 s27, s24, 1
	s_sub_i32 s25, s18, s22
	s_cmp_ge_u32 s18, s22
	s_cselect_b32 s24, s27, s24
	s_cselect_b32 s18, s25, s18
	s_add_i32 s25, s24, 1
	s_cmp_ge_u32 s18, s22
	s_cselect_b32 s18, s25, s24
	s_xor_b32 s18, s18, s23
	s_sub_i32 s18, s18, s23
	s_mul_i32 s21, s18, s21
	s_sub_i32 s19, s19, s21
	s_add_i32 s20, s19, s20
.LBB0_162:
	s_ashr_i32 s21, s20, 31
	s_lshl_b64 s[22:23], s[20:21], 19
	s_add_u32 s22, s46, s22
	s_addc_u32 s23, s47, s23
	s_and_b64 s[24:25], s[6:7], exec
	s_cselect_b32 s21, s23, s31
	s_cselect_b32 s27, s22, s30
	s_ashr_i32 s19, s18, 31
	s_lshl_b64 s[24:25], s[18:19], 19
	s_add_u32 s24, s48, s24
	s_addc_u32 s25, s49, s25
	s_and_b64 s[40:41], s[6:7], exec
	s_cselect_b32 s19, s25, s35
	s_cselect_b32 s50, s24, s34
	s_add_u32 s30, s30, 0x40080
	s_addc_u32 s31, s31, 0
	s_add_u32 s52, s34, 0x100
	v_mov_b32_e32 v2, 0
	s_addc_u32 s54, s35, 0
	s_mov_b32 s62, -2
	v_mov_b32_e32 v3, v2
	v_mov_b32_e32 v4, v2
	v_mov_b32_e32 v5, v2
	v_mov_b32_e32 v6, v2
	v_mov_b32_e32 v7, v2
	v_mov_b32_e32 v8, v2
	v_mov_b32_e32 v9, v2
	v_mov_b32_e32 v18, v2
	v_mov_b32_e32 v19, v2
	v_mov_b32_e32 v20, v2
	v_mov_b32_e32 v21, v2
	v_mov_b32_e32 v22, v2
	v_mov_b32_e32 v23, v2
	v_mov_b32_e32 v24, v2
	v_mov_b32_e32 v25, v2
	v_mov_b32_e32 v34, v2
	v_mov_b32_e32 v35, v2
	v_mov_b32_e32 v36, v2
	v_mov_b32_e32 v37, v2
	v_mov_b32_e32 v38, v2
	v_mov_b32_e32 v39, v2
	v_mov_b32_e32 v40, v2
	v_mov_b32_e32 v41, v2
	v_mov_b32_e32 v50, v2
	v_mov_b32_e32 v51, v2
	v_mov_b32_e32 v52, v2
	v_mov_b32_e32 v53, v2
	v_mov_b32_e32 v54, v2
	v_mov_b32_e32 v55, v2
	v_mov_b32_e32 v56, v2
	v_mov_b32_e32 v57, v2
	v_mov_b32_e32 v10, v2
	v_mov_b32_e32 v11, v2
	v_mov_b32_e32 v12, v2
	v_mov_b32_e32 v13, v2
	v_mov_b32_e32 v14, v2
	v_mov_b32_e32 v15, v2
	v_mov_b32_e32 v16, v2
	v_mov_b32_e32 v17, v2
	v_mov_b32_e32 v26, v2
	v_mov_b32_e32 v27, v2
	v_mov_b32_e32 v28, v2
	v_mov_b32_e32 v29, v2
	v_mov_b32_e32 v30, v2
	v_mov_b32_e32 v31, v2
	v_mov_b32_e32 v32, v2
	v_mov_b32_e32 v33, v2
	v_mov_b32_e32 v42, v2
	v_mov_b32_e32 v43, v2
	v_mov_b32_e32 v44, v2
	v_mov_b32_e32 v45, v2
	v_mov_b32_e32 v46, v2
	v_mov_b32_e32 v47, v2
	v_mov_b32_e32 v48, v2
	v_mov_b32_e32 v49, v2
	v_mov_b32_e32 v58, v2
	v_mov_b32_e32 v59, v2
	v_mov_b32_e32 v60, v2
	v_mov_b32_e32 v61, v2
	v_mov_b32_e32 v62, v2
	v_mov_b32_e32 v63, v2
	v_mov_b32_e32 v64, v2
	v_mov_b32_e32 v65, v2
	v_mov_b32_e32 v66, v2
	v_mov_b32_e32 v67, v2
	v_mov_b32_e32 v68, v2
	v_mov_b32_e32 v69, v2
	v_mov_b32_e32 v70, v2
	v_mov_b32_e32 v71, v2
	v_mov_b32_e32 v72, v2
	v_mov_b32_e32 v73, v2
	v_mov_b32_e32 v82, v2
	v_mov_b32_e32 v83, v2
	v_mov_b32_e32 v84, v2
	v_mov_b32_e32 v85, v2
	v_mov_b32_e32 v86, v2
	v_mov_b32_e32 v87, v2
	v_mov_b32_e32 v88, v2
	v_mov_b32_e32 v89, v2
	v_mov_b32_e32 v98, v2
	v_mov_b32_e32 v99, v2
	v_mov_b32_e32 v100, v2
	v_mov_b32_e32 v101, v2
	v_mov_b32_e32 v102, v2
	v_mov_b32_e32 v103, v2
	v_mov_b32_e32 v104, v2
	v_mov_b32_e32 v105, v2
	v_mov_b32_e32 v114, v2
	v_mov_b32_e32 v115, v2
	v_mov_b32_e32 v116, v2
	v_mov_b32_e32 v117, v2
	v_mov_b32_e32 v118, v2
	v_mov_b32_e32 v119, v2
	v_mov_b32_e32 v120, v2
	v_mov_b32_e32 v121, v2
	v_mov_b32_e32 v74, v2
	v_mov_b32_e32 v75, v2
	v_mov_b32_e32 v76, v2
	v_mov_b32_e32 v77, v2
	v_mov_b32_e32 v78, v2
	v_mov_b32_e32 v79, v2
	v_mov_b32_e32 v80, v2
	v_mov_b32_e32 v81, v2
	v_mov_b32_e32 v90, v2
	v_mov_b32_e32 v91, v2
	v_mov_b32_e32 v92, v2
	v_mov_b32_e32 v93, v2
	v_mov_b32_e32 v94, v2
	v_mov_b32_e32 v95, v2
	v_mov_b32_e32 v96, v2
	v_mov_b32_e32 v97, v2
	v_mov_b32_e32 v106, v2
	v_mov_b32_e32 v107, v2
	v_mov_b32_e32 v108, v2
	v_mov_b32_e32 v109, v2
	v_mov_b32_e32 v110, v2
	v_mov_b32_e32 v111, v2
	v_mov_b32_e32 v112, v2
	v_mov_b32_e32 v113, v2
	v_mov_b32_e32 v122, v2
	v_mov_b32_e32 v123, v2
	v_mov_b32_e32 v124, v2
	v_mov_b32_e32 v125, v2
	v_mov_b32_e32 v126, v2
	v_mov_b32_e32 v127, v2
	v_mov_b32_e32 v128, v2
	v_mov_b32_e32 v129, v2
	s_cmp_lg_u32 s101, 0
	s_cbranch_scc0 .LBB0_163
	s_cmp_eq_u32 s101, 1
	s_cbranch_scc1 .Lku_a0
	s_branch .Lku_a1
; #define PG8_STAGE(bufoff, gbase, voff) do { _Pragma("unroll") for (int _i = 0; _i < 2; ++_i) \
;         __builtin_amdgcn_global_load_lds((const unsigned*)((const char*)(gbase) + (voff)[_i]), (PG8_LAS unsigned*)(lds + (bufoff) + ldsw + _i * 8192), 16, 0, 0); } while (0)
; #define PG8_LDA(dst, b, h) do { _Pragma("unroll") for (int m = 0; m < 4; ++m) _Pragma("unroll") for (int k = 0; k < 2; ++k) dst[m][k] = *(const PG8_LAS bf16x8*)(lds + PG8_SA(b, h) + aoff + m * 2048 + k * 1024); } while (0)
; #define PG8_LDB(dst, b, h) do { _Pragma("unroll") for (int n = 0; n < 2; ++n) _Pragma("unroll") for (int k = 0; k < 2; ++k) dst[n][k] = *(const PG8_LAS bf16x8*)(lds + PG8_SB(b, h) + boff + n * 2048 + k * 1024); } while (0)
; #define PG8_MMA(ai, bj, At, Bt) do { __builtin_amdgcn_s_setprio(1); _Pragma("unroll") for (int m = 0; m < 4; ++m) _Pragma("unroll") for (int n = 0; n < 2; ++n) _Pragma("unroll") for (int k = 0; k < 2; ++k) \
;         acc[ai][bj][m][n] = __builtin_amdgcn_mfma_f32_16x16x32_bf16(Bt[n][k], At[m][k], acc[ai][bj][m][n], 0, 0, 0); __builtin_amdgcn_s_setprio(0); } while (0)
; #define PG8_WAIT_V(n) asm volatile("s_waitcnt vmcnt(" #n ")" ::: "memory")
; #define PG8_WAIT_L(n) asm volatile("s_waitcnt lgkmcnt(" #n ")" ::: "memory")
; #define PG8_BAR __builtin_amdgcn_s_barrier()
; #define PG8_SCHED __builtin_amdgcn_sched_barrier(0)
; template <class Epi, class Sched, bool ALIGN_EPI = false, bool SP2 = false>
; __device__ __forceinline__ void gemm_phase(PG8_LAS unsigned char* lds, const Gemm g, const Sched& S, const Epi& E) {
;     ...
;             PG8_LDB(B0, 0, 0); PG8_LDB(B1, 0, 1); PG8_SCHED; PG8_LDA(At, 0, 0); PG8_STAGE(PG8_SA(1, 1), a1 + hstep, voffA);
;             PG8_WAIT_V(8); PG8_WAIT_L(0); PG8_BAR; PG8_MMA(0, 0, At, B0); PG8_MMA(0, 1, At, B1); PG8_BAR; PG8_SCHED;
;             PG8_LDA(At, 0, 1); PG8_STAGE(PG8_SB(0, 0), b2, voffB); PG8_STAGE(PG8_SB(0, 1), b2 + hstep, voffB); PG8_STAGE(PG8_SA(0, 0), a2, voffA);
;             PG8_WAIT_V(8); PG8_WAIT_L(0); PG8_BAR; PG8_MMA(1, 0, At, B0); PG8_MMA(1, 1, At, B1); PG8_BAR; PG8_SCHED;
.LBB0_163:
	s_add_u32 s34, s30, 0xfffc0080
	s_addc_u32 s35, s31, -1
	s_add_i32 s71, 0, 0x10000
	s_cmp_eq_u32 s62, 12
	s_cselect_b32 s41, s21, s35
	s_cselect_b32 s40, s27, s34
	v_add_u32_e32 v155, s71, v145
	s_cselect_b32 s35, s19, s54
	s_cselect_b32 s34, s50, s52
	s_add_i32 s74, 0, 0x14000
	ds_read_b128 v[156:159], v155
	ds_read_b128 v[160:163], v155 offset:1024
	ds_read_b128 v[164:167], v155 offset:2048
	ds_read_b128 v[168:171], v155 offset:3072
	v_add_u32_e32 v155, s74, v145
	ds_read_b128 v[172:175], v155
	ds_read_b128 v[176:179], v155 offset:1024
	ds_read_b128 v[180:183], v155 offset:2048
	ds_read_b128 v[208:211], v155 offset:3072
	v_lshl_add_u64 v[202:203], s[30:31], 0, v[134:135]
	s_add_i32 m0, s29, 0xc000
	ds_read_b128 v[212:215], v154
	ds_read_b128 v[216:219], v154 offset:1024
	ds_read_b128 v[220:223], v154 offset:2048
	ds_read_b128 v[224:227], v154 offset:3072
	ds_read_b128 v[228:231], v154 offset:4096
	ds_read_b128 v[232:235], v154 offset:5120
	ds_read_b128 v[236:239], v154 offset:6144
	ds_read_b128 v[240:243], v154 offset:7168
	global_load_lds_dwordx4 v[202:203], off
	v_lshl_add_u64 v[202:203], s[30:31], 0, v[136:137]
	s_add_i32 m0, s29, 0xe000
	s_nop 0
	global_load_lds_dwordx4 v[202:203], off
	s_waitcnt vmcnt(8)
	s_waitcnt lgkmcnt(0)
	s_barrier
	s_setprio 1
	s_waitcnt lgkmcnt(0)
	v_mfma_f32_16x16x32_bf16 v[126:129], v[156:159], v[212:215], v[126:129]
	v_mfma_f32_16x16x32_bf16 v[122:125], v[164:167], v[212:215], v[122:125]
	v_mfma_f32_16x16x32_bf16 v[110:113], v[156:159], v[220:223], v[110:113]
	v_mfma_f32_16x16x32_bf16 v[106:109], v[164:167], v[220:223], v[106:109]
	v_mfma_f32_16x16x32_bf16 v[94:97], v[156:159], v[228:231], v[94:97]
	v_mfma_f32_16x16x32_bf16 v[90:93], v[164:167], v[228:231], v[90:93]
	v_mfma_f32_16x16x32_bf16 v[78:81], v[156:159], v[236:239], v[78:81]
	v_mfma_f32_16x16x32_bf16 v[74:77], v[164:167], v[236:239], v[74:77]
	v_mfma_f32_16x16x32_bf16 v[126:129], v[160:163], v[216:219], v[126:129]
	v_mfma_f32_16x16x32_bf16 v[122:125], v[168:171], v[216:219], v[122:125]
	v_mfma_f32_16x16x32_bf16 v[110:113], v[160:163], v[224:227], v[110:113]
	v_mfma_f32_16x16x32_bf16 v[106:109], v[168:171], v[224:227], v[106:109]
	v_mfma_f32_16x16x32_bf16 v[94:97], v[160:163], v[232:235], v[94:97]
	v_mfma_f32_16x16x32_bf16 v[90:93], v[168:171], v[232:235], v[90:93]
	v_mfma_f32_16x16x32_bf16 v[78:81], v[160:163], v[240:243], v[78:81]
	v_mfma_f32_16x16x32_bf16 v[74:77], v[168:171], v[240:243], v[74:77]
	s_setprio 0
	s_setprio 1
	v_mfma_f32_16x16x32_bf16 v[118:121], v[172:175], v[212:215], v[118:121]
	v_mfma_f32_16x16x32_bf16 v[114:117], v[180:183], v[212:215], v[114:117]
	v_mfma_f32_16x16x32_bf16 v[102:105], v[172:175], v[220:223], v[102:105]
	v_mfma_f32_16x16x32_bf16 v[98:101], v[180:183], v[220:223], v[98:101]
	v_mfma_f32_16x16x32_bf16 v[86:89], v[172:175], v[228:231], v[86:89]
	v_mfma_f32_16x16x32_bf16 v[82:85], v[180:183], v[228:231], v[82:85]
	v_mfma_f32_16x16x32_bf16 v[70:73], v[172:175], v[236:239], v[70:73]
	v_mfma_f32_16x16x32_bf16 v[66:69], v[180:183], v[236:239], v[66:69]
	v_mfma_f32_16x16x32_bf16 v[118:121], v[176:179], v[216:219], v[118:121]
	v_mfma_f32_16x16x32_bf16 v[114:117], v[208:211], v[216:219], v[114:117]
	v_mfma_f32_16x16x32_bf16 v[102:105], v[176:179], v[224:227], v[102:105]
	v_mfma_f32_16x16x32_bf16 v[98:101], v[208:211], v[224:227], v[98:101]
	v_mfma_f32_16x16x32_bf16 v[86:89], v[176:179], v[232:235], v[86:89]
	v_mfma_f32_16x16x32_bf16 v[82:85], v[208:211], v[232:235], v[82:85]
	v_mfma_f32_16x16x32_bf16 v[70:73], v[176:179], v[240:243], v[70:73]
	v_mfma_f32_16x16x32_bf16 v[66:69], v[208:211], v[240:243], v[66:69]
	s_setprio 0
	s_barrier
	s_add_i32 s71, s71, s80
	v_lshl_add_u64 v[202:203], s[34:35], 0, v[132:133]
	s_mov_b32 m0, s71
	ds_read_b128 v[212:215], v154 offset:16384
	ds_read_b128 v[216:219], v154 offset:17408
	ds_read_b128 v[220:223], v154 offset:18432
	ds_read_b128 v[224:227], v154 offset:19456
	ds_read_b128 v[228:231], v154 offset:20480
	ds_read_b128 v[232:235], v154 offset:21504
	ds_read_b128 v[236:239], v154 offset:22528
	ds_read_b128 v[240:243], v154 offset:23552
	global_load_lds_dwordx4 v[202:203], off
	s_add_i32 m0, s71, 0x2000
	s_add_u32 s72, s34, 0x40000
	v_lshl_add_u64 v[204:205], s[34:35], 0, v[130:131]
	s_addc_u32 s73, s35, 0
	s_add_i32 s71, s74, s80
	global_load_lds_dwordx4 v[204:205], off
	v_lshl_add_u64 v[244:245], s[72:73], 0, v[132:133]
	s_mov_b32 m0, s71
	v_lshl_add_u64 v[246:247], s[40:41], 0, v[130:131]
	global_load_lds_dwordx4 v[244:245], off
	v_lshl_add_u64 v[244:245], s[72:73], 0, v[130:131]
	s_add_i32 m0, s71, 0x2000
	s_nop 0
	global_load_lds_dwordx4 v[244:245], off
	v_lshl_add_u64 v[244:245], s[40:41], 0, v[132:133]
	s_mov_b32 m0, s29
	s_nop 0
	global_load_lds_dwordx4 v[244:245], off
	s_mov_b32 m0, s81
	s_nop 0
	global_load_lds_dwordx4 v[246:247], off
	s_waitcnt vmcnt(8)
	s_waitcnt lgkmcnt(0)
	s_barrier
; #define PG8_STAGE(bufoff, gbase, voff) do { _Pragma("unroll") for (int _i = 0; _i < 2; ++_i) \
;         __builtin_amdgcn_global_load_lds((const unsigned*)((const char*)(gbase) + (voff)[_i]), (PG8_LAS unsigned*)(lds + (bufoff) + ldsw + _i * 8192), 16, 0, 0); } while (0)
; #define PG8_LDA(dst, b, h) do { _Pragma("unroll") for (int m = 0; m < 4; ++m) _Pragma("unroll") for (int k = 0; k < 2; ++k) dst[m][k] = *(const PG8_LAS bf16x8*)(lds + PG8_SA(b, h) + aoff + m * 2048 + k * 1024); } while (0)
; #define PG8_LDB(dst, b, h) do { _Pragma("unroll") for (int n = 0; n < 2; ++n) _Pragma("unroll") for (int k = 0; k < 2; ++k) dst[n][k] = *(const PG8_LAS bf16x8*)(lds + PG8_SB(b, h) + boff + n * 2048 + k * 1024); } while (0)
; #define PG8_MMA(ai, bj, At, Bt) do { __builtin_amdgcn_s_setprio(1); _Pragma("unroll") for (int m = 0; m < 4; ++m) _Pragma("unroll") for (int n = 0; n < 2; ++n) _Pragma("unroll") for (int k = 0; k < 2; ++k) \
;         acc[ai][bj][m][n] = __builtin_amdgcn_mfma_f32_16x16x32_bf16(Bt[n][k], At[m][k], acc[ai][bj][m][n], 0, 0, 0); __builtin_amdgcn_s_setprio(0); } while (0)
; #define PG8_WAIT_V(n) asm volatile("s_waitcnt vmcnt(" #n ")" ::: "memory")
; #define PG8_WAIT_L(n) asm volatile("s_waitcnt lgkmcnt(" #n ")" ::: "memory")
; #define PG8_BAR __builtin_amdgcn_s_barrier()
; #define PG8_SCHED __builtin_amdgcn_sched_barrier(0)
; template <class Epi, class Sched, bool ALIGN_EPI = false, bool SP2 = false>
; __device__ __forceinline__ void gemm_phase(PG8_LAS unsigned char* lds, const Gemm g, const Sched& S, const Epi& E) {
;     ...
;             PG8_WAIT_V(8); PG8_WAIT_L(0); PG8_BAR; PG8_MMA(1, 0, At, B0); PG8_MMA(1, 1, At, B1); PG8_BAR; PG8_SCHED;
;             PG8_LDB(B0, 1, 0); PG8_LDB(B1, 1, 1); PG8_SCHED; PG8_LDA(At, 1, 0); PG8_STAGE(PG8_SA(0, 1), a2 + hstep, voffA);
;             PG8_WAIT_V(8); PG8_WAIT_L(0); PG8_BAR; PG8_MMA(0, 0, At, B0); PG8_MMA(0, 1, At, B1); PG8_BAR; PG8_SCHED;
	s_setprio 1
	s_waitcnt lgkmcnt(0)
	v_mfma_f32_16x16x32_bf16 v[62:65], v[156:159], v[212:215], v[62:65]
	v_mfma_f32_16x16x32_bf16 v[58:61], v[164:167], v[212:215], v[58:61]
	v_mfma_f32_16x16x32_bf16 v[46:49], v[156:159], v[220:223], v[46:49]
	v_mfma_f32_16x16x32_bf16 v[42:45], v[164:167], v[220:223], v[42:45]
	v_mfma_f32_16x16x32_bf16 v[30:33], v[156:159], v[228:231], v[30:33]
	v_mfma_f32_16x16x32_bf16 v[26:29], v[164:167], v[228:231], v[26:29]
	v_mfma_f32_16x16x32_bf16 v[14:17], v[156:159], v[236:239], v[14:17]
	v_mfma_f32_16x16x32_bf16 v[10:13], v[164:167], v[236:239], v[10:13]
	v_mfma_f32_16x16x32_bf16 v[62:65], v[160:163], v[216:219], v[62:65]
	v_mfma_f32_16x16x32_bf16 v[58:61], v[168:171], v[216:219], v[58:61]
	v_mfma_f32_16x16x32_bf16 v[46:49], v[160:163], v[224:227], v[46:49]
	v_mfma_f32_16x16x32_bf16 v[42:45], v[168:171], v[224:227], v[42:45]
	v_mfma_f32_16x16x32_bf16 v[30:33], v[160:163], v[232:235], v[30:33]
	v_mfma_f32_16x16x32_bf16 v[26:29], v[168:171], v[232:235], v[26:29]
	v_mfma_f32_16x16x32_bf16 v[14:17], v[160:163], v[240:243], v[14:17]
	v_mfma_f32_16x16x32_bf16 v[10:13], v[168:171], v[240:243], v[10:13]
	s_setprio 0
	s_setprio 1
	v_mfma_f32_16x16x32_bf16 v[54:57], v[172:175], v[212:215], v[54:57]
	v_mfma_f32_16x16x32_bf16 v[50:53], v[180:183], v[212:215], v[50:53]
	v_mfma_f32_16x16x32_bf16 v[38:41], v[172:175], v[220:223], v[38:41]
	v_mfma_f32_16x16x32_bf16 v[34:37], v[180:183], v[220:223], v[34:37]
	v_mfma_f32_16x16x32_bf16 v[22:25], v[172:175], v[228:231], v[22:25]
	v_mfma_f32_16x16x32_bf16 v[18:21], v[180:183], v[228:231], v[18:21]
	v_mfma_f32_16x16x32_bf16 v[6:9], v[172:175], v[236:239], v[6:9]
	v_mfma_f32_16x16x32_bf16 v[2:5], v[180:183], v[236:239], v[2:5]
	v_mfma_f32_16x16x32_bf16 v[54:57], v[176:179], v[216:219], v[54:57]
	v_mfma_f32_16x16x32_bf16 v[50:53], v[208:211], v[216:219], v[50:53]
	v_mfma_f32_16x16x32_bf16 v[38:41], v[176:179], v[224:227], v[38:41]
	v_mfma_f32_16x16x32_bf16 v[34:37], v[208:211], v[224:227], v[34:37]
	v_mfma_f32_16x16x32_bf16 v[22:25], v[176:179], v[232:235], v[22:25]
	v_mfma_f32_16x16x32_bf16 v[18:21], v[208:211], v[232:235], v[18:21]
	v_mfma_f32_16x16x32_bf16 v[6:9], v[176:179], v[240:243], v[6:9]
	v_mfma_f32_16x16x32_bf16 v[2:5], v[208:211], v[240:243], v[2:5]
	s_setprio 0
	s_barrier
	s_add_i32 s71, 0, 0x18000
	v_add_u32_e32 v155, s71, v145
	s_add_i32 s72, 0, 0x1c000
	ds_read_b128 v[156:159], v155
	ds_read_b128 v[160:163], v155 offset:1024
	ds_read_b128 v[164:167], v155 offset:2048
	ds_read_b128 v[168:171], v155 offset:3072
	v_add_u32_e32 v155, s72, v145
	ds_read_b128 v[172:175], v155
	ds_read_b128 v[176:179], v155 offset:1024
	ds_read_b128 v[180:183], v155 offset:2048
	ds_read_b128 v[208:211], v155 offset:3072
	s_add_u32 s40, s40, 0x40000
	s_addc_u32 s41, s41, 0
	s_mov_b32 m0, s82
	v_lshl_add_u64 v[248:249], s[40:41], 0, v[132:133]
	ds_read_b128 v[212:215], v154 offset:32768
	ds_read_b128 v[216:219], v154 offset:33792
	ds_read_b128 v[220:223], v154 offset:34816
	ds_read_b128 v[224:227], v154 offset:35840
	ds_read_b128 v[228:231], v154 offset:36864
	ds_read_b128 v[232:235], v154 offset:37888
	ds_read_b128 v[236:239], v154 offset:38912
	ds_read_b128 v[240:243], v154 offset:39936
	global_load_lds_dwordx4 v[248:249], off
	v_lshl_add_u64 v[248:249], s[40:41], 0, v[130:131]
	s_mov_b32 m0, s83
	s_nop 0
	global_load_lds_dwordx4 v[248:249], off
	s_waitcnt vmcnt(8)
	s_waitcnt lgkmcnt(0)
	s_barrier
	s_setprio 1
	s_waitcnt lgkmcnt(0)
	v_mfma_f32_16x16x32_bf16 v[126:129], v[156:159], v[212:215], v[126:129]
	v_mfma_f32_16x16x32_bf16 v[122:125], v[164:167], v[212:215], v[122:125]
	v_mfma_f32_16x16x32_bf16 v[110:113], v[156:159], v[220:223], v[110:113]
	v_mfma_f32_16x16x32_bf16 v[106:109], v[164:167], v[220:223], v[106:109]
	v_mfma_f32_16x16x32_bf16 v[94:97], v[156:159], v[228:231], v[94:97]
	v_mfma_f32_16x16x32_bf16 v[90:93], v[164:167], v[228:231], v[90:93]
	v_mfma_f32_16x16x32_bf16 v[78:81], v[156:159], v[236:239], v[78:81]
	v_mfma_f32_16x16x32_bf16 v[74:77], v[164:167], v[236:239], v[74:77]
	v_mfma_f32_16x16x32_bf16 v[126:129], v[160:163], v[216:219], v[126:129]
	v_mfma_f32_16x16x32_bf16 v[122:125], v[168:171], v[216:219], v[122:125]
	v_mfma_f32_16x16x32_bf16 v[110:113], v[160:163], v[224:227], v[110:113]
	v_mfma_f32_16x16x32_bf16 v[106:109], v[168:171], v[224:227], v[106:109]
	v_mfma_f32_16x16x32_bf16 v[94:97], v[160:163], v[232:235], v[94:97]
	v_mfma_f32_16x16x32_bf16 v[90:93], v[168:171], v[232:235], v[90:93]
	v_mfma_f32_16x16x32_bf16 v[78:81], v[160:163], v[240:243], v[78:81]
	v_mfma_f32_16x16x32_bf16 v[74:77], v[168:171], v[240:243], v[74:77]
	s_setprio 0
	s_setprio 1
	v_mfma_f32_16x16x32_bf16 v[118:121], v[172:175], v[212:215], v[118:121]
	v_mfma_f32_16x16x32_bf16 v[114:117], v[180:183], v[212:215], v[114:117]
	v_mfma_f32_16x16x32_bf16 v[102:105], v[172:175], v[220:223], v[102:105]
	v_mfma_f32_16x16x32_bf16 v[98:101], v[180:183], v[220:223], v[98:101]
	v_mfma_f32_16x16x32_bf16 v[86:89], v[172:175], v[228:231], v[86:89]
	v_mfma_f32_16x16x32_bf16 v[82:85], v[180:183], v[228:231], v[82:85]
	v_mfma_f32_16x16x32_bf16 v[70:73], v[172:175], v[236:239], v[70:73]
	v_mfma_f32_16x16x32_bf16 v[66:69], v[180:183], v[236:239], v[66:69]
	v_mfma_f32_16x16x32_bf16 v[118:121], v[176:179], v[216:219], v[118:121]
	v_mfma_f32_16x16x32_bf16 v[114:117], v[208:211], v[216:219], v[114:117]
	v_mfma_f32_16x16x32_bf16 v[102:105], v[176:179], v[224:227], v[102:105]
	v_mfma_f32_16x16x32_bf16 v[98:101], v[208:211], v[224:227], v[98:101]
	v_mfma_f32_16x16x32_bf16 v[86:89], v[176:179], v[232:235], v[86:89]
	v_mfma_f32_16x16x32_bf16 v[82:85], v[208:211], v[232:235], v[82:85]
	v_mfma_f32_16x16x32_bf16 v[70:73], v[176:179], v[240:243], v[70:73]
	v_mfma_f32_16x16x32_bf16 v[66:69], v[208:211], v[240:243], v[66:69]
	s_setprio 0
	s_barrier
; #define PG8_STAGE(bufoff, gbase, voff) do { _Pragma("unroll") for (int _i = 0; _i < 2; ++_i) \
;         __builtin_amdgcn_global_load_lds((const unsigned*)((const char*)(gbase) + (voff)[_i]), (PG8_LAS unsigned*)(lds + (bufoff) + ldsw + _i * 8192), 16, 0, 0); } while (0)
; #define PG8_LDA(dst, b, h) do { _Pragma("unroll") for (int m = 0; m < 4; ++m) _Pragma("unroll") for (int k = 0; k < 2; ++k) dst[m][k] = *(const PG8_LAS bf16x8*)(lds + PG8_SA(b, h) + aoff + m * 2048 + k * 1024); } while (0)
; #define PG8_LDB(dst, b, h) do { _Pragma("unroll") for (int n = 0; n < 2; ++n) _Pragma("unroll") for (int k = 0; k < 2; ++k) dst[n][k] = *(const PG8_LAS bf16x8*)(lds + PG8_SB(b, h) + boff + n * 2048 + k * 1024); } while (0)
; #define PG8_MMA(ai, bj, At, Bt) do { __builtin_amdgcn_s_setprio(1); _Pragma("unroll") for (int m = 0; m < 4; ++m) _Pragma("unroll") for (int n = 0; n < 2; ++n) _Pragma("unroll") for (int k = 0; k < 2; ++k) \
;         acc[ai][bj][m][n] = __builtin_amdgcn_mfma_f32_16x16x32_bf16(Bt[n][k], At[m][k], acc[ai][bj][m][n], 0, 0, 0); __builtin_amdgcn_s_setprio(0); } while (0)
; #define PG8_WAIT_V(n) asm volatile("s_waitcnt vmcnt(" #n ")" ::: "memory")
; #define PG8_WAIT_L(n) asm volatile("s_waitcnt lgkmcnt(" #n ")" ::: "memory")
; #define PG8_BAR __builtin_amdgcn_s_barrier()
; #define PG8_SCHED __builtin_amdgcn_sched_barrier(0)
; template <class Epi, class Sched, bool ALIGN_EPI = false, bool SP2 = false>
; __device__ __forceinline__ void gemm_phase(PG8_LAS unsigned char* lds, const Gemm g, const Sched& S, const Epi& E) {
;     ...
;             PG8_LDB(B0, 0, 0); PG8_LDB(B1, 0, 1); PG8_SCHED; PG8_LDA(At, 0, 0); PG8_STAGE(PG8_SA(1, 1), a1 + hstep, voffA);
;             PG8_WAIT_V(8); PG8_WAIT_L(0); PG8_BAR; PG8_MMA(0, 0, At, B0); PG8_MMA(0, 1, At, B1); PG8_BAR; PG8_SCHED;
;     ...
;             PG8_LDA(At, 1, 1); PG8_STAGE(PG8_SB(1, 0), b3, voffB); PG8_STAGE(PG8_SB(1, 1), b3 + hstep, voffB); PG8_STAGE(PG8_SA(1, 0), a3, voffA);
;             PG8_WAIT_V(8); PG8_WAIT_L(0); PG8_BAR; PG8_MMA(1, 0, At, B0); PG8_MMA(1, 1, At, B1); PG8_BAR; PG8_SCHED;
	s_add_i32 s40, s71, s80
	v_lshl_add_u64 v[202:203], v[202:203], 0, s[66:67]
	s_mov_b32 m0, s40
	ds_read_b128 v[212:215], v154 offset:49152
	ds_read_b128 v[216:219], v154 offset:50176
	ds_read_b128 v[220:223], v154 offset:51200
	ds_read_b128 v[224:227], v154 offset:52224
	ds_read_b128 v[228:231], v154 offset:53248
	ds_read_b128 v[232:235], v154 offset:54272
	ds_read_b128 v[236:239], v154 offset:55296
	ds_read_b128 v[240:243], v154 offset:56320
	global_load_lds_dwordx4 v[202:203], off
	s_add_i32 m0, s40, 0x2000
	s_add_u32 s34, s34, 0x40080
	v_lshl_add_u64 v[202:203], v[204:205], 0, s[66:67]
	s_addc_u32 s35, s35, 0
	s_add_i32 s40, s72, s80
	global_load_lds_dwordx4 v[202:203], off
	v_lshl_add_u64 v[202:203], s[34:35], 0, v[132:133]
	s_mov_b32 m0, s40
	s_nop 0
	global_load_lds_dwordx4 v[202:203], off
	v_lshl_add_u64 v[202:203], s[34:35], 0, v[130:131]
	s_add_i32 m0, s40, 0x2000
	s_nop 0
	global_load_lds_dwordx4 v[202:203], off
	v_lshl_add_u64 v[202:203], v[244:245], 0, s[66:67]
	s_mov_b32 m0, s84
	s_nop 0
	global_load_lds_dwordx4 v[202:203], off
	v_lshl_add_u64 v[202:203], v[246:247], 0, s[66:67]
	s_mov_b32 m0, s85
	s_nop 0
	global_load_lds_dwordx4 v[202:203], off
	s_waitcnt vmcnt(8)
	s_waitcnt lgkmcnt(0)
	s_barrier
	s_setprio 1
	s_waitcnt lgkmcnt(0)
	v_mfma_f32_16x16x32_bf16 v[62:65], v[156:159], v[212:215], v[62:65]
	v_mfma_f32_16x16x32_bf16 v[58:61], v[164:167], v[212:215], v[58:61]
	v_mfma_f32_16x16x32_bf16 v[46:49], v[156:159], v[220:223], v[46:49]
	v_mfma_f32_16x16x32_bf16 v[42:45], v[164:167], v[220:223], v[42:45]
	v_mfma_f32_16x16x32_bf16 v[30:33], v[156:159], v[228:231], v[30:33]
	v_mfma_f32_16x16x32_bf16 v[26:29], v[164:167], v[228:231], v[26:29]
	v_mfma_f32_16x16x32_bf16 v[14:17], v[156:159], v[236:239], v[14:17]
	v_mfma_f32_16x16x32_bf16 v[10:13], v[164:167], v[236:239], v[10:13]
	v_mfma_f32_16x16x32_bf16 v[62:65], v[160:163], v[216:219], v[62:65]
	v_mfma_f32_16x16x32_bf16 v[58:61], v[168:171], v[216:219], v[58:61]
	v_mfma_f32_16x16x32_bf16 v[46:49], v[160:163], v[224:227], v[46:49]
	v_mfma_f32_16x16x32_bf16 v[42:45], v[168:171], v[224:227], v[42:45]
	v_mfma_f32_16x16x32_bf16 v[30:33], v[160:163], v[232:235], v[30:33]
	v_mfma_f32_16x16x32_bf16 v[26:29], v[168:171], v[232:235], v[26:29]
	v_mfma_f32_16x16x32_bf16 v[14:17], v[160:163], v[240:243], v[14:17]
	v_mfma_f32_16x16x32_bf16 v[10:13], v[168:171], v[240:243], v[10:13]
	s_setprio 0
	s_setprio 1
	v_mfma_f32_16x16x32_bf16 v[54:57], v[172:175], v[212:215], v[54:57]
	v_mfma_f32_16x16x32_bf16 v[50:53], v[180:183], v[212:215], v[50:53]
	v_mfma_f32_16x16x32_bf16 v[38:41], v[172:175], v[220:223], v[38:41]
	v_mfma_f32_16x16x32_bf16 v[34:37], v[180:183], v[220:223], v[34:37]
	v_mfma_f32_16x16x32_bf16 v[22:25], v[172:175], v[228:231], v[22:25]
	v_mfma_f32_16x16x32_bf16 v[18:21], v[180:183], v[228:231], v[18:21]
	v_mfma_f32_16x16x32_bf16 v[6:9], v[172:175], v[236:239], v[6:9]
	v_mfma_f32_16x16x32_bf16 v[2:5], v[180:183], v[236:239], v[2:5]
	v_mfma_f32_16x16x32_bf16 v[54:57], v[176:179], v[216:219], v[54:57]
	v_mfma_f32_16x16x32_bf16 v[50:53], v[208:211], v[216:219], v[50:53]
	v_mfma_f32_16x16x32_bf16 v[38:41], v[176:179], v[224:227], v[38:41]
	v_mfma_f32_16x16x32_bf16 v[34:37], v[208:211], v[224:227], v[34:37]
	v_mfma_f32_16x16x32_bf16 v[22:25], v[176:179], v[232:235], v[22:25]
	v_mfma_f32_16x16x32_bf16 v[18:21], v[208:211], v[232:235], v[18:21]
	v_mfma_f32_16x16x32_bf16 v[6:9], v[176:179], v[240:243], v[6:9]
	v_mfma_f32_16x16x32_bf16 v[2:5], v[208:211], v[240:243], v[2:5]
	s_setprio 0
	s_barrier
	s_add_i32 s62, s62, 2
	s_add_u32 s30, s30, 0x100
	s_addc_u32 s31, s31, 0
	s_add_u32 s52, s52, 0x100
	s_addc_u32 s54, s54, 0
	s_cmp_gt_u32 s62, 13
	s_cbranch_scc0 .LBB0_163
	s_branch .Lku_exit
.Lku_a0:
	s_add_u32 s34, s30, 0xfffc0080
	s_addc_u32 s35, s31, -1
	s_add_i32 s71, 0, 0x10000
	s_cmp_eq_u32 s62, 12
	s_cselect_b32 s41, s21, s35
	s_cselect_b32 s40, s27, s34
	v_add_u32_e32 v155, s71, v145
	s_cselect_b32 s35, s19, s54
	s_cselect_b32 s34, s50, s52
	s_add_i32 s74, 0, 0x14000
	ds_read_b128 v[156:159], v155
	ds_read_b128 v[160:163], v155 offset:1024
	ds_read_b128 v[164:167], v155 offset:2048
	ds_read_b128 v[168:171], v155 offset:3072
	v_add_u32_e32 v155, s74, v145
	ds_read_b128 v[172:175], v155
	ds_read_b128 v[176:179], v155 offset:1024
	ds_read_b128 v[180:183], v155 offset:2048
	ds_read_b128 v[208:211], v155 offset:3072
	v_lshl_add_u64 v[202:203], s[30:31], 0, v[134:135]
	s_add_i32 m0, s29, 0xc000
	ds_read_b128 v[212:215], v154
	ds_read_b128 v[216:219], v154 offset:1024
	ds_read_b128 v[220:223], v154 offset:2048
	ds_read_b128 v[224:227], v154 offset:3072
	ds_read_b128 v[228:231], v154 offset:4096
	ds_read_b128 v[232:235], v154 offset:5120
	ds_read_b128 v[236:239], v154 offset:6144
	ds_read_b128 v[240:243], v154 offset:7168
	v_lshl_add_u64 v[202:203], s[30:31], 0, v[136:137]
	s_add_i32 m0, s29, 0xe000
	s_nop 0
	s_waitcnt vmcnt(6)
	s_waitcnt lgkmcnt(0)
	s_barrier
; #define PG8_STAGE(bufoff, gbase, voff) do { _Pragma("unroll") for (int _i = 0; _i < 2; ++_i) \
;         __builtin_amdgcn_global_load_lds((const unsigned*)((const char*)(gbase) + (voff)[_i]), (PG8_LAS unsigned*)(lds + (bufoff) + ldsw + _i * 8192), 16, 0, 0); } while (0)
; #define PG8_LDA(dst, b, h) do { _Pragma("unroll") for (int m = 0; m < 4; ++m) _Pragma("unroll") for (int k = 0; k < 2; ++k) dst[m][k] = *(const PG8_LAS bf16x8*)(lds + PG8_SA(b, h) + aoff + m * 2048 + k * 1024); } while (0)
; #define PG8_LDB(dst, b, h) do { _Pragma("unroll") for (int n = 0; n < 2; ++n) _Pragma("unroll") for (int k = 0; k < 2; ++k) dst[n][k] = *(const PG8_LAS bf16x8*)(lds + PG8_SB(b, h) + boff + n * 2048 + k * 1024); } while (0)
; #define PG8_MMA(ai, bj, At, Bt) do { __builtin_amdgcn_s_setprio(1); _Pragma("unroll") for (int m = 0; m < 4; ++m) _Pragma("unroll") for (int n = 0; n < 2; ++n) _Pragma("unroll") for (int k = 0; k < 2; ++k) \
;         acc[ai][bj][m][n] = __builtin_amdgcn_mfma_f32_16x16x32_bf16(Bt[n][k], At[m][k], acc[ai][bj][m][n], 0, 0, 0); __builtin_amdgcn_s_setprio(0); } while (0)
; #define PG8_WAIT_V(n) asm volatile("s_waitcnt vmcnt(" #n ")" ::: "memory")
; #define PG8_WAIT_L(n) asm volatile("s_waitcnt lgkmcnt(" #n ")" ::: "memory")
; #define PG8_BAR __builtin_amdgcn_s_barrier()
; #define PG8_SCHED __builtin_amdgcn_sched_barrier(0)
; template <class Epi, class Sched, bool ALIGN_EPI = false, bool SP2 = false>
; __device__ __forceinline__ void gemm_phase(PG8_LAS unsigned char* lds, const Gemm g, const Sched& S, const Epi& E) {
;     ...
;             PG8_WAIT_V(8); PG8_WAIT_L(0); PG8_BAR; PG8_MMA(0, 0, At, B0); PG8_MMA(0, 1, At, B1); PG8_BAR; PG8_SCHED;
;             PG8_LDA(At, 0, 1); PG8_STAGE(PG8_SB(0, 0), b2, voffB); PG8_STAGE(PG8_SB(0, 1), b2 + hstep, voffB); PG8_STAGE(PG8_SA(0, 0), a2, voffA);
;             PG8_WAIT_V(8); PG8_WAIT_L(0); PG8_BAR; PG8_MMA(1, 0, At, B0); PG8_MMA(1, 1, At, B1); PG8_BAR; PG8_SCHED;
;             PG8_LDB(B0, 1, 0); PG8_LDB(B1, 1, 1); PG8_SCHED; PG8_LDA(At, 1, 0); PG8_STAGE(PG8_SA(0, 1), a2 + hstep, voffA);
;             PG8_WAIT_V(8); PG8_WAIT_L(0); PG8_BAR; PG8_MMA(0, 0, At, B0); PG8_MMA(0, 1, At, B1); PG8_BAR; PG8_SCHED;
	s_setprio 1
	s_waitcnt lgkmcnt(0)
	v_mfma_f32_16x16x32_bf16 v[126:129], v[156:159], v[212:215], v[126:129]
	v_mfma_f32_16x16x32_bf16 v[122:125], v[164:167], v[212:215], v[122:125]
	v_mfma_f32_16x16x32_bf16 v[110:113], v[156:159], v[220:223], v[110:113]
	v_mfma_f32_16x16x32_bf16 v[106:109], v[164:167], v[220:223], v[106:109]
	v_mfma_f32_16x16x32_bf16 v[94:97], v[156:159], v[228:231], v[94:97]
	v_mfma_f32_16x16x32_bf16 v[90:93], v[164:167], v[228:231], v[90:93]
	v_mfma_f32_16x16x32_bf16 v[78:81], v[156:159], v[236:239], v[78:81]
	v_mfma_f32_16x16x32_bf16 v[74:77], v[164:167], v[236:239], v[74:77]
	v_mfma_f32_16x16x32_bf16 v[126:129], v[160:163], v[216:219], v[126:129]
	v_mfma_f32_16x16x32_bf16 v[122:125], v[168:171], v[216:219], v[122:125]
	v_mfma_f32_16x16x32_bf16 v[110:113], v[160:163], v[224:227], v[110:113]
	v_mfma_f32_16x16x32_bf16 v[106:109], v[168:171], v[224:227], v[106:109]
	v_mfma_f32_16x16x32_bf16 v[94:97], v[160:163], v[232:235], v[94:97]
	v_mfma_f32_16x16x32_bf16 v[90:93], v[168:171], v[232:235], v[90:93]
	v_mfma_f32_16x16x32_bf16 v[78:81], v[160:163], v[240:243], v[78:81]
	v_mfma_f32_16x16x32_bf16 v[74:77], v[168:171], v[240:243], v[74:77]
	s_setprio 0
	s_setprio 1
	v_mfma_f32_16x16x32_bf16 v[118:121], v[172:175], v[212:215], v[118:121]
	v_mfma_f32_16x16x32_bf16 v[114:117], v[180:183], v[212:215], v[114:117]
	v_mfma_f32_16x16x32_bf16 v[102:105], v[172:175], v[220:223], v[102:105]
	v_mfma_f32_16x16x32_bf16 v[98:101], v[180:183], v[220:223], v[98:101]
	v_mfma_f32_16x16x32_bf16 v[86:89], v[172:175], v[228:231], v[86:89]
	v_mfma_f32_16x16x32_bf16 v[82:85], v[180:183], v[228:231], v[82:85]
	v_mfma_f32_16x16x32_bf16 v[70:73], v[172:175], v[236:239], v[70:73]
	v_mfma_f32_16x16x32_bf16 v[66:69], v[180:183], v[236:239], v[66:69]
	v_mfma_f32_16x16x32_bf16 v[118:121], v[176:179], v[216:219], v[118:121]
	v_mfma_f32_16x16x32_bf16 v[114:117], v[208:211], v[216:219], v[114:117]
	v_mfma_f32_16x16x32_bf16 v[102:105], v[176:179], v[224:227], v[102:105]
	v_mfma_f32_16x16x32_bf16 v[98:101], v[208:211], v[224:227], v[98:101]
	v_mfma_f32_16x16x32_bf16 v[86:89], v[176:179], v[232:235], v[86:89]
	v_mfma_f32_16x16x32_bf16 v[82:85], v[208:211], v[232:235], v[82:85]
	v_mfma_f32_16x16x32_bf16 v[70:73], v[176:179], v[240:243], v[70:73]
	v_mfma_f32_16x16x32_bf16 v[66:69], v[208:211], v[240:243], v[66:69]
	s_setprio 0
	s_barrier
	s_add_i32 s71, s71, s80
	v_lshl_add_u64 v[202:203], s[34:35], 0, v[132:133]
	s_mov_b32 m0, s71
	global_load_lds_dwordx4 v[202:203], off
	s_add_i32 m0, s71, 0x2000
	s_add_u32 s72, s34, 0x40000
	v_lshl_add_u64 v[204:205], s[34:35], 0, v[130:131]
	s_addc_u32 s73, s35, 0
	s_add_i32 s71, s74, s80
	global_load_lds_dwordx4 v[204:205], off
	v_lshl_add_u64 v[244:245], s[72:73], 0, v[132:133]
	s_mov_b32 m0, s71
	v_lshl_add_u64 v[246:247], s[40:41], 0, v[130:131]
	global_load_lds_dwordx4 v[244:245], off
	v_lshl_add_u64 v[244:245], s[72:73], 0, v[130:131]
	s_add_i32 m0, s71, 0x2000
	s_nop 0
	global_load_lds_dwordx4 v[244:245], off
	v_lshl_add_u64 v[244:245], s[40:41], 0, v[132:133]
	s_mov_b32 m0, s29
	s_nop 0
	global_load_lds_dwordx4 v[244:245], off
	s_mov_b32 m0, s81
	s_nop 0
	global_load_lds_dwordx4 v[246:247], off
	s_waitcnt vmcnt(6)
	s_waitcnt lgkmcnt(0)
	s_barrier
	s_setprio 1
	s_waitcnt lgkmcnt(0)
	s_setprio 0
	s_setprio 1
	s_setprio 0
	s_barrier
	s_add_i32 s71, 0, 0x18000
	v_add_u32_e32 v155, s71, v145
	s_add_i32 s72, 0, 0x1c000
	ds_read_b128 v[156:159], v155
	ds_read_b128 v[160:163], v155 offset:1024
	ds_read_b128 v[164:167], v155 offset:2048
	ds_read_b128 v[168:171], v155 offset:3072
	v_add_u32_e32 v155, s72, v145
	ds_read_b128 v[172:175], v155
	ds_read_b128 v[176:179], v155 offset:1024
	ds_read_b128 v[180:183], v155 offset:2048
	ds_read_b128 v[208:211], v155 offset:3072
	s_add_u32 s40, s40, 0x40000
	s_addc_u32 s41, s41, 0
	s_mov_b32 m0, s82
	v_lshl_add_u64 v[248:249], s[40:41], 0, v[132:133]
	ds_read_b128 v[212:215], v154 offset:32768
	ds_read_b128 v[216:219], v154 offset:33792
	ds_read_b128 v[220:223], v154 offset:34816
	ds_read_b128 v[224:227], v154 offset:35840
	ds_read_b128 v[228:231], v154 offset:36864
	ds_read_b128 v[232:235], v154 offset:37888
	ds_read_b128 v[236:239], v154 offset:38912
	ds_read_b128 v[240:243], v154 offset:39936
	v_lshl_add_u64 v[248:249], s[40:41], 0, v[130:131]
	s_mov_b32 m0, s83
	s_nop 0
	s_waitcnt vmcnt(6)
	s_waitcnt lgkmcnt(0)
	s_barrier
	s_setprio 1
	s_waitcnt lgkmcnt(0)
	v_mfma_f32_16x16x32_bf16 v[126:129], v[156:159], v[212:215], v[126:129]
	v_mfma_f32_16x16x32_bf16 v[122:125], v[164:167], v[212:215], v[122:125]
	v_mfma_f32_16x16x32_bf16 v[110:113], v[156:159], v[220:223], v[110:113]
	v_mfma_f32_16x16x32_bf16 v[106:109], v[164:167], v[220:223], v[106:109]
	v_mfma_f32_16x16x32_bf16 v[94:97], v[156:159], v[228:231], v[94:97]
	v_mfma_f32_16x16x32_bf16 v[90:93], v[164:167], v[228:231], v[90:93]
	v_mfma_f32_16x16x32_bf16 v[78:81], v[156:159], v[236:239], v[78:81]
	v_mfma_f32_16x16x32_bf16 v[74:77], v[164:167], v[236:239], v[74:77]
	v_mfma_f32_16x16x32_bf16 v[126:129], v[160:163], v[216:219], v[126:129]
	v_mfma_f32_16x16x32_bf16 v[122:125], v[168:171], v[216:219], v[122:125]
	v_mfma_f32_16x16x32_bf16 v[110:113], v[160:163], v[224:227], v[110:113]
	v_mfma_f32_16x16x32_bf16 v[106:109], v[168:171], v[224:227], v[106:109]
	v_mfma_f32_16x16x32_bf16 v[94:97], v[160:163], v[232:235], v[94:97]
	v_mfma_f32_16x16x32_bf16 v[90:93], v[168:171], v[232:235], v[90:93]
	v_mfma_f32_16x16x32_bf16 v[78:81], v[160:163], v[240:243], v[78:81]
	v_mfma_f32_16x16x32_bf16 v[74:77], v[168:171], v[240:243], v[74:77]
	s_setprio 0
	s_setprio 1
	v_mfma_f32_16x16x32_bf16 v[118:121], v[172:175], v[212:215], v[118:121]
	v_mfma_f32_16x16x32_bf16 v[114:117], v[180:183], v[212:215], v[114:117]
	v_mfma_f32_16x16x32_bf16 v[102:105], v[172:175], v[220:223], v[102:105]
	v_mfma_f32_16x16x32_bf16 v[98:101], v[180:183], v[220:223], v[98:101]
	v_mfma_f32_16x16x32_bf16 v[86:89], v[172:175], v[228:231], v[86:89]
	v_mfma_f32_16x16x32_bf16 v[82:85], v[180:183], v[228:231], v[82:85]
	v_mfma_f32_16x16x32_bf16 v[70:73], v[172:175], v[236:239], v[70:73]
	v_mfma_f32_16x16x32_bf16 v[66:69], v[180:183], v[236:239], v[66:69]
	v_mfma_f32_16x16x32_bf16 v[118:121], v[176:179], v[216:219], v[118:121]
	v_mfma_f32_16x16x32_bf16 v[114:117], v[208:211], v[216:219], v[114:117]
	v_mfma_f32_16x16x32_bf16 v[102:105], v[176:179], v[224:227], v[102:105]
	v_mfma_f32_16x16x32_bf16 v[98:101], v[208:211], v[224:227], v[98:101]
	v_mfma_f32_16x16x32_bf16 v[86:89], v[176:179], v[232:235], v[86:89]
	v_mfma_f32_16x16x32_bf16 v[82:85], v[208:211], v[232:235], v[82:85]
	v_mfma_f32_16x16x32_bf16 v[70:73], v[176:179], v[240:243], v[70:73]
	v_mfma_f32_16x16x32_bf16 v[66:69], v[208:211], v[240:243], v[66:69]
	s_setprio 0
	s_barrier
; #define PG8_STAGE(bufoff, gbase, voff) do { _Pragma("unroll") for (int _i = 0; _i < 2; ++_i) \
;         __builtin_amdgcn_global_load_lds((const unsigned*)((const char*)(gbase) + (voff)[_i]), (PG8_LAS unsigned*)(lds + (bufoff) + ldsw + _i * 8192), 16, 0, 0); } while (0)
; #define PG8_LDA(dst, b, h) do { _Pragma("unroll") for (int m = 0; m < 4; ++m) _Pragma("unroll") for (int k = 0; k < 2; ++k) dst[m][k] = *(const PG8_LAS bf16x8*)(lds + PG8_SA(b, h) + aoff + m * 2048 + k * 1024); } while (0)
; #define PG8_LDB(dst, b, h) do { _Pragma("unroll") for (int n = 0; n < 2; ++n) _Pragma("unroll") for (int k = 0; k < 2; ++k) dst[n][k] = *(const PG8_LAS bf16x8*)(lds + PG8_SB(b, h) + boff + n * 2048 + k * 1024); } while (0)
; #define PG8_MMA(ai, bj, At, Bt) do { __builtin_amdgcn_s_setprio(1); _Pragma("unroll") for (int m = 0; m < 4; ++m) _Pragma("unroll") for (int n = 0; n < 2; ++n) _Pragma("unroll") for (int k = 0; k < 2; ++k) \
;         acc[ai][bj][m][n] = __builtin_amdgcn_mfma_f32_16x16x32_bf16(Bt[n][k], At[m][k], acc[ai][bj][m][n], 0, 0, 0); __builtin_amdgcn_s_setprio(0); } while (0)
; #define PG8_WAIT_V(n) asm volatile("s_waitcnt vmcnt(" #n ")" ::: "memory")
; #define PG8_WAIT_L(n) asm volatile("s_waitcnt lgkmcnt(" #n ")" ::: "memory")
; #define PG8_BAR __builtin_amdgcn_s_barrier()
; #define PG8_SCHED __builtin_amdgcn_sched_barrier(0)
; template <class Epi, class Sched, bool ALIGN_EPI = false, bool SP2 = false>
; __device__ __forceinline__ void gemm_phase(PG8_LAS unsigned char* lds, const Gemm g, const Sched& S, const Epi& E) {
;     ...
;             PG8_LDB(B0, 0, 0); PG8_LDB(B1, 0, 1); PG8_SCHED; PG8_LDA(At, 0, 0); PG8_STAGE(PG8_SA(1, 1), a1 + hstep, voffA);
;             PG8_WAIT_V(8); PG8_WAIT_L(0); PG8_BAR; PG8_MMA(0, 0, At, B0); PG8_MMA(0, 1, At, B1); PG8_BAR; PG8_SCHED;
;             PG8_LDA(At, 0, 1); PG8_STAGE(PG8_SB(0, 0), b2, voffB); PG8_STAGE(PG8_SB(0, 1), b2 + hstep, voffB); PG8_STAGE(PG8_SA(0, 0), a2, voffA);
;             PG8_WAIT_V(8); PG8_WAIT_L(0); PG8_BAR; PG8_MMA(1, 0, At, B0); PG8_MMA(1, 1, At, B1); PG8_BAR; PG8_SCHED;
;     ...
;             PG8_LDA(At, 1, 1); PG8_STAGE(PG8_SB(1, 0), b3, voffB); PG8_STAGE(PG8_SB(1, 1), b3 + hstep, voffB); PG8_STAGE(PG8_SA(1, 0), a3, voffA);
;             PG8_WAIT_V(8); PG8_WAIT_L(0); PG8_BAR; PG8_MMA(1, 0, At, B0); PG8_MMA(1, 1, At, B1); PG8_BAR; PG8_SCHED;
	s_add_i32 s40, s71, s80
	v_lshl_add_u64 v[202:203], v[202:203], 0, s[66:67]
	s_mov_b32 m0, s40
	global_load_lds_dwordx4 v[202:203], off
	s_add_i32 m0, s40, 0x2000
	s_add_u32 s34, s34, 0x40080
	v_lshl_add_u64 v[202:203], v[204:205], 0, s[66:67]
	s_addc_u32 s35, s35, 0
	s_add_i32 s40, s72, s80
	global_load_lds_dwordx4 v[202:203], off
	v_lshl_add_u64 v[202:203], s[34:35], 0, v[132:133]
	s_mov_b32 m0, s40
	s_nop 0
	global_load_lds_dwordx4 v[202:203], off
	v_lshl_add_u64 v[202:203], s[34:35], 0, v[130:131]
	s_add_i32 m0, s40, 0x2000
	s_nop 0
	global_load_lds_dwordx4 v[202:203], off
	v_lshl_add_u64 v[202:203], v[244:245], 0, s[66:67]
	s_mov_b32 m0, s84
	s_nop 0
	global_load_lds_dwordx4 v[202:203], off
	v_lshl_add_u64 v[202:203], v[246:247], 0, s[66:67]
	s_mov_b32 m0, s85
	s_nop 0
	global_load_lds_dwordx4 v[202:203], off
	s_waitcnt vmcnt(6)
	s_waitcnt lgkmcnt(0)
	s_barrier
	s_setprio 1
	s_waitcnt lgkmcnt(0)
	s_setprio 0
	s_setprio 1
	s_setprio 0
	s_barrier
	s_add_i32 s62, s62, 2
	s_add_u32 s30, s30, 0x100
	s_addc_u32 s31, s31, 0
	s_add_u32 s52, s52, 0x100
	s_addc_u32 s54, s54, 0
	s_cmp_gt_u32 s62, 13
	s_cbranch_scc0 .Lku_a0
	s_branch .Lku_exit
.Lku_a1:
	s_add_u32 s34, s30, 0xfffc0080
	s_addc_u32 s35, s31, -1
	s_add_i32 s71, 0, 0x10000
	s_cmp_eq_u32 s62, 12
	s_cselect_b32 s41, s21, s35
	s_cselect_b32 s40, s27, s34
	v_add_u32_e32 v155, s71, v145
	s_cselect_b32 s35, s19, s54
	s_cselect_b32 s34, s50, s52
	s_add_i32 s74, 0, 0x14000
	ds_read_b128 v[156:159], v155
	ds_read_b128 v[160:163], v155 offset:1024
	ds_read_b128 v[164:167], v155 offset:2048
	ds_read_b128 v[168:171], v155 offset:3072
	v_add_u32_e32 v155, s74, v145
	ds_read_b128 v[172:175], v155
	ds_read_b128 v[176:179], v155 offset:1024
	ds_read_b128 v[180:183], v155 offset:2048
	ds_read_b128 v[208:211], v155 offset:3072
	v_lshl_add_u64 v[202:203], s[30:31], 0, v[134:135]
	s_add_i32 m0, s29, 0xc000
	global_load_lds_dwordx4 v[202:203], off
	v_lshl_add_u64 v[202:203], s[30:31], 0, v[136:137]
	s_add_i32 m0, s29, 0xe000
	s_nop 0
	global_load_lds_dwordx4 v[202:203], off
	s_waitcnt vmcnt(6)
	s_waitcnt lgkmcnt(0)
	s_barrier
	s_setprio 1
	s_waitcnt lgkmcnt(0)
	s_setprio 0
	s_setprio 1
	s_setprio 0
	s_barrier
	s_add_i32 s71, s71, s80
	v_lshl_add_u64 v[202:203], s[34:35], 0, v[132:133]
	s_mov_b32 m0, s71
	ds_read_b128 v[212:215], v154 offset:16384
	ds_read_b128 v[216:219], v154 offset:17408
	ds_read_b128 v[220:223], v154 offset:18432
	ds_read_b128 v[224:227], v154 offset:19456
	ds_read_b128 v[228:231], v154 offset:20480
	ds_read_b128 v[232:235], v154 offset:21504
	ds_read_b128 v[236:239], v154 offset:22528
	ds_read_b128 v[240:243], v154 offset:23552
	global_load_lds_dwordx4 v[202:203], off
	s_add_i32 m0, s71, 0x2000
	s_add_u32 s72, s34, 0x40000
	v_lshl_add_u64 v[204:205], s[34:35], 0, v[130:131]
	s_addc_u32 s73, s35, 0
	s_add_i32 s71, s74, s80
	global_load_lds_dwordx4 v[204:205], off
	v_lshl_add_u64 v[244:245], s[72:73], 0, v[132:133]
	s_mov_b32 m0, s71
	v_lshl_add_u64 v[246:247], s[40:41], 0, v[130:131]
	global_load_lds_dwordx4 v[244:245], off
	v_lshl_add_u64 v[244:245], s[72:73], 0, v[130:131]
	s_add_i32 m0, s71, 0x2000
	s_nop 0
	global_load_lds_dwordx4 v[244:245], off
	v_lshl_add_u64 v[244:245], s[40:41], 0, v[132:133]
	s_mov_b32 m0, s29
	s_nop 0
	s_mov_b32 m0, s81
	s_nop 0
	s_waitcnt vmcnt(6)
	s_waitcnt lgkmcnt(0)
	s_barrier
	s_setprio 1
	s_waitcnt lgkmcnt(0)
	v_mfma_f32_16x16x32_bf16 v[62:65], v[156:159], v[212:215], v[62:65]
	v_mfma_f32_16x16x32_bf16 v[58:61], v[164:167], v[212:215], v[58:61]
	v_mfma_f32_16x16x32_bf16 v[46:49], v[156:159], v[220:223], v[46:49]
	v_mfma_f32_16x16x32_bf16 v[42:45], v[164:167], v[220:223], v[42:45]
	v_mfma_f32_16x16x32_bf16 v[30:33], v[156:159], v[228:231], v[30:33]
	v_mfma_f32_16x16x32_bf16 v[26:29], v[164:167], v[228:231], v[26:29]
	v_mfma_f32_16x16x32_bf16 v[14:17], v[156:159], v[236:239], v[14:17]
	v_mfma_f32_16x16x32_bf16 v[10:13], v[164:167], v[236:239], v[10:13]
	v_mfma_f32_16x16x32_bf16 v[62:65], v[160:163], v[216:219], v[62:65]
	v_mfma_f32_16x16x32_bf16 v[58:61], v[168:171], v[216:219], v[58:61]
	v_mfma_f32_16x16x32_bf16 v[46:49], v[160:163], v[224:227], v[46:49]
	v_mfma_f32_16x16x32_bf16 v[42:45], v[168:171], v[224:227], v[42:45]
	v_mfma_f32_16x16x32_bf16 v[30:33], v[160:163], v[232:235], v[30:33]
	v_mfma_f32_16x16x32_bf16 v[26:29], v[168:171], v[232:235], v[26:29]
	v_mfma_f32_16x16x32_bf16 v[14:17], v[160:163], v[240:243], v[14:17]
	v_mfma_f32_16x16x32_bf16 v[10:13], v[168:171], v[240:243], v[10:13]
	s_setprio 0
	s_setprio 1
	v_mfma_f32_16x16x32_bf16 v[54:57], v[172:175], v[212:215], v[54:57]
	v_mfma_f32_16x16x32_bf16 v[50:53], v[180:183], v[212:215], v[50:53]
	v_mfma_f32_16x16x32_bf16 v[38:41], v[172:175], v[220:223], v[38:41]
	v_mfma_f32_16x16x32_bf16 v[34:37], v[180:183], v[220:223], v[34:37]
	v_mfma_f32_16x16x32_bf16 v[22:25], v[172:175], v[228:231], v[22:25]
	v_mfma_f32_16x16x32_bf16 v[18:21], v[180:183], v[228:231], v[18:21]
	v_mfma_f32_16x16x32_bf16 v[6:9], v[172:175], v[236:239], v[6:9]
	v_mfma_f32_16x16x32_bf16 v[2:5], v[180:183], v[236:239], v[2:5]
	v_mfma_f32_16x16x32_bf16 v[54:57], v[176:179], v[216:219], v[54:57]
	v_mfma_f32_16x16x32_bf16 v[50:53], v[208:211], v[216:219], v[50:53]
	v_mfma_f32_16x16x32_bf16 v[38:41], v[176:179], v[224:227], v[38:41]
	v_mfma_f32_16x16x32_bf16 v[34:37], v[208:211], v[224:227], v[34:37]
	v_mfma_f32_16x16x32_bf16 v[22:25], v[176:179], v[232:235], v[22:25]
	v_mfma_f32_16x16x32_bf16 v[18:21], v[208:211], v[232:235], v[18:21]
	v_mfma_f32_16x16x32_bf16 v[6:9], v[176:179], v[240:243], v[6:9]
	v_mfma_f32_16x16x32_bf16 v[2:5], v[208:211], v[240:243], v[2:5]
	s_setprio 0
	s_barrier
; #define PG8_STAGE(bufoff, gbase, voff) do { _Pragma("unroll") for (int _i = 0; _i < 2; ++_i) \
;         __builtin_amdgcn_global_load_lds((const unsigned*)((const char*)(gbase) + (voff)[_i]), (PG8_LAS unsigned*)(lds + (bufoff) + ldsw + _i * 8192), 16, 0, 0); } while (0)
; #define PG8_LDA(dst, b, h) do { _Pragma("unroll") for (int m = 0; m < 4; ++m) _Pragma("unroll") for (int k = 0; k < 2; ++k) dst[m][k] = *(const PG8_LAS bf16x8*)(lds + PG8_SA(b, h) + aoff + m * 2048 + k * 1024); } while (0)
; #define PG8_LDB(dst, b, h) do { _Pragma("unroll") for (int n = 0; n < 2; ++n) _Pragma("unroll") for (int k = 0; k < 2; ++k) dst[n][k] = *(const PG8_LAS bf16x8*)(lds + PG8_SB(b, h) + boff + n * 2048 + k * 1024); } while (0)
; #define PG8_MMA(ai, bj, At, Bt) do { __builtin_amdgcn_s_setprio(1); _Pragma("unroll") for (int m = 0; m < 4; ++m) _Pragma("unroll") for (int n = 0; n < 2; ++n) _Pragma("unroll") for (int k = 0; k < 2; ++k) \
;         acc[ai][bj][m][n] = __builtin_amdgcn_mfma_f32_16x16x32_bf16(Bt[n][k], At[m][k], acc[ai][bj][m][n], 0, 0, 0); __builtin_amdgcn_s_setprio(0); } while (0)
; #define PG8_WAIT_V(n) asm volatile("s_waitcnt vmcnt(" #n ")" ::: "memory")
; #define PG8_WAIT_L(n) asm volatile("s_waitcnt lgkmcnt(" #n ")" ::: "memory")
; #define PG8_BAR __builtin_amdgcn_s_barrier()
; #define PG8_SCHED __builtin_amdgcn_sched_barrier(0)
; template <class Epi, class Sched, bool ALIGN_EPI = false, bool SP2 = false>
; __device__ __forceinline__ void gemm_phase(PG8_LAS unsigned char* lds, const Gemm g, const Sched& S, const Epi& E) {
;     ...
;             PG8_LDB(B0, 1, 0); PG8_LDB(B1, 1, 1); PG8_SCHED; PG8_LDA(At, 1, 0); PG8_STAGE(PG8_SA(0, 1), a2 + hstep, voffA);
;             PG8_WAIT_V(8); PG8_WAIT_L(0); PG8_BAR; PG8_MMA(0, 0, At, B0); PG8_MMA(0, 1, At, B1); PG8_BAR; PG8_SCHED;
;             PG8_LDA(At, 1, 1); PG8_STAGE(PG8_SB(1, 0), b3, voffB); PG8_STAGE(PG8_SB(1, 1), b3 + hstep, voffB); PG8_STAGE(PG8_SA(1, 0), a3, voffA);
;             PG8_WAIT_V(8); PG8_WAIT_L(0); PG8_BAR; PG8_MMA(1, 0, At, B0); PG8_MMA(1, 1, At, B1); PG8_BAR; PG8_SCHED;
	s_add_i32 s71, 0, 0x18000
	v_add_u32_e32 v155, s71, v145
	s_add_i32 s72, 0, 0x1c000
	ds_read_b128 v[156:159], v155
	ds_read_b128 v[160:163], v155 offset:1024
	ds_read_b128 v[164:167], v155 offset:2048
	ds_read_b128 v[168:171], v155 offset:3072
	v_add_u32_e32 v155, s72, v145
	ds_read_b128 v[172:175], v155
	ds_read_b128 v[176:179], v155 offset:1024
	ds_read_b128 v[180:183], v155 offset:2048
	ds_read_b128 v[208:211], v155 offset:3072
	s_add_u32 s40, s40, 0x40000
	s_addc_u32 s41, s41, 0
	s_mov_b32 m0, s82
	v_lshl_add_u64 v[248:249], s[40:41], 0, v[132:133]
	global_load_lds_dwordx4 v[248:249], off
	v_lshl_add_u64 v[248:249], s[40:41], 0, v[130:131]
	s_mov_b32 m0, s83
	s_nop 0
	global_load_lds_dwordx4 v[248:249], off
	s_waitcnt vmcnt(6)
	s_waitcnt lgkmcnt(0)
	s_barrier
	s_setprio 1
	s_waitcnt lgkmcnt(0)
	s_setprio 0
	s_setprio 1
	s_setprio 0
	s_barrier
	s_add_i32 s40, s71, s80
	v_lshl_add_u64 v[202:203], v[202:203], 0, s[66:67]
	s_mov_b32 m0, s40
	ds_read_b128 v[212:215], v154 offset:49152
	ds_read_b128 v[216:219], v154 offset:50176
	ds_read_b128 v[220:223], v154 offset:51200
	ds_read_b128 v[224:227], v154 offset:52224
	ds_read_b128 v[228:231], v154 offset:53248
	ds_read_b128 v[232:235], v154 offset:54272
	ds_read_b128 v[236:239], v154 offset:55296
	ds_read_b128 v[240:243], v154 offset:56320
	global_load_lds_dwordx4 v[202:203], off
	s_add_i32 m0, s40, 0x2000
	s_add_u32 s34, s34, 0x40080
	v_lshl_add_u64 v[202:203], v[204:205], 0, s[66:67]
	s_addc_u32 s35, s35, 0
	s_add_i32 s40, s72, s80
	global_load_lds_dwordx4 v[202:203], off
	v_lshl_add_u64 v[202:203], s[34:35], 0, v[132:133]
	s_mov_b32 m0, s40
	s_nop 0
	global_load_lds_dwordx4 v[202:203], off
	v_lshl_add_u64 v[202:203], s[34:35], 0, v[130:131]
	s_add_i32 m0, s40, 0x2000
	s_nop 0
	global_load_lds_dwordx4 v[202:203], off
	v_lshl_add_u64 v[202:203], v[244:245], 0, s[66:67]
	s_mov_b32 m0, s84
	s_nop 0
	v_lshl_add_u64 v[202:203], v[246:247], 0, s[66:67]
	s_mov_b32 m0, s85
	s_nop 0
	s_waitcnt vmcnt(6)
	s_waitcnt lgkmcnt(0)
	s_barrier
	s_setprio 1
	s_waitcnt lgkmcnt(0)
	v_mfma_f32_16x16x32_bf16 v[62:65], v[156:159], v[212:215], v[62:65]
	v_mfma_f32_16x16x32_bf16 v[58:61], v[164:167], v[212:215], v[58:61]
	v_mfma_f32_16x16x32_bf16 v[46:49], v[156:159], v[220:223], v[46:49]
	v_mfma_f32_16x16x32_bf16 v[42:45], v[164:167], v[220:223], v[42:45]
	v_mfma_f32_16x16x32_bf16 v[30:33], v[156:159], v[228:231], v[30:33]
	v_mfma_f32_16x16x32_bf16 v[26:29], v[164:167], v[228:231], v[26:29]
	v_mfma_f32_16x16x32_bf16 v[14:17], v[156:159], v[236:239], v[14:17]
	v_mfma_f32_16x16x32_bf16 v[10:13], v[164:167], v[236:239], v[10:13]
	v_mfma_f32_16x16x32_bf16 v[62:65], v[160:163], v[216:219], v[62:65]
	v_mfma_f32_16x16x32_bf16 v[58:61], v[168:171], v[216:219], v[58:61]
	v_mfma_f32_16x16x32_bf16 v[46:49], v[160:163], v[224:227], v[46:49]
	v_mfma_f32_16x16x32_bf16 v[42:45], v[168:171], v[224:227], v[42:45]
	v_mfma_f32_16x16x32_bf16 v[30:33], v[160:163], v[232:235], v[30:33]
	v_mfma_f32_16x16x32_bf16 v[26:29], v[168:171], v[232:235], v[26:29]
	v_mfma_f32_16x16x32_bf16 v[14:17], v[160:163], v[240:243], v[14:17]
	v_mfma_f32_16x16x32_bf16 v[10:13], v[168:171], v[240:243], v[10:13]
	s_setprio 0
	s_setprio 1
	v_mfma_f32_16x16x32_bf16 v[54:57], v[172:175], v[212:215], v[54:57]
	v_mfma_f32_16x16x32_bf16 v[50:53], v[180:183], v[212:215], v[50:53]
	v_mfma_f32_16x16x32_bf16 v[38:41], v[172:175], v[220:223], v[38:41]
	v_mfma_f32_16x16x32_bf16 v[34:37], v[180:183], v[220:223], v[34:37]
	v_mfma_f32_16x16x32_bf16 v[22:25], v[172:175], v[228:231], v[22:25]
	v_mfma_f32_16x16x32_bf16 v[18:21], v[180:183], v[228:231], v[18:21]
	v_mfma_f32_16x16x32_bf16 v[6:9], v[172:175], v[236:239], v[6:9]
	v_mfma_f32_16x16x32_bf16 v[2:5], v[180:183], v[236:239], v[2:5]
	v_mfma_f32_16x16x32_bf16 v[54:57], v[176:179], v[216:219], v[54:57]
	v_mfma_f32_16x16x32_bf16 v[50:53], v[208:211], v[216:219], v[50:53]
	v_mfma_f32_16x16x32_bf16 v[38:41], v[176:179], v[224:227], v[38:41]
	v_mfma_f32_16x16x32_bf16 v[34:37], v[208:211], v[224:227], v[34:37]
	v_mfma_f32_16x16x32_bf16 v[22:25], v[176:179], v[232:235], v[22:25]
	v_mfma_f32_16x16x32_bf16 v[18:21], v[208:211], v[232:235], v[18:21]
	v_mfma_f32_16x16x32_bf16 v[6:9], v[176:179], v[240:243], v[6:9]
	v_mfma_f32_16x16x32_bf16 v[2:5], v[208:211], v[240:243], v[2:5]
	s_setprio 0
	s_barrier
	s_add_i32 s62, s62, 2
	s_add_u32 s30, s30, 0x100
	s_addc_u32 s31, s31, 0
	s_add_u32 s52, s52, 0x100
	s_addc_u32 s54, s54, 0
	s_cmp_gt_u32 s62, 13
	s_cbranch_scc0 .Lku_a1
.Lku_exit:
	s_and_b64 vcc, exec, s[16:17]
	s_cbranch_vccz .LBB0_166
	s_barrier
; __device__ __forceinline__ unsigned pk2(float lo, float hi) { unsigned r; asm("v_cvt_pk_bf16_f32 %0, %1, %2" : "=v"(r) : "v"(lo), "v"(hi)); return r; }
; __device__ __forceinline__ float siluf(float v) { return v * __builtin_amdgcn_rcpf(1.f + __expf(-v)); }
;     __device__ __forceinline__ void operator()(const f32x4 (&acc)[2][2][4][2], const Unit& u, int wr, int wc, int fr, int fq) const {
; #pragma unroll
;         for (int ai = 0; ai < 2; ++ai)
; #pragma unroll
;             for (int m = 0; m < 4; ++m) {
;                 const int row = u.pm * 256 + ai * 128 + wr * 64 + m * 16 + fr;
;                 const f32x4 g0 = acc[ai][0][m][0], u0 = acc[ai][0][m][1], g1 = acc[ai][1][m][0], u1 = acc[ai][1][m][1];
;                 u32x4 w;
;                 w.x = pk2(siluf(g0[0]) * u0[0], siluf(g0[1]) * u0[1]); w.y = pk2(siluf(g0[2]) * u0[2], siluf(g0[3]) * u0[3]);
;                 w.z = pk2(siluf(g1[0]) * u1[0], siluf(g1[1]) * u1[1]); w.w = pk2(siluf(g1[2]) * u1[2], siluf(g1[3]) * u1[3]);
;                 *(u32x4*)(act + (size_t)row * DFF + u.pn * 128 + wc * 32 + 8 * fq) = w;
.LBB0_166:
	s_cmp_eq_u32 s101, 2
	s_cbranch_scc1 .Lku_epi_skip0
	v_mul_f32_e32 v156, 0xbfb8aa3b, v126
	v_exp_f32_e32 v156, v156
	s_lshl_b32 s19, s28, 8
	s_lshl_b32 s26, s26, 7
	v_add_u32_e32 v155, s19, v143
	v_add_f32_e32 v156, 1.0, v156
	v_rcp_f32_e32 v156, v156
	s_movk_i32 s21, 0x1600
	s_ashr_i32 s27, s26, 31
	s_lshl_b64 s[26:27], s[26:27], 1
	v_mul_f32_e32 v126, v126, v156
	v_mul_f32_e32 v122, v122, v126
	v_mul_f32_e32 v126, 0xbfb8aa3b, v127
	v_exp_f32_e32 v126, v126
	s_andn2_b64 vcc, exec, s[6:7]
	v_add_f32_e32 v126, 1.0, v126
	v_rcp_f32_e32 v126, v126
	s_nop 0
	v_mul_f32_e32 v126, v127, v126
	v_mul_f32_e32 v123, v123, v126
	v_cvt_pk_bf16_f32 v122, v122, v123
	v_mul_f32_e32 v123, 0xbfb8aa3b, v128
	v_exp_f32_e32 v123, v123
	s_nop 0
	v_add_f32_e32 v123, 1.0, v123
	v_rcp_f32_e32 v123, v123
	s_nop 0
	v_mul_f32_e32 v123, v128, v123
	v_mul_f32_e32 v123, v124, v123
	v_mul_f32_e32 v124, 0xbfb8aa3b, v129
	v_exp_f32_e32 v124, v124
	s_nop 0
	v_add_f32_e32 v124, 1.0, v124
	v_rcp_f32_e32 v124, v124
	s_nop 0
	v_mul_f32_e32 v124, v129, v124
	v_mul_f32_e32 v124, v125, v124
	v_cvt_pk_bf16_f32 v123, v123, v124
	v_mul_f32_e32 v124, 0xbfb8aa3b, v118
	v_exp_f32_e32 v124, v124
	s_nop 0
	v_add_f32_e32 v124, 1.0, v124
	v_rcp_f32_e32 v124, v124
	s_nop 0
	v_mul_f32_e32 v118, v118, v124
	v_mul_f32_e32 v114, v114, v118
	v_mul_f32_e32 v118, 0xbfb8aa3b, v119
	v_exp_f32_e32 v118, v118
	s_nop 0
	v_add_f32_e32 v118, 1.0, v118
	v_rcp_f32_e32 v118, v118
	s_nop 0
	v_mul_f32_e32 v118, v119, v118
	v_mul_f32_e32 v115, v115, v118
	v_cvt_pk_bf16_f32 v124, v114, v115
	v_mul_f32_e32 v114, 0xbfb8aa3b, v120
	v_mul_f32_e32 v115, 0xbfb8aa3b, v121
	v_exp_f32_e32 v114, v114
	v_exp_f32_e32 v115, v115
	v_add_f32_e32 v114, 1.0, v114
	v_add_f32_e32 v115, 1.0, v115
	v_rcp_f32_e32 v114, v114
	v_rcp_f32_e32 v115, v115
	v_mul_f32_e32 v114, v120, v114
	v_mul_f32_e32 v115, v121, v115
	v_mul_f32_e32 v114, v116, v114
	v_mul_f32_e32 v115, v117, v115
	v_cvt_pk_bf16_f32 v125, v114, v115
	v_mov_b64_e32 v[114:115], s[14:15]
	v_mad_i64_i32 v[116:117], s[30:31], v155, s21, v[114:115]
	v_lshl_add_u64 v[116:117], v[116:117], 0, s[26:27]
	v_lshl_add_u64 v[116:117], v[116:117], 0, s[64:65]
	v_lshl_add_u64 v[116:117], v[116:117], 0, v[0:1]
	global_store_dwordx4 v[116:117], v[122:125], off
	v_mul_f32_e32 v117, 0xbfb8aa3b, v110
	v_exp_f32_e32 v117, v117
	v_add_u32_e32 v116, s19, v147
	v_add_f32_e32 v117, 1.0, v117
	v_rcp_f32_e32 v117, v117
	s_nop 0
	v_mul_f32_e32 v110, v110, v117
	v_mul_f32_e32 v106, v106, v110
	v_mul_f32_e32 v110, 0xbfb8aa3b, v111
	v_exp_f32_e32 v110, v110
	s_nop 0
	v_add_f32_e32 v110, 1.0, v110
	v_rcp_f32_e32 v110, v110
	s_nop 0
	v_mul_f32_e32 v110, v111, v110
	v_mul_f32_e32 v107, v107, v110
	v_cvt_pk_bf16_f32 v106, v106, v107
	v_mul_f32_e32 v107, 0xbfb8aa3b, v112
	v_exp_f32_e32 v107, v107
	s_nop 0
	v_add_f32_e32 v107, 1.0, v107
	v_rcp_f32_e32 v107, v107
	s_nop 0
	v_mul_f32_e32 v107, v112, v107
	v_mul_f32_e32 v107, v108, v107
	v_mul_f32_e32 v108, 0xbfb8aa3b, v113
	v_exp_f32_e32 v108, v108
	s_nop 0
	v_add_f32_e32 v108, 1.0, v108
	v_rcp_f32_e32 v108, v108
	s_nop 0
	v_mul_f32_e32 v108, v113, v108
	v_mul_f32_e32 v108, v109, v108
	v_cvt_pk_bf16_f32 v107, v107, v108
	v_mul_f32_e32 v108, 0xbfb8aa3b, v102
	v_exp_f32_e32 v108, v108
	s_nop 0
	v_add_f32_e32 v108, 1.0, v108
	v_rcp_f32_e32 v108, v108
	s_nop 0
	v_mul_f32_e32 v102, v102, v108
	v_mul_f32_e32 v98, v98, v102
	v_mul_f32_e32 v102, 0xbfb8aa3b, v103
	v_exp_f32_e32 v102, v102
	s_nop 0
	v_add_f32_e32 v102, 1.0, v102
	v_rcp_f32_e32 v102, v102
	s_nop 0
	v_mul_f32_e32 v102, v103, v102
	v_mul_f32_e32 v99, v99, v102
	v_cvt_pk_bf16_f32 v108, v98, v99
	v_mul_f32_e32 v98, 0xbfb8aa3b, v104
	v_mul_f32_e32 v99, 0xbfb8aa3b, v105
	v_exp_f32_e32 v98, v98
	v_exp_f32_e32 v99, v99
	v_add_f32_e32 v98, 1.0, v98
	v_add_f32_e32 v99, 1.0, v99
	v_rcp_f32_e32 v98, v98
	v_rcp_f32_e32 v99, v99
	v_mul_f32_e32 v98, v104, v98
	v_mul_f32_e32 v99, v105, v99
	v_mul_f32_e32 v98, v100, v98
	v_mul_f32_e32 v99, v101, v99
	v_cvt_pk_bf16_f32 v109, v98, v99
	v_mad_i64_i32 v[98:99], s[30:31], v116, s21, v[114:115]
	v_lshl_add_u64 v[98:99], v[98:99], 0, s[26:27]
	v_lshl_add_u64 v[98:99], v[98:99], 0, s[64:65]
	v_lshl_add_u64 v[98:99], v[98:99], 0, v[0:1]
	global_store_dwordx4 v[98:99], v[106:109], off
	v_mul_f32_e32 v99, 0xbfb8aa3b, v94
	v_exp_f32_e32 v99, v99
	v_add_u32_e32 v98, s19, v148
	v_add_f32_e32 v99, 1.0, v99
	v_rcp_f32_e32 v99, v99
	s_nop 0
	v_mul_f32_e32 v94, v94, v99
	v_mul_f32_e32 v90, v90, v94
	v_mul_f32_e32 v94, 0xbfb8aa3b, v95
	v_exp_f32_e32 v94, v94
	s_nop 0
	v_add_f32_e32 v94, 1.0, v94
	v_rcp_f32_e32 v94, v94
	s_nop 0
	v_mul_f32_e32 v94, v95, v94
	v_mul_f32_e32 v91, v91, v94
	v_cvt_pk_bf16_f32 v90, v90, v91
	v_mul_f32_e32 v91, 0xbfb8aa3b, v96
	v_exp_f32_e32 v91, v91
	s_nop 0
	v_add_f32_e32 v91, 1.0, v91
	v_rcp_f32_e32 v91, v91
	s_nop 0
	v_mul_f32_e32 v91, v96, v91
	v_mul_f32_e32 v91, v92, v91
	v_mul_f32_e32 v92, 0xbfb8aa3b, v97
	v_exp_f32_e32 v92, v92
	s_nop 0
	v_add_f32_e32 v92, 1.0, v92
	v_rcp_f32_e32 v92, v92
	s_nop 0
	v_mul_f32_e32 v92, v97, v92
	v_mul_f32_e32 v92, v93, v92
	v_cvt_pk_bf16_f32 v91, v91, v92
	v_mul_f32_e32 v92, 0xbfb8aa3b, v86
	v_exp_f32_e32 v92, v92
	s_nop 0
	v_add_f32_e32 v92, 1.0, v92
	v_rcp_f32_e32 v92, v92
	s_nop 0
	v_mul_f32_e32 v86, v86, v92
	v_mul_f32_e32 v82, v82, v86
	v_mul_f32_e32 v86, 0xbfb8aa3b, v87
	v_exp_f32_e32 v86, v86
	s_nop 0
	v_add_f32_e32 v86, 1.0, v86
	v_rcp_f32_e32 v86, v86
	s_nop 0
	v_mul_f32_e32 v86, v87, v86
	v_mul_f32_e32 v83, v83, v86
	v_cvt_pk_bf16_f32 v92, v82, v83
	v_mul_f32_e32 v82, 0xbfb8aa3b, v88
	v_mul_f32_e32 v83, 0xbfb8aa3b, v89
	v_exp_f32_e32 v82, v82
	v_exp_f32_e32 v83, v83
	v_add_f32_e32 v82, 1.0, v82
; __device__ __forceinline__ unsigned pk2(float lo, float hi) { unsigned r; asm("v_cvt_pk_bf16_f32 %0, %1, %2" : "=v"(r) : "v"(lo), "v"(hi)); return r; }
; __device__ __forceinline__ float siluf(float v) { return v * __builtin_amdgcn_rcpf(1.f + __expf(-v)); }
;     __device__ __forceinline__ void operator()(const f32x4 (&acc)[2][2][4][2], const Unit& u, int wr, int wc, int fr, int fq) const {
;     ...
;             for (int m = 0; m < 4; ++m) {
;                 const int row = u.pm * 256 + ai * 128 + wr * 64 + m * 16 + fr;
;                 const f32x4 g0 = acc[ai][0][m][0], u0 = acc[ai][0][m][1], g1 = acc[ai][1][m][0], u1 = acc[ai][1][m][1];
;                 u32x4 w;
;                 w.x = pk2(siluf(g0[0]) * u0[0], siluf(g0[1]) * u0[1]); w.y = pk2(siluf(g0[2]) * u0[2], siluf(g0[3]) * u0[3]);
;                 w.z = pk2(siluf(g1[0]) * u1[0], siluf(g1[1]) * u1[1]); w.w = pk2(siluf(g1[2]) * u1[2], siluf(g1[3]) * u1[3]);
;                 *(u32x4*)(act + (size_t)row * DFF + u.pn * 128 + wc * 32 + 8 * fq) = w;
	v_add_f32_e32 v83, 1.0, v83
	v_rcp_f32_e32 v82, v82
	v_rcp_f32_e32 v83, v83
	v_mul_f32_e32 v82, v88, v82
	v_mul_f32_e32 v83, v89, v83
	v_mul_f32_e32 v82, v84, v82
	v_mul_f32_e32 v83, v85, v83
	v_cvt_pk_bf16_f32 v93, v82, v83
	v_mad_i64_i32 v[82:83], s[30:31], v98, s21, v[114:115]
	v_lshl_add_u64 v[82:83], v[82:83], 0, s[26:27]
	v_lshl_add_u64 v[82:83], v[82:83], 0, s[64:65]
	v_lshl_add_u64 v[82:83], v[82:83], 0, v[0:1]
	global_store_dwordx4 v[82:83], v[90:93], off
	v_mul_f32_e32 v83, 0xbfb8aa3b, v78
	v_exp_f32_e32 v83, v83
	v_add_u32_e32 v82, s19, v149
	v_add_f32_e32 v83, 1.0, v83
	v_rcp_f32_e32 v83, v83
	s_nop 0
	v_mul_f32_e32 v78, v78, v83
	v_mul_f32_e32 v74, v74, v78
	v_mul_f32_e32 v78, 0xbfb8aa3b, v79
	v_exp_f32_e32 v78, v78
	s_nop 0
	v_add_f32_e32 v78, 1.0, v78
	v_rcp_f32_e32 v78, v78
	s_nop 0
	v_mul_f32_e32 v78, v79, v78
	v_mul_f32_e32 v75, v75, v78
	v_cvt_pk_bf16_f32 v74, v74, v75
	v_mul_f32_e32 v75, 0xbfb8aa3b, v80
	v_exp_f32_e32 v75, v75
	s_nop 0
	v_add_f32_e32 v75, 1.0, v75
	v_rcp_f32_e32 v75, v75
	s_nop 0
	v_mul_f32_e32 v75, v80, v75
	v_mul_f32_e32 v75, v76, v75
	v_mul_f32_e32 v76, 0xbfb8aa3b, v81
	v_exp_f32_e32 v76, v76
	s_nop 0
	v_add_f32_e32 v76, 1.0, v76
	v_rcp_f32_e32 v76, v76
	s_nop 0
	v_mul_f32_e32 v76, v81, v76
	v_mul_f32_e32 v76, v77, v76
	v_cvt_pk_bf16_f32 v75, v75, v76
	v_mul_f32_e32 v76, 0xbfb8aa3b, v70
	v_exp_f32_e32 v76, v76
	s_nop 0
	v_add_f32_e32 v76, 1.0, v76
	v_rcp_f32_e32 v76, v76
	s_nop 0
	v_mul_f32_e32 v70, v70, v76
	v_mul_f32_e32 v66, v66, v70
	v_mul_f32_e32 v70, 0xbfb8aa3b, v71
	v_exp_f32_e32 v70, v70
	s_nop 0
	v_add_f32_e32 v70, 1.0, v70
	v_rcp_f32_e32 v70, v70
	s_nop 0
	v_mul_f32_e32 v70, v71, v70
	v_mul_f32_e32 v67, v67, v70
	v_cvt_pk_bf16_f32 v76, v66, v67
	v_mul_f32_e32 v66, 0xbfb8aa3b, v72
	v_mul_f32_e32 v67, 0xbfb8aa3b, v73
	v_exp_f32_e32 v66, v66
	v_exp_f32_e32 v67, v67
	v_add_f32_e32 v66, 1.0, v66
	v_add_f32_e32 v67, 1.0, v67
	v_rcp_f32_e32 v66, v66
	v_rcp_f32_e32 v67, v67
	v_mul_f32_e32 v66, v72, v66
	v_mul_f32_e32 v67, v73, v67
	v_mul_f32_e32 v66, v68, v66
	v_mul_f32_e32 v67, v69, v67
	v_cvt_pk_bf16_f32 v77, v66, v67
	v_mad_i64_i32 v[66:67], s[30:31], v82, s21, v[114:115]
	v_lshl_add_u64 v[66:67], v[66:67], 0, s[26:27]
	v_lshl_add_u64 v[66:67], v[66:67], 0, s[64:65]
	v_lshl_add_u64 v[66:67], v[66:67], 0, v[0:1]
	global_store_dwordx4 v[66:67], v[74:77], off
	s_cmp_eq_u32 s101, 1
	s_cbranch_scc1 .Lku_epi_skip1
	s_branch .Lku_epi_g4
.Lku_epi_skip0:
	s_lshl_b32 s19, s28, 8
	s_lshl_b32 s26, s26, 7
	s_movk_i32 s21, 0x1600
	s_ashr_i32 s27, s26, 31
	s_lshl_b64 s[26:27], s[26:27], 1
	s_andn2_b64 vcc, exec, s[6:7]
	v_mov_b64_e32 v[114:115], s[14:15]
.Lku_epi_g4:
	v_mul_f32_e32 v67, 0xbfb8aa3b, v62
	v_exp_f32_e32 v67, v67
	v_add_u32_e32 v66, s19, v150
	v_add_f32_e32 v67, 1.0, v67
	v_rcp_f32_e32 v67, v67
	s_nop 0
	v_mul_f32_e32 v62, v62, v67
	v_mul_f32_e32 v58, v58, v62
	v_mul_f32_e32 v62, 0xbfb8aa3b, v63
	v_exp_f32_e32 v62, v62
	s_nop 0
	v_add_f32_e32 v62, 1.0, v62
	v_rcp_f32_e32 v62, v62
	s_nop 0
	v_mul_f32_e32 v62, v63, v62
	v_mul_f32_e32 v59, v59, v62
	v_cvt_pk_bf16_f32 v58, v58, v59
	v_mul_f32_e32 v59, 0xbfb8aa3b, v64
	v_exp_f32_e32 v59, v59
	s_nop 0
	v_add_f32_e32 v59, 1.0, v59
	v_rcp_f32_e32 v59, v59
	s_nop 0
	v_mul_f32_e32 v59, v64, v59
	v_mul_f32_e32 v59, v60, v59
	v_mul_f32_e32 v60, 0xbfb8aa3b, v65
	v_exp_f32_e32 v60, v60
	s_nop 0
	v_add_f32_e32 v60, 1.0, v60
	v_rcp_f32_e32 v60, v60
	s_nop 0
	v_mul_f32_e32 v60, v65, v60
	v_mul_f32_e32 v60, v61, v60
	v_cvt_pk_bf16_f32 v59, v59, v60
	v_mul_f32_e32 v60, 0xbfb8aa3b, v54
	v_exp_f32_e32 v60, v60
	s_nop 0
	v_add_f32_e32 v60, 1.0, v60
	v_rcp_f32_e32 v60, v60
	s_nop 0
	v_mul_f32_e32 v54, v54, v60
	v_mul_f32_e32 v50, v50, v54
	v_mul_f32_e32 v54, 0xbfb8aa3b, v55
	v_exp_f32_e32 v54, v54
	s_nop 0
	v_add_f32_e32 v54, 1.0, v54
	v_rcp_f32_e32 v54, v54
	s_nop 0
	v_mul_f32_e32 v54, v55, v54
	v_mul_f32_e32 v51, v51, v54
	v_cvt_pk_bf16_f32 v60, v50, v51
	v_mul_f32_e32 v50, 0xbfb8aa3b, v56
	v_mul_f32_e32 v51, 0xbfb8aa3b, v57
	v_exp_f32_e32 v50, v50
	v_exp_f32_e32 v51, v51
	v_add_f32_e32 v50, 1.0, v50
	v_add_f32_e32 v51, 1.0, v51
	v_rcp_f32_e32 v50, v50
	v_rcp_f32_e32 v51, v51
	v_mul_f32_e32 v50, v56, v50
	v_mul_f32_e32 v51, v57, v51
	v_mul_f32_e32 v50, v52, v50
	v_mul_f32_e32 v51, v53, v51
	v_cvt_pk_bf16_f32 v61, v50, v51
	v_mad_i64_i32 v[50:51], s[30:31], v66, s21, v[114:115]
	v_lshl_add_u64 v[50:51], v[50:51], 0, s[26:27]
	v_lshl_add_u64 v[50:51], v[50:51], 0, s[64:65]
	v_lshl_add_u64 v[50:51], v[50:51], 0, v[0:1]
	global_store_dwordx4 v[50:51], v[58:61], off
	v_mul_f32_e32 v51, 0xbfb8aa3b, v46
	v_exp_f32_e32 v51, v51
	v_add_u32_e32 v50, s19, v151
	v_add_f32_e32 v51, 1.0, v51
	v_rcp_f32_e32 v51, v51
	s_nop 0
	v_mul_f32_e32 v46, v46, v51
	v_mul_f32_e32 v42, v42, v46
	v_mul_f32_e32 v46, 0xbfb8aa3b, v47
	v_exp_f32_e32 v46, v46
	s_nop 0
	v_add_f32_e32 v46, 1.0, v46
	v_rcp_f32_e32 v46, v46
	s_nop 0
	v_mul_f32_e32 v46, v47, v46
	v_mul_f32_e32 v43, v43, v46
	v_cvt_pk_bf16_f32 v42, v42, v43
	v_mul_f32_e32 v43, 0xbfb8aa3b, v48
	v_exp_f32_e32 v43, v43
	s_nop 0
	v_add_f32_e32 v43, 1.0, v43
	v_rcp_f32_e32 v43, v43
	s_nop 0
	v_mul_f32_e32 v43, v48, v43
	v_mul_f32_e32 v43, v44, v43
; __device__ __forceinline__ unsigned pk2(float lo, float hi) { unsigned r; asm("v_cvt_pk_bf16_f32 %0, %1, %2" : "=v"(r) : "v"(lo), "v"(hi)); return r; }
; __device__ __forceinline__ float siluf(float v) { return v * __builtin_amdgcn_rcpf(1.f + __expf(-v)); }
;     __device__ __forceinline__ void operator()(const f32x4 (&acc)[2][2][4][2], const Unit& u, int wr, int wc, int fr, int fq) const {
;     ...
;             for (int m = 0; m < 4; ++m) {
;                 const int row = u.pm * 256 + ai * 128 + wr * 64 + m * 16 + fr;
;                 const f32x4 g0 = acc[ai][0][m][0], u0 = acc[ai][0][m][1], g1 = acc[ai][1][m][0], u1 = acc[ai][1][m][1];
;                 u32x4 w;
;                 w.x = pk2(siluf(g0[0]) * u0[0], siluf(g0[1]) * u0[1]); w.y = pk2(siluf(g0[2]) * u0[2], siluf(g0[3]) * u0[3]);
;                 w.z = pk2(siluf(g1[0]) * u1[0], siluf(g1[1]) * u1[1]); w.w = pk2(siluf(g1[2]) * u1[2], siluf(g1[3]) * u1[3]);
;                 *(u32x4*)(act + (size_t)row * DFF + u.pn * 128 + wc * 32 + 8 * fq) = w;
	v_mul_f32_e32 v44, 0xbfb8aa3b, v49
	v_exp_f32_e32 v44, v44
	s_nop 0
	v_add_f32_e32 v44, 1.0, v44
	v_rcp_f32_e32 v44, v44
	s_nop 0
	v_mul_f32_e32 v44, v49, v44
	v_mul_f32_e32 v44, v45, v44
	v_cvt_pk_bf16_f32 v43, v43, v44
	v_mul_f32_e32 v44, 0xbfb8aa3b, v38
	v_exp_f32_e32 v44, v44
	s_nop 0
	v_add_f32_e32 v44, 1.0, v44
	v_rcp_f32_e32 v44, v44
	s_nop 0
	v_mul_f32_e32 v38, v38, v44
	v_mul_f32_e32 v34, v34, v38
	v_mul_f32_e32 v38, 0xbfb8aa3b, v39
	v_exp_f32_e32 v38, v38
	s_nop 0
	v_add_f32_e32 v38, 1.0, v38
	v_rcp_f32_e32 v38, v38
	s_nop 0
	v_mul_f32_e32 v38, v39, v38
	v_mul_f32_e32 v35, v35, v38
	v_cvt_pk_bf16_f32 v44, v34, v35
	v_mul_f32_e32 v34, 0xbfb8aa3b, v40
	v_mul_f32_e32 v35, 0xbfb8aa3b, v41
	v_exp_f32_e32 v34, v34
	v_exp_f32_e32 v35, v35
	v_add_f32_e32 v34, 1.0, v34
	v_add_f32_e32 v35, 1.0, v35
	v_rcp_f32_e32 v34, v34
	v_rcp_f32_e32 v35, v35
	v_mul_f32_e32 v34, v40, v34
	v_mul_f32_e32 v35, v41, v35
	v_mul_f32_e32 v34, v36, v34
	v_mul_f32_e32 v35, v37, v35
	v_cvt_pk_bf16_f32 v45, v34, v35
	v_mad_i64_i32 v[34:35], s[30:31], v50, s21, v[114:115]
	v_lshl_add_u64 v[34:35], v[34:35], 0, s[26:27]
	v_lshl_add_u64 v[34:35], v[34:35], 0, s[64:65]
	v_lshl_add_u64 v[34:35], v[34:35], 0, v[0:1]
	global_store_dwordx4 v[34:35], v[42:45], off
	v_mul_f32_e32 v35, 0xbfb8aa3b, v30
	v_exp_f32_e32 v35, v35
	v_add_u32_e32 v34, s19, v152
	v_add_f32_e32 v35, 1.0, v35
	v_rcp_f32_e32 v35, v35
	s_nop 0
	v_mul_f32_e32 v30, v30, v35
	v_mul_f32_e32 v26, v26, v30
	v_mul_f32_e32 v30, 0xbfb8aa3b, v31
	v_exp_f32_e32 v30, v30
	s_nop 0
	v_add_f32_e32 v30, 1.0, v30
	v_rcp_f32_e32 v30, v30
	s_nop 0
	v_mul_f32_e32 v30, v31, v30
	v_mul_f32_e32 v27, v27, v30
	v_cvt_pk_bf16_f32 v26, v26, v27
	v_mul_f32_e32 v27, 0xbfb8aa3b, v32
	v_exp_f32_e32 v27, v27
	s_nop 0
	v_add_f32_e32 v27, 1.0, v27
	v_rcp_f32_e32 v27, v27
	s_nop 0
	v_mul_f32_e32 v27, v32, v27
	v_mul_f32_e32 v27, v28, v27
	v_mul_f32_e32 v28, 0xbfb8aa3b, v33
	v_exp_f32_e32 v28, v28
	s_nop 0
	v_add_f32_e32 v28, 1.0, v28
	v_rcp_f32_e32 v28, v28
	s_nop 0
	v_mul_f32_e32 v28, v33, v28
	v_mul_f32_e32 v28, v29, v28
	v_cvt_pk_bf16_f32 v27, v27, v28
	v_mul_f32_e32 v28, 0xbfb8aa3b, v22
	v_exp_f32_e32 v28, v28
	s_nop 0
	v_add_f32_e32 v28, 1.0, v28
	v_rcp_f32_e32 v28, v28
	s_nop 0
	v_mul_f32_e32 v22, v22, v28
	v_mul_f32_e32 v18, v18, v22
	v_mul_f32_e32 v22, 0xbfb8aa3b, v23
	v_exp_f32_e32 v22, v22
	s_nop 0
	v_add_f32_e32 v22, 1.0, v22
	v_rcp_f32_e32 v22, v22
	s_nop 0
	v_mul_f32_e32 v22, v23, v22
	v_mul_f32_e32 v19, v19, v22
	v_cvt_pk_bf16_f32 v28, v18, v19
	v_mul_f32_e32 v18, 0xbfb8aa3b, v24
	v_mul_f32_e32 v19, 0xbfb8aa3b, v25
	v_exp_f32_e32 v18, v18
	v_exp_f32_e32 v19, v19
	v_add_f32_e32 v18, 1.0, v18
	v_add_f32_e32 v19, 1.0, v19
	v_rcp_f32_e32 v18, v18
	v_rcp_f32_e32 v19, v19
	v_mul_f32_e32 v18, v24, v18
	v_mul_f32_e32 v19, v25, v19
	v_mul_f32_e32 v18, v20, v18
	v_mul_f32_e32 v19, v21, v19
	v_cvt_pk_bf16_f32 v29, v18, v19
	v_mad_i64_i32 v[18:19], s[30:31], v34, s21, v[114:115]
	v_lshl_add_u64 v[18:19], v[18:19], 0, s[26:27]
	v_lshl_add_u64 v[18:19], v[18:19], 0, s[64:65]
	v_lshl_add_u64 v[18:19], v[18:19], 0, v[0:1]
	global_store_dwordx4 v[18:19], v[26:29], off
	v_mul_f32_e32 v19, 0xbfb8aa3b, v14
	v_exp_f32_e32 v19, v19
	v_add_u32_e32 v18, s19, v153
	v_add_f32_e32 v19, 1.0, v19
	v_rcp_f32_e32 v19, v19
	s_nop 0
	v_mul_f32_e32 v14, v14, v19
	v_mul_f32_e32 v10, v10, v14
	v_mul_f32_e32 v14, 0xbfb8aa3b, v15
	v_exp_f32_e32 v14, v14
	s_nop 0
	v_add_f32_e32 v14, 1.0, v14
	v_rcp_f32_e32 v14, v14
	s_nop 0
	v_mul_f32_e32 v14, v15, v14
	v_mul_f32_e32 v11, v11, v14
	v_cvt_pk_bf16_f32 v10, v10, v11
	v_mul_f32_e32 v11, 0xbfb8aa3b, v16
	v_exp_f32_e32 v11, v11
	s_nop 0
	v_add_f32_e32 v11, 1.0, v11
	v_rcp_f32_e32 v11, v11
	s_nop 0
	v_mul_f32_e32 v11, v16, v11
	v_mul_f32_e32 v11, v12, v11
	v_mul_f32_e32 v12, 0xbfb8aa3b, v17
	v_exp_f32_e32 v12, v12
	s_nop 0
	v_add_f32_e32 v12, 1.0, v12
	v_rcp_f32_e32 v12, v12
	s_nop 0
	v_mul_f32_e32 v12, v17, v12
	v_mul_f32_e32 v12, v13, v12
	v_cvt_pk_bf16_f32 v11, v11, v12
	v_mul_f32_e32 v12, 0xbfb8aa3b, v6
	v_exp_f32_e32 v12, v12
	s_nop 0
	v_add_f32_e32 v12, 1.0, v12
	v_rcp_f32_e32 v12, v12
	s_nop 0
	v_mul_f32_e32 v6, v6, v12
	v_mul_f32_e32 v2, v2, v6
	v_mul_f32_e32 v6, 0xbfb8aa3b, v7
	v_exp_f32_e32 v6, v6
	s_nop 0
	v_add_f32_e32 v6, 1.0, v6
	v_rcp_f32_e32 v6, v6
	s_nop 0
	v_mul_f32_e32 v6, v7, v6
	v_mul_f32_e32 v3, v3, v6
	v_cvt_pk_bf16_f32 v12, v2, v3
	v_mul_f32_e32 v2, 0xbfb8aa3b, v8
	v_mul_f32_e32 v3, 0xbfb8aa3b, v9
	v_exp_f32_e32 v2, v2
	v_exp_f32_e32 v3, v3
	v_add_f32_e32 v2, 1.0, v2
	v_add_f32_e32 v3, 1.0, v3
	v_rcp_f32_e32 v2, v2
	v_rcp_f32_e32 v3, v3
	v_mul_f32_e32 v2, v8, v2
	v_mul_f32_e32 v3, v9, v3
	v_mul_f32_e32 v2, v4, v2
	v_mul_f32_e32 v3, v5, v3
	v_cvt_pk_bf16_f32 v13, v2, v3
	v_mad_i64_i32 v[2:3], s[30:31], v18, s21, v[114:115]
	v_lshl_add_u64 v[2:3], v[2:3], 0, s[26:27]
	v_lshl_add_u64 v[2:3], v[2:3], 0, s[64:65]
	v_lshl_add_u64 v[2:3], v[2:3], 0, v[0:1]
	s_mov_b64 s[26:27], -1
	global_store_dwordx4 v[2:3], v[10:13], off
	s_branch .Lku_epi_end
.Lku_epi_skip1:
	s_mov_b64 s[26:27], -1
.Lku_epi_end:
	s_cbranch_vccnz .LBB0_159
	s_andn2_b64 vcc, exec, s[12:13]
	s_cbranch_vccnz .LBB0_158
	s_barrier
	s_branch .LBB0_158

;     __host__ __device__ bool next(int i, Unit& u) const {
;         const long L = (long)i * G + c; if (L >= nwg) return false;
;         int wgid = (int)L; { const int q = nwg / NXCD, r = nwg % NXCD, xcd = wgid % NXCD, off = wgid / NXCD; wgid = (xcd < r ? xcd * (q + 1) : r * (q + 1) + (xcd - r) * q) + off; }
;         const int nig = WGM * nN, gid = wgid / nig, fm = gid * WGM, gsz = (nM - fm) < WGM ? (nM - fm) : WGM;
;         u.pm = fm + ((wgid % nig) % gsz); u.pn = (wgid % nig) / gsz; return true;
; template <class Epi, class Sched, bool ALIGN_EPI = false, bool SP2 = false>
; __device__ __forceinline__ void gemm_phase(PG8_LAS unsigned char* lds, const Gemm g, const Sched& S, const Epi& E) {
;     ...
;         const bool has_next = S.next(ui + 1, nxt);
.LBB0_842:
	s_mov_b32 s101, s100
	s_add_i32 s11, s11, 1
	s_mul_i32 s6, s11, s39
	s_mul_hi_u32 s7, s11, s38
	s_add_i32 s7, s7, s6
	s_mul_i32 s6, s11, s38
	v_readlane_b32 s8, v254, 56
	v_readlane_b32 s9, v254, 57
	s_add_u32 s6, s6, s8
	s_addc_u32 s7, s7, s9
	s_sub_i32 s80, s6, s8
	s_sub_i32 s81, s64, s80
	s_mov_b32 s100, 0
	s_cmp_lt_i32 s81, 1
	s_cbranch_scc1 .Lhr_done
	s_lshl_b32 s82, s81, 1
	s_cmp_gt_u32 s82, s38
	s_cbranch_scc1 .Lhr_done
	s_cmp_lt_u32 s8, s81
	s_cbranch_scc0 .Lhr_second
	s_mov_b32 s100, 1
	s_branch .Lhr_done
.Lhr_second:
	s_cmp_lt_u32 s8, s82
	s_cbranch_scc0 .Lhr_done
	s_sub_u32 s6, s6, s81
	s_subb_u32 s7, s7, 0
	s_mov_b32 s100, 2
.Lhr_done:
	v_mov_b64_e32 v[2:3], s[64:65]
	v_cmp_ge_i64_e32 vcc, s[6:7], v[2:3]
	v_cmp_lt_i64_e64 s[8:9], s[6:7], v[2:3]
	s_cbranch_vccnz .LBB0_844
	s_ashr_i32 s7, s6, 31
	s_lshr_b32 s7, s7, 29
	s_add_i32 s7, s6, s7
	s_ashr_i32 s46, s7, 3
	s_and_b32 s7, s7, -8
	s_sub_i32 s6, s6, s7
	s_cmp_lt_i32 s6, 0
	s_cselect_b32 s7, s92, s91
	s_mul_i32 s6, s7, s6
	s_add_i32 s6, s6, s46
	s_ashr_i32 s7, s6, 31
	s_lshr_b32 s7, s7, 28
	s_add_i32 s7, s6, s7
	s_ashr_i32 s46, s7, 4
	s_lshl_b32 s46, s46, 2
	s_sub_i32 s47, s89, s46
	s_min_i32 s47, s47, 4
	s_abs_i32 s54, s47
	v_cvt_f32_u32_e32 v2, s54
	s_sub_i32 s80, 0, s54
	s_and_b32 s7, s7, -16
	s_sub_i32 s6, s6, s7
	v_rcp_iflag_f32_e32 v2, v2
	s_abs_i32 s7, s6
	s_xor_b32 s71, s6, s47
	s_ashr_i32 s71, s71, 31
	v_mul_f32_e32 v2, 0x4f7ffffe, v2
	v_cvt_u32_f32_e32 v2, v2
	s_nop 0
	v_readfirstlane_b32 s81, v2
	s_mul_i32 s80, s80, s81
	s_mul_hi_u32 s80, s81, s80
	s_add_i32 s81, s81, s80
	s_mul_hi_u32 s80, s7, s81
	s_mul_i32 s81, s80, s54
	s_sub_i32 s7, s7, s81
	s_add_i32 s82, s80, 1
	s_sub_i32 s81, s7, s54
	s_cmp_ge_u32 s7, s54
	s_cselect_b32 s80, s82, s80
	s_cselect_b32 s7, s81, s7
	s_add_i32 s81, s80, 1
	s_cmp_ge_u32 s7, s54
	s_cselect_b32 s7, s81, s80
	s_xor_b32 s7, s7, s71
	s_sub_i32 s71, s7, s71
	s_mul_i32 s7, s71, s47
	s_sub_i32 s6, s6, s7
	s_add_i32 s54, s6, s46

; #define PG8_STAGE(bufoff, gbase, voff) do { _Pragma("unroll") for (int _i = 0; _i < 2; ++_i) \
;         __builtin_amdgcn_global_load_lds((const unsigned*)((const char*)(gbase) + (voff)[_i]), (PG8_LAS unsigned*)(lds + (bufoff) + ldsw + _i * 8192), 16, 0, 0); } while (0)
; #define PG8_LDA(dst, b, h) do { _Pragma("unroll") for (int m = 0; m < 4; ++m) _Pragma("unroll") for (int k = 0; k < 2; ++k) dst[m][k] = *(const PG8_LAS bf16x8*)(lds + PG8_SA(b, h) + aoff + m * 2048 + k * 1024); } while (0)
; #define PG8_LDB(dst, b, h) do { _Pragma("unroll") for (int n = 0; n < 2; ++n) _Pragma("unroll") for (int k = 0; k < 2; ++k) dst[n][k] = *(const PG8_LAS bf16x8*)(lds + PG8_SB(b, h) + boff + n * 2048 + k * 1024); } while (0)
; #define PG8_MMA(ai, bj, At, Bt) do { __builtin_amdgcn_s_setprio(1); _Pragma("unroll") for (int m = 0; m < 4; ++m) _Pragma("unroll") for (int n = 0; n < 2; ++n) _Pragma("unroll") for (int k = 0; k < 2; ++k) \
;         acc[ai][bj][m][n] = __builtin_amdgcn_mfma_f32_16x16x32_bf16(Bt[n][k], At[m][k], acc[ai][bj][m][n], 0, 0, 0); __builtin_amdgcn_s_setprio(0); } while (0)
; #define PG8_WAIT_V(n) asm volatile("s_waitcnt vmcnt(" #n ")" ::: "memory")
; #define PG8_WAIT_L(n) asm volatile("s_waitcnt lgkmcnt(" #n ")" ::: "memory")
; #define PG8_BAR __builtin_amdgcn_s_barrier()
; #define PG8_SCHED __builtin_amdgcn_sched_barrier(0)
; template <class Epi, class Sched, bool ALIGN_EPI = false, bool SP2 = false>
; __device__ __forceinline__ void gemm_phase(PG8_LAS unsigned char* lds, const Gemm g, const Sched& S, const Epi& E) {
;     ...
;             PG8_LDB(B0, 0, 0); PG8_LDB(B1, 0, 1); PG8_SCHED; PG8_LDA(At, 0, 0); PG8_STAGE(PG8_SA(1, 1), a1 + hstep, voffA);
;             PG8_WAIT_V(8); PG8_WAIT_L(0); PG8_BAR; PG8_MMA(0, 0, At, B0); PG8_MMA(0, 1, At, B1); PG8_BAR; PG8_SCHED;
;     ...
; #pragma unroll
;         for (int a = 0; a < 2; ++a)
; #pragma unroll
;             for (int b = 0; b < 2; ++b)
; #pragma unroll
;                 for (int m = 0; m < 4; ++m)
; #pragma unroll
;                     for (int n = 0; n < 2; ++n) acc[a][b][m][n] = (f32x4){0.f, 0.f, 0.f, 0.f};
.LBB0_848:
	s_add_u32 s48, s48, 0x80
	s_addc_u32 s49, s49, 0
	s_add_u32 s80, s76, 0x100
	v_mov_b32_e32 v2, 0
	s_addc_u32 s81, s77, 0
	s_mov_b32 s76, 0
	v_mov_b32_e32 v3, v2
	v_mov_b32_e32 v4, v2
	v_mov_b32_e32 v5, v2
	v_mov_b32_e32 v6, v2
	v_mov_b32_e32 v7, v2
	v_mov_b32_e32 v8, v2
	v_mov_b32_e32 v9, v2
	v_mov_b32_e32 v18, v2
	v_mov_b32_e32 v19, v2
	v_mov_b32_e32 v20, v2
	v_mov_b32_e32 v21, v2
	v_mov_b32_e32 v22, v2
	v_mov_b32_e32 v23, v2
	v_mov_b32_e32 v24, v2
	v_mov_b32_e32 v25, v2
	v_mov_b32_e32 v34, v2
	v_mov_b32_e32 v35, v2
	v_mov_b32_e32 v36, v2
	v_mov_b32_e32 v37, v2
	v_mov_b32_e32 v38, v2
	v_mov_b32_e32 v39, v2
	v_mov_b32_e32 v40, v2
	v_mov_b32_e32 v41, v2
	v_mov_b32_e32 v50, v2
	v_mov_b32_e32 v51, v2
	v_mov_b32_e32 v52, v2
	v_mov_b32_e32 v53, v2
	v_mov_b32_e32 v54, v2
	v_mov_b32_e32 v55, v2
	v_mov_b32_e32 v56, v2
	v_mov_b32_e32 v57, v2
	v_mov_b32_e32 v10, v2
	v_mov_b32_e32 v11, v2
	v_mov_b32_e32 v12, v2
	v_mov_b32_e32 v13, v2
	v_mov_b32_e32 v14, v2
	v_mov_b32_e32 v15, v2
	v_mov_b32_e32 v16, v2
	v_mov_b32_e32 v17, v2
	v_mov_b32_e32 v26, v2
	v_mov_b32_e32 v27, v2
	v_mov_b32_e32 v28, v2
	v_mov_b32_e32 v29, v2
	v_mov_b32_e32 v30, v2
	v_mov_b32_e32 v31, v2
	v_mov_b32_e32 v32, v2
	v_mov_b32_e32 v33, v2
	v_mov_b32_e32 v42, v2
	v_mov_b32_e32 v43, v2
	v_mov_b32_e32 v44, v2
	v_mov_b32_e32 v45, v2
	v_mov_b32_e32 v46, v2
	v_mov_b32_e32 v47, v2
	v_mov_b32_e32 v48, v2
	v_mov_b32_e32 v49, v2
	v_mov_b32_e32 v58, v2
	v_mov_b32_e32 v59, v2
	v_mov_b32_e32 v60, v2
	v_mov_b32_e32 v61, v2
	v_mov_b32_e32 v62, v2
	v_mov_b32_e32 v63, v2
	v_mov_b32_e32 v64, v2
	v_mov_b32_e32 v65, v2
	v_mov_b32_e32 v66, v2
	v_mov_b32_e32 v67, v2
	v_mov_b32_e32 v68, v2
	v_mov_b32_e32 v69, v2
	v_mov_b32_e32 v70, v2
	v_mov_b32_e32 v71, v2
	v_mov_b32_e32 v72, v2
	v_mov_b32_e32 v73, v2
	v_mov_b32_e32 v82, v2
	v_mov_b32_e32 v83, v2
	v_mov_b32_e32 v84, v2
	v_mov_b32_e32 v85, v2
	v_mov_b32_e32 v86, v2
	v_mov_b32_e32 v87, v2
	v_mov_b32_e32 v88, v2
	v_mov_b32_e32 v89, v2
	v_mov_b32_e32 v98, v2
	v_mov_b32_e32 v99, v2
	v_mov_b32_e32 v100, v2
	v_mov_b32_e32 v101, v2
	v_mov_b32_e32 v102, v2
	v_mov_b32_e32 v103, v2
	v_mov_b32_e32 v104, v2
	v_mov_b32_e32 v105, v2
	v_mov_b32_e32 v114, v2
	v_mov_b32_e32 v115, v2
	v_mov_b32_e32 v116, v2
	v_mov_b32_e32 v117, v2
	v_mov_b32_e32 v118, v2
	v_mov_b32_e32 v119, v2
	v_mov_b32_e32 v120, v2
	v_mov_b32_e32 v121, v2
	v_mov_b32_e32 v74, v2
	v_mov_b32_e32 v75, v2
	v_mov_b32_e32 v76, v2
	v_mov_b32_e32 v77, v2
	v_mov_b32_e32 v78, v2
	v_mov_b32_e32 v79, v2
	v_mov_b32_e32 v80, v2
	v_mov_b32_e32 v81, v2
	v_mov_b32_e32 v90, v2
	v_mov_b32_e32 v91, v2
	v_mov_b32_e32 v92, v2
	v_mov_b32_e32 v93, v2
	v_mov_b32_e32 v94, v2
	v_mov_b32_e32 v95, v2
	v_mov_b32_e32 v96, v2
	v_mov_b32_e32 v97, v2
	v_mov_b32_e32 v106, v2
	v_mov_b32_e32 v107, v2
	v_mov_b32_e32 v108, v2
	v_mov_b32_e32 v109, v2
	v_mov_b32_e32 v110, v2
	v_mov_b32_e32 v111, v2
	v_mov_b32_e32 v112, v2
	v_mov_b32_e32 v113, v2
	v_mov_b32_e32 v122, v2
	v_mov_b32_e32 v123, v2
	v_mov_b32_e32 v124, v2
	v_mov_b32_e32 v125, v2
	v_mov_b32_e32 v126, v2
	v_mov_b32_e32 v127, v2
	v_mov_b32_e32 v128, v2
	v_mov_b32_e32 v129, v2
	s_cmp_lg_u32 s101, 0
	s_cbranch_scc0 .LBB0_849
	s_cmp_eq_u32 s101, 1
	s_cbranch_scc1 .Lkr_a0
	s_branch .Lkr_a1
.LBB0_849:
	s_add_i32 s82, s76, 2
	s_add_u32 s83, s48, 0x80
	s_addc_u32 s77, s49, 0
	s_add_i32 s59, 0, 0x10000
	s_cmp_eq_u32 s72, s76
	s_cselect_b32 s77, s9, s77
	s_cselect_b32 s76, s8, s83
	v_add_u32_e32 v136, s59, v147
	s_cselect_b32 vcc_hi, s47, s81
	s_cselect_b32 vcc_lo, s46, s80
	s_add_i32 s83, 0, 0x14000
	ds_read_b128 v[148:151], v136
	ds_read_b128 v[152:155], v136 offset:1024
	ds_read_b128 v[156:159], v136 offset:2048
	ds_read_b128 v[160:163], v136 offset:3072
	v_add_u32_e32 v136, s83, v147
	ds_read_b128 v[166:169], v136
	ds_read_b128 v[170:173], v136 offset:1024
	ds_read_b128 v[174:177], v136 offset:2048
	ds_read_b128 v[178:181], v136 offset:3072
	v_lshl_add_u64 v[136:137], s[48:49], 0, v[132:133]
	s_add_i32 m0, s94, 0xc000
	ds_read_b128 v[202:205], v165
	ds_read_b128 v[208:211], v165 offset:1024
	ds_read_b128 v[212:215], v165 offset:2048
	ds_read_b128 v[216:219], v165 offset:3072
	ds_read_b128 v[220:223], v165 offset:4096
	ds_read_b128 v[224:227], v165 offset:5120
	ds_read_b128 v[228:231], v165 offset:6144
	ds_read_b128 v[232:235], v165 offset:7168
	global_load_lds_dwordx4 v[136:137], off
	v_lshl_add_u64 v[136:137], s[48:49], 0, v[134:135]
	s_add_i32 m0, s94, 0xe000
	s_nop 0
	global_load_lds_dwordx4 v[136:137], off
	s_waitcnt vmcnt(8)
	s_waitcnt lgkmcnt(0)
	s_barrier
; #define PG8_STAGE(bufoff, gbase, voff) do { _Pragma("unroll") for (int _i = 0; _i < 2; ++_i) \
;         __builtin_amdgcn_global_load_lds((const unsigned*)((const char*)(gbase) + (voff)[_i]), (PG8_LAS unsigned*)(lds + (bufoff) + ldsw + _i * 8192), 16, 0, 0); } while (0)
; #define PG8_LDA(dst, b, h) do { _Pragma("unroll") for (int m = 0; m < 4; ++m) _Pragma("unroll") for (int k = 0; k < 2; ++k) dst[m][k] = *(const PG8_LAS bf16x8*)(lds + PG8_SA(b, h) + aoff + m * 2048 + k * 1024); } while (0)
; #define PG8_MMA(ai, bj, At, Bt) do { __builtin_amdgcn_s_setprio(1); _Pragma("unroll") for (int m = 0; m < 4; ++m) _Pragma("unroll") for (int n = 0; n < 2; ++n) _Pragma("unroll") for (int k = 0; k < 2; ++k) \
;         acc[ai][bj][m][n] = __builtin_amdgcn_mfma_f32_16x16x32_bf16(Bt[n][k], At[m][k], acc[ai][bj][m][n], 0, 0, 0); __builtin_amdgcn_s_setprio(0); } while (0)
; #define PG8_WAIT_V(n) asm volatile("s_waitcnt vmcnt(" #n ")" ::: "memory")
; #define PG8_WAIT_L(n) asm volatile("s_waitcnt lgkmcnt(" #n ")" ::: "memory")
; #define PG8_BAR __builtin_amdgcn_s_barrier()
; #define PG8_SCHED __builtin_amdgcn_sched_barrier(0)
; template <class Epi, class Sched, bool ALIGN_EPI = false, bool SP2 = false>
; __device__ __forceinline__ void gemm_phase(PG8_LAS unsigned char* lds, const Gemm g, const Sched& S, const Epi& E) {
;     ...
;             PG8_WAIT_V(8); PG8_WAIT_L(0); PG8_BAR; PG8_MMA(0, 0, At, B0); PG8_MMA(0, 1, At, B1); PG8_BAR; PG8_SCHED;
;             PG8_LDA(At, 0, 1); PG8_STAGE(PG8_SB(0, 0), b2, voffB); PG8_STAGE(PG8_SB(0, 1), b2 + hstep, voffB); PG8_STAGE(PG8_SA(0, 0), a2, voffA);
;             PG8_WAIT_V(8); PG8_WAIT_L(0); PG8_BAR; PG8_MMA(1, 0, At, B0); PG8_MMA(1, 1, At, B1); PG8_BAR; PG8_SCHED;
	s_setprio 1
	s_waitcnt lgkmcnt(0)
	v_mfma_f32_16x16x32_bf16 v[126:129], v[148:151], v[202:205], v[126:129]
	v_mfma_f32_16x16x32_bf16 v[122:125], v[156:159], v[202:205], v[122:125]
	v_mfma_f32_16x16x32_bf16 v[110:113], v[148:151], v[212:215], v[110:113]
	v_mfma_f32_16x16x32_bf16 v[106:109], v[156:159], v[212:215], v[106:109]
	v_mfma_f32_16x16x32_bf16 v[94:97], v[148:151], v[220:223], v[94:97]
	v_mfma_f32_16x16x32_bf16 v[90:93], v[156:159], v[220:223], v[90:93]
	v_mfma_f32_16x16x32_bf16 v[78:81], v[148:151], v[228:231], v[78:81]
	v_mfma_f32_16x16x32_bf16 v[74:77], v[156:159], v[228:231], v[74:77]
	v_mfma_f32_16x16x32_bf16 v[126:129], v[152:155], v[208:211], v[126:129]
	v_mfma_f32_16x16x32_bf16 v[122:125], v[160:163], v[208:211], v[122:125]
	v_mfma_f32_16x16x32_bf16 v[110:113], v[152:155], v[216:219], v[110:113]
	v_mfma_f32_16x16x32_bf16 v[106:109], v[160:163], v[216:219], v[106:109]
	v_mfma_f32_16x16x32_bf16 v[94:97], v[152:155], v[224:227], v[94:97]
	v_mfma_f32_16x16x32_bf16 v[90:93], v[160:163], v[224:227], v[90:93]
	v_mfma_f32_16x16x32_bf16 v[78:81], v[152:155], v[232:235], v[78:81]
	v_mfma_f32_16x16x32_bf16 v[74:77], v[160:163], v[232:235], v[74:77]
	s_setprio 0
	s_setprio 1
	v_mfma_f32_16x16x32_bf16 v[118:121], v[166:169], v[202:205], v[118:121]
	v_mfma_f32_16x16x32_bf16 v[114:117], v[174:177], v[202:205], v[114:117]
	v_mfma_f32_16x16x32_bf16 v[102:105], v[166:169], v[212:215], v[102:105]
	v_mfma_f32_16x16x32_bf16 v[98:101], v[174:177], v[212:215], v[98:101]
	v_mfma_f32_16x16x32_bf16 v[86:89], v[166:169], v[220:223], v[86:89]
	v_mfma_f32_16x16x32_bf16 v[82:85], v[174:177], v[220:223], v[82:85]
	v_mfma_f32_16x16x32_bf16 v[70:73], v[166:169], v[228:231], v[70:73]
	v_mfma_f32_16x16x32_bf16 v[66:69], v[174:177], v[228:231], v[66:69]
	v_mfma_f32_16x16x32_bf16 v[118:121], v[170:173], v[208:211], v[118:121]
	v_mfma_f32_16x16x32_bf16 v[114:117], v[178:181], v[208:211], v[114:117]
	v_mfma_f32_16x16x32_bf16 v[102:105], v[170:173], v[216:219], v[102:105]
	v_mfma_f32_16x16x32_bf16 v[98:101], v[178:181], v[216:219], v[98:101]
	v_mfma_f32_16x16x32_bf16 v[86:89], v[170:173], v[224:227], v[86:89]
	v_mfma_f32_16x16x32_bf16 v[82:85], v[178:181], v[224:227], v[82:85]
	v_mfma_f32_16x16x32_bf16 v[70:73], v[170:173], v[232:235], v[70:73]
	v_mfma_f32_16x16x32_bf16 v[66:69], v[178:181], v[232:235], v[66:69]
	s_setprio 0
	s_barrier
	s_add_i32 s59, s59, s93
	v_lshl_add_u64 v[136:137], vcc, 0, v[0:1]
	s_mov_b32 m0, s59
	ds_read_b128 v[202:205], v165 offset:16384
	ds_read_b128 v[208:211], v165 offset:17408
	ds_read_b128 v[212:215], v165 offset:18432
	ds_read_b128 v[216:219], v165 offset:19456
	ds_read_b128 v[220:223], v165 offset:20480
	ds_read_b128 v[224:227], v165 offset:21504
	ds_read_b128 v[228:231], v165 offset:22528
	ds_read_b128 v[232:235], v165 offset:23552
	global_load_lds_dwordx4 v[136:137], off
	s_add_i32 m0, s59, 0x2000
	v_lshl_add_u64 v[144:145], vcc, 0, v[130:131]
	s_add_u32 vcc_lo, vcc_lo, s10
	s_addc_u32 vcc_hi, vcc_hi, 0
	s_add_i32 s59, s83, s93
	global_load_lds_dwordx4 v[144:145], off
	v_lshl_add_u64 v[182:183], vcc, 0, v[0:1]
	s_mov_b32 m0, s59
	v_lshl_add_u64 v[236:237], vcc, 0, v[130:131]
	global_load_lds_dwordx4 v[182:183], off
	s_add_i32 m0, s59, 0x2000
	v_lshl_add_u64 v[238:239], s[76:77], 0, v[0:1]
	global_load_lds_dwordx4 v[236:237], off
	s_mov_b32 m0, s94
	v_lshl_add_u64 v[240:241], s[76:77], 0, v[130:131]
	global_load_lds_dwordx4 v[238:239], off
	s_mov_b32 m0, s95
	s_nop 0
	global_load_lds_dwordx4 v[240:241], off
	s_waitcnt vmcnt(8)
	s_waitcnt lgkmcnt(0)
	s_barrier
	s_setprio 1
	s_waitcnt lgkmcnt(0)
	v_mfma_f32_16x16x32_bf16 v[62:65], v[148:151], v[202:205], v[62:65]
	v_mfma_f32_16x16x32_bf16 v[58:61], v[156:159], v[202:205], v[58:61]
	v_mfma_f32_16x16x32_bf16 v[46:49], v[148:151], v[212:215], v[46:49]
	v_mfma_f32_16x16x32_bf16 v[42:45], v[156:159], v[212:215], v[42:45]
	v_mfma_f32_16x16x32_bf16 v[30:33], v[148:151], v[220:223], v[30:33]
	v_mfma_f32_16x16x32_bf16 v[26:29], v[156:159], v[220:223], v[26:29]
	v_mfma_f32_16x16x32_bf16 v[14:17], v[148:151], v[228:231], v[14:17]
	v_mfma_f32_16x16x32_bf16 v[10:13], v[156:159], v[228:231], v[10:13]
	v_mfma_f32_16x16x32_bf16 v[62:65], v[152:155], v[208:211], v[62:65]
	v_mfma_f32_16x16x32_bf16 v[58:61], v[160:163], v[208:211], v[58:61]
	v_mfma_f32_16x16x32_bf16 v[46:49], v[152:155], v[216:219], v[46:49]
	v_mfma_f32_16x16x32_bf16 v[42:45], v[160:163], v[216:219], v[42:45]
	v_mfma_f32_16x16x32_bf16 v[30:33], v[152:155], v[224:227], v[30:33]
	v_mfma_f32_16x16x32_bf16 v[26:29], v[160:163], v[224:227], v[26:29]
	v_mfma_f32_16x16x32_bf16 v[14:17], v[152:155], v[232:235], v[14:17]
	v_mfma_f32_16x16x32_bf16 v[10:13], v[160:163], v[232:235], v[10:13]
	s_setprio 0
	s_setprio 1
	v_mfma_f32_16x16x32_bf16 v[54:57], v[166:169], v[202:205], v[54:57]
	v_mfma_f32_16x16x32_bf16 v[50:53], v[174:177], v[202:205], v[50:53]
	v_mfma_f32_16x16x32_bf16 v[38:41], v[166:169], v[212:215], v[38:41]
	v_mfma_f32_16x16x32_bf16 v[34:37], v[174:177], v[212:215], v[34:37]
	v_mfma_f32_16x16x32_bf16 v[22:25], v[166:169], v[220:223], v[22:25]
	v_mfma_f32_16x16x32_bf16 v[18:21], v[174:177], v[220:223], v[18:21]
	v_mfma_f32_16x16x32_bf16 v[6:9], v[166:169], v[228:231], v[6:9]
	v_mfma_f32_16x16x32_bf16 v[2:5], v[174:177], v[228:231], v[2:5]
	v_mfma_f32_16x16x32_bf16 v[54:57], v[170:173], v[208:211], v[54:57]
	v_mfma_f32_16x16x32_bf16 v[50:53], v[178:181], v[208:211], v[50:53]
	v_mfma_f32_16x16x32_bf16 v[38:41], v[170:173], v[216:219], v[38:41]
	v_mfma_f32_16x16x32_bf16 v[34:37], v[178:181], v[216:219], v[34:37]
	v_mfma_f32_16x16x32_bf16 v[22:25], v[170:173], v[224:227], v[22:25]
	v_mfma_f32_16x16x32_bf16 v[18:21], v[178:181], v[224:227], v[18:21]
	v_mfma_f32_16x16x32_bf16 v[6:9], v[170:173], v[232:235], v[6:9]
	v_mfma_f32_16x16x32_bf16 v[2:5], v[178:181], v[232:235], v[2:5]
	s_setprio 0
	s_barrier
; #define PG8_STAGE(bufoff, gbase, voff) do { _Pragma("unroll") for (int _i = 0; _i < 2; ++_i) \
;         __builtin_amdgcn_global_load_lds((const unsigned*)((const char*)(gbase) + (voff)[_i]), (PG8_LAS unsigned*)(lds + (bufoff) + ldsw + _i * 8192), 16, 0, 0); } while (0)
; #define PG8_LDA(dst, b, h) do { _Pragma("unroll") for (int m = 0; m < 4; ++m) _Pragma("unroll") for (int k = 0; k < 2; ++k) dst[m][k] = *(const PG8_LAS bf16x8*)(lds + PG8_SA(b, h) + aoff + m * 2048 + k * 1024); } while (0)
; #define PG8_LDB(dst, b, h) do { _Pragma("unroll") for (int n = 0; n < 2; ++n) _Pragma("unroll") for (int k = 0; k < 2; ++k) dst[n][k] = *(const PG8_LAS bf16x8*)(lds + PG8_SB(b, h) + boff + n * 2048 + k * 1024); } while (0)
; #define PG8_MMA(ai, bj, At, Bt) do { __builtin_amdgcn_s_setprio(1); _Pragma("unroll") for (int m = 0; m < 4; ++m) _Pragma("unroll") for (int n = 0; n < 2; ++n) _Pragma("unroll") for (int k = 0; k < 2; ++k) \
;         acc[ai][bj][m][n] = __builtin_amdgcn_mfma_f32_16x16x32_bf16(Bt[n][k], At[m][k], acc[ai][bj][m][n], 0, 0, 0); __builtin_amdgcn_s_setprio(0); } while (0)
; #define PG8_WAIT_V(n) asm volatile("s_waitcnt vmcnt(" #n ")" ::: "memory")
; #define PG8_WAIT_L(n) asm volatile("s_waitcnt lgkmcnt(" #n ")" ::: "memory")
; #define PG8_BAR __builtin_amdgcn_s_barrier()
; #define PG8_SCHED __builtin_amdgcn_sched_barrier(0)
; template <class Epi, class Sched, bool ALIGN_EPI = false, bool SP2 = false>
; __device__ __forceinline__ void gemm_phase(PG8_LAS unsigned char* lds, const Gemm g, const Sched& S, const Epi& E) {
;     ...
;             PG8_LDB(B0, 1, 0); PG8_LDB(B1, 1, 1); PG8_SCHED; PG8_LDA(At, 1, 0); PG8_STAGE(PG8_SA(0, 1), a2 + hstep, voffA);
;             PG8_WAIT_V(8); PG8_WAIT_L(0); PG8_BAR; PG8_MMA(0, 0, At, B0); PG8_MMA(0, 1, At, B1); PG8_BAR; PG8_SCHED;
;             PG8_LDA(At, 1, 1); PG8_STAGE(PG8_SB(1, 0), b3, voffB); PG8_STAGE(PG8_SB(1, 1), b3 + hstep, voffB); PG8_STAGE(PG8_SA(1, 0), a3, voffA);
;             PG8_WAIT_V(8); PG8_WAIT_L(0); PG8_BAR; PG8_MMA(1, 0, At, B0); PG8_MMA(1, 1, At, B1); PG8_BAR; PG8_SCHED;
	s_add_i32 s59, 0, 0x18000
	s_add_i32 s83, 0, 0x1c000
	v_add_u32_e32 v160, s59, v147
	v_add_u32_e32 v178, s83, v147
	ds_read_b128 v[148:151], v160
	ds_read_b128 v[152:155], v160 offset:1024
	ds_read_b128 v[156:159], v160 offset:2048
	ds_read_b128 v[160:163], v160 offset:3072
	ds_read_b128 v[166:169], v178
	ds_read_b128 v[170:173], v178 offset:1024
	ds_read_b128 v[174:177], v178 offset:2048
	ds_read_b128 v[178:181], v178 offset:3072
	s_add_u32 s76, s76, s10
	s_addc_u32 s77, s77, 0
	s_mov_b32 m0, s84
	v_lshl_add_u64 v[242:243], s[76:77], 0, v[0:1]
	ds_read_b128 v[202:205], v165 offset:32768
	ds_read_b128 v[208:211], v165 offset:33792
	ds_read_b128 v[212:215], v165 offset:34816
	ds_read_b128 v[216:219], v165 offset:35840
	ds_read_b128 v[220:223], v165 offset:36864
	ds_read_b128 v[224:227], v165 offset:37888
	ds_read_b128 v[228:231], v165 offset:38912
	ds_read_b128 v[232:235], v165 offset:39936
	global_load_lds_dwordx4 v[242:243], off
	v_lshl_add_u64 v[242:243], s[76:77], 0, v[130:131]
	s_mov_b32 m0, s74
	s_nop 0
	global_load_lds_dwordx4 v[242:243], off
	s_waitcnt vmcnt(8)
	s_waitcnt lgkmcnt(0)
	s_barrier
	s_setprio 1
	s_waitcnt lgkmcnt(0)
	v_mfma_f32_16x16x32_bf16 v[126:129], v[148:151], v[202:205], v[126:129]
	v_mfma_f32_16x16x32_bf16 v[122:125], v[156:159], v[202:205], v[122:125]
	v_mfma_f32_16x16x32_bf16 v[110:113], v[148:151], v[212:215], v[110:113]
	v_mfma_f32_16x16x32_bf16 v[106:109], v[156:159], v[212:215], v[106:109]
	v_mfma_f32_16x16x32_bf16 v[94:97], v[148:151], v[220:223], v[94:97]
	v_mfma_f32_16x16x32_bf16 v[90:93], v[156:159], v[220:223], v[90:93]
	v_mfma_f32_16x16x32_bf16 v[78:81], v[148:151], v[228:231], v[78:81]
	v_mfma_f32_16x16x32_bf16 v[74:77], v[156:159], v[228:231], v[74:77]
	v_mfma_f32_16x16x32_bf16 v[126:129], v[152:155], v[208:211], v[126:129]
	v_mfma_f32_16x16x32_bf16 v[122:125], v[160:163], v[208:211], v[122:125]
	v_mfma_f32_16x16x32_bf16 v[110:113], v[152:155], v[216:219], v[110:113]
	v_mfma_f32_16x16x32_bf16 v[106:109], v[160:163], v[216:219], v[106:109]
	v_mfma_f32_16x16x32_bf16 v[94:97], v[152:155], v[224:227], v[94:97]
	v_mfma_f32_16x16x32_bf16 v[90:93], v[160:163], v[224:227], v[90:93]
	v_mfma_f32_16x16x32_bf16 v[78:81], v[152:155], v[232:235], v[78:81]
	v_mfma_f32_16x16x32_bf16 v[74:77], v[160:163], v[232:235], v[74:77]
	s_setprio 0
	s_setprio 1
	v_mfma_f32_16x16x32_bf16 v[118:121], v[166:169], v[202:205], v[118:121]
	v_mfma_f32_16x16x32_bf16 v[114:117], v[174:177], v[202:205], v[114:117]
	v_mfma_f32_16x16x32_bf16 v[102:105], v[166:169], v[212:215], v[102:105]
	v_mfma_f32_16x16x32_bf16 v[98:101], v[174:177], v[212:215], v[98:101]
	v_mfma_f32_16x16x32_bf16 v[86:89], v[166:169], v[220:223], v[86:89]
	v_mfma_f32_16x16x32_bf16 v[82:85], v[174:177], v[220:223], v[82:85]
	v_mfma_f32_16x16x32_bf16 v[70:73], v[166:169], v[228:231], v[70:73]
	v_mfma_f32_16x16x32_bf16 v[66:69], v[174:177], v[228:231], v[66:69]
	v_mfma_f32_16x16x32_bf16 v[118:121], v[170:173], v[208:211], v[118:121]
	v_mfma_f32_16x16x32_bf16 v[114:117], v[178:181], v[208:211], v[114:117]
	v_mfma_f32_16x16x32_bf16 v[102:105], v[170:173], v[216:219], v[102:105]
	v_mfma_f32_16x16x32_bf16 v[98:101], v[178:181], v[216:219], v[98:101]
	v_mfma_f32_16x16x32_bf16 v[86:89], v[170:173], v[224:227], v[86:89]
	v_mfma_f32_16x16x32_bf16 v[82:85], v[178:181], v[224:227], v[82:85]
	v_mfma_f32_16x16x32_bf16 v[70:73], v[170:173], v[232:235], v[70:73]
	v_mfma_f32_16x16x32_bf16 v[66:69], v[178:181], v[232:235], v[66:69]
	s_setprio 0
	s_barrier
	s_add_i32 s59, s59, s93
	v_lshl_add_u64 v[136:137], v[136:137], 0, s[66:67]
	s_mov_b32 m0, s59
	ds_read_b128 v[202:205], v165 offset:49152
	ds_read_b128 v[208:211], v165 offset:50176
	ds_read_b128 v[212:215], v165 offset:51200
	ds_read_b128 v[216:219], v165 offset:52224
	ds_read_b128 v[220:223], v165 offset:53248
	ds_read_b128 v[224:227], v165 offset:54272
	ds_read_b128 v[228:231], v165 offset:55296
	ds_read_b128 v[232:235], v165 offset:56320
	global_load_lds_dwordx4 v[136:137], off
	v_lshl_add_u64 v[136:137], v[144:145], 0, s[66:67]
	s_add_i32 m0, s59, 0x2000
	s_add_i32 s59, s83, s93
	global_load_lds_dwordx4 v[136:137], off
	v_lshl_add_u64 v[136:137], v[182:183], 0, s[66:67]
	s_mov_b32 m0, s59
	s_nop 0
	global_load_lds_dwordx4 v[136:137], off
	v_lshl_add_u64 v[136:137], v[236:237], 0, s[66:67]
	s_add_i32 m0, s59, 0x2000
	s_nop 0
	global_load_lds_dwordx4 v[136:137], off
	v_lshl_add_u64 v[136:137], v[238:239], 0, s[66:67]
	s_mov_b32 m0, s73
	s_nop 0
	global_load_lds_dwordx4 v[136:137], off
	v_lshl_add_u64 v[136:137], v[240:241], 0, s[66:67]
	s_mov_b32 m0, s50
	s_nop 0
	global_load_lds_dwordx4 v[136:137], off
	s_waitcnt vmcnt(8)
	s_waitcnt lgkmcnt(0)
	s_barrier
; #define PG8_STAGE(bufoff, gbase, voff) do { _Pragma("unroll") for (int _i = 0; _i < 2; ++_i) \
;         __builtin_amdgcn_global_load_lds((const unsigned*)((const char*)(gbase) + (voff)[_i]), (PG8_LAS unsigned*)(lds + (bufoff) + ldsw + _i * 8192), 16, 0, 0); } while (0)
; #define PG8_LDA(dst, b, h) do { _Pragma("unroll") for (int m = 0; m < 4; ++m) _Pragma("unroll") for (int k = 0; k < 2; ++k) dst[m][k] = *(const PG8_LAS bf16x8*)(lds + PG8_SA(b, h) + aoff + m * 2048 + k * 1024); } while (0)
; #define PG8_LDB(dst, b, h) do { _Pragma("unroll") for (int n = 0; n < 2; ++n) _Pragma("unroll") for (int k = 0; k < 2; ++k) dst[n][k] = *(const PG8_LAS bf16x8*)(lds + PG8_SB(b, h) + boff + n * 2048 + k * 1024); } while (0)
; #define PG8_MMA(ai, bj, At, Bt) do { __builtin_amdgcn_s_setprio(1); _Pragma("unroll") for (int m = 0; m < 4; ++m) _Pragma("unroll") for (int n = 0; n < 2; ++n) _Pragma("unroll") for (int k = 0; k < 2; ++k) \
;         acc[ai][bj][m][n] = __builtin_amdgcn_mfma_f32_16x16x32_bf16(Bt[n][k], At[m][k], acc[ai][bj][m][n], 0, 0, 0); __builtin_amdgcn_s_setprio(0); } while (0)
; #define PG8_WAIT_V(n) asm volatile("s_waitcnt vmcnt(" #n ")" ::: "memory")
; #define PG8_WAIT_L(n) asm volatile("s_waitcnt lgkmcnt(" #n ")" ::: "memory")
; #define PG8_BAR __builtin_amdgcn_s_barrier()
; #define PG8_SCHED __builtin_amdgcn_sched_barrier(0)
; template <class Epi, class Sched, bool ALIGN_EPI = false, bool SP2 = false>
; __device__ __forceinline__ void gemm_phase(PG8_LAS unsigned char* lds, const Gemm g, const Sched& S, const Epi& E) {
;     ...
;             PG8_LDB(B0, 0, 0); PG8_LDB(B1, 0, 1); PG8_SCHED; PG8_LDA(At, 0, 0); PG8_STAGE(PG8_SA(1, 1), a1 + hstep, voffA);
;             PG8_WAIT_V(8); PG8_WAIT_L(0); PG8_BAR; PG8_MMA(0, 0, At, B0); PG8_MMA(0, 1, At, B1); PG8_BAR; PG8_SCHED;
;     ...
;             PG8_LDA(At, 1, 1); PG8_STAGE(PG8_SB(1, 0), b3, voffB); PG8_STAGE(PG8_SB(1, 1), b3 + hstep, voffB); PG8_STAGE(PG8_SA(1, 0), a3, voffA);
;             PG8_WAIT_V(8); PG8_WAIT_L(0); PG8_BAR; PG8_MMA(1, 0, At, B0); PG8_MMA(1, 1, At, B1); PG8_BAR; PG8_SCHED;
	s_setprio 1
	s_waitcnt lgkmcnt(0)
	v_mfma_f32_16x16x32_bf16 v[62:65], v[148:151], v[202:205], v[62:65]
	v_mfma_f32_16x16x32_bf16 v[58:61], v[156:159], v[202:205], v[58:61]
	v_mfma_f32_16x16x32_bf16 v[46:49], v[148:151], v[212:215], v[46:49]
	v_mfma_f32_16x16x32_bf16 v[42:45], v[156:159], v[212:215], v[42:45]
	v_mfma_f32_16x16x32_bf16 v[30:33], v[148:151], v[220:223], v[30:33]
	v_mfma_f32_16x16x32_bf16 v[26:29], v[156:159], v[220:223], v[26:29]
	v_mfma_f32_16x16x32_bf16 v[14:17], v[148:151], v[228:231], v[14:17]
	v_mfma_f32_16x16x32_bf16 v[10:13], v[156:159], v[228:231], v[10:13]
	v_mfma_f32_16x16x32_bf16 v[62:65], v[152:155], v[208:211], v[62:65]
	v_mfma_f32_16x16x32_bf16 v[58:61], v[160:163], v[208:211], v[58:61]
	v_mfma_f32_16x16x32_bf16 v[46:49], v[152:155], v[216:219], v[46:49]
	v_mfma_f32_16x16x32_bf16 v[42:45], v[160:163], v[216:219], v[42:45]
	v_mfma_f32_16x16x32_bf16 v[30:33], v[152:155], v[224:227], v[30:33]
	v_mfma_f32_16x16x32_bf16 v[26:29], v[160:163], v[224:227], v[26:29]
	v_mfma_f32_16x16x32_bf16 v[14:17], v[152:155], v[232:235], v[14:17]
	v_mfma_f32_16x16x32_bf16 v[10:13], v[160:163], v[232:235], v[10:13]
	s_setprio 0
	s_setprio 1
	v_mfma_f32_16x16x32_bf16 v[54:57], v[166:169], v[202:205], v[54:57]
	v_mfma_f32_16x16x32_bf16 v[50:53], v[174:177], v[202:205], v[50:53]
	v_mfma_f32_16x16x32_bf16 v[38:41], v[166:169], v[212:215], v[38:41]
	v_mfma_f32_16x16x32_bf16 v[34:37], v[174:177], v[212:215], v[34:37]
	v_mfma_f32_16x16x32_bf16 v[22:25], v[166:169], v[220:223], v[22:25]
	v_mfma_f32_16x16x32_bf16 v[18:21], v[174:177], v[220:223], v[18:21]
	v_mfma_f32_16x16x32_bf16 v[6:9], v[166:169], v[228:231], v[6:9]
	v_mfma_f32_16x16x32_bf16 v[2:5], v[174:177], v[228:231], v[2:5]
	v_mfma_f32_16x16x32_bf16 v[54:57], v[170:173], v[208:211], v[54:57]
	v_mfma_f32_16x16x32_bf16 v[50:53], v[178:181], v[208:211], v[50:53]
	v_mfma_f32_16x16x32_bf16 v[38:41], v[170:173], v[216:219], v[38:41]
	v_mfma_f32_16x16x32_bf16 v[34:37], v[178:181], v[216:219], v[34:37]
	v_mfma_f32_16x16x32_bf16 v[22:25], v[170:173], v[224:227], v[22:25]
	v_mfma_f32_16x16x32_bf16 v[18:21], v[178:181], v[224:227], v[18:21]
	v_mfma_f32_16x16x32_bf16 v[6:9], v[170:173], v[232:235], v[6:9]
	v_mfma_f32_16x16x32_bf16 v[2:5], v[178:181], v[232:235], v[2:5]
	s_setprio 0
	s_barrier
	s_add_u32 s48, s48, 0x100
	s_addc_u32 s49, s49, 0
	s_add_u32 s80, s80, 0x100
	s_addc_u32 s81, s81, 0
	s_cmp_ge_u32 s82, s79
	s_mov_b32 s76, s82
	s_cbranch_scc0 .LBB0_849
	s_branch .Lkr_exit
.Lkr_a0:
	s_add_i32 s82, s76, 2
	s_add_u32 s83, s48, 0x80
	s_addc_u32 s77, s49, 0
	s_add_i32 s59, 0, 0x10000
	s_cmp_eq_u32 s72, s76
	s_cselect_b32 s77, s9, s77
	s_cselect_b32 s76, s8, s83
	v_add_u32_e32 v136, s59, v147
	s_cselect_b32 vcc_hi, s47, s81
	s_cselect_b32 vcc_lo, s46, s80
	s_add_i32 s83, 0, 0x14000
	ds_read_b128 v[148:151], v136
	ds_read_b128 v[152:155], v136 offset:1024
	ds_read_b128 v[156:159], v136 offset:2048
	ds_read_b128 v[160:163], v136 offset:3072
	v_add_u32_e32 v136, s83, v147
	ds_read_b128 v[166:169], v136
	ds_read_b128 v[170:173], v136 offset:1024
	ds_read_b128 v[174:177], v136 offset:2048
	ds_read_b128 v[178:181], v136 offset:3072
	v_lshl_add_u64 v[136:137], s[48:49], 0, v[132:133]
	s_add_i32 m0, s94, 0xc000
	ds_read_b128 v[202:205], v165
	ds_read_b128 v[208:211], v165 offset:1024
	ds_read_b128 v[212:215], v165 offset:2048
	ds_read_b128 v[216:219], v165 offset:3072
	ds_read_b128 v[220:223], v165 offset:4096
	ds_read_b128 v[224:227], v165 offset:5120
	ds_read_b128 v[228:231], v165 offset:6144
	ds_read_b128 v[232:235], v165 offset:7168
	v_lshl_add_u64 v[136:137], s[48:49], 0, v[134:135]
	s_add_i32 m0, s94, 0xe000
	s_nop 0
	s_waitcnt vmcnt(6)
	s_waitcnt lgkmcnt(0)
	s_barrier
	s_setprio 1
	s_waitcnt lgkmcnt(0)
	v_mfma_f32_16x16x32_bf16 v[126:129], v[148:151], v[202:205], v[126:129]
	v_mfma_f32_16x16x32_bf16 v[122:125], v[156:159], v[202:205], v[122:125]
	v_mfma_f32_16x16x32_bf16 v[110:113], v[148:151], v[212:215], v[110:113]
	v_mfma_f32_16x16x32_bf16 v[106:109], v[156:159], v[212:215], v[106:109]
	v_mfma_f32_16x16x32_bf16 v[94:97], v[148:151], v[220:223], v[94:97]
	v_mfma_f32_16x16x32_bf16 v[90:93], v[156:159], v[220:223], v[90:93]
	v_mfma_f32_16x16x32_bf16 v[78:81], v[148:151], v[228:231], v[78:81]
	v_mfma_f32_16x16x32_bf16 v[74:77], v[156:159], v[228:231], v[74:77]
	v_mfma_f32_16x16x32_bf16 v[126:129], v[152:155], v[208:211], v[126:129]
	v_mfma_f32_16x16x32_bf16 v[122:125], v[160:163], v[208:211], v[122:125]
	v_mfma_f32_16x16x32_bf16 v[110:113], v[152:155], v[216:219], v[110:113]
	v_mfma_f32_16x16x32_bf16 v[106:109], v[160:163], v[216:219], v[106:109]
	v_mfma_f32_16x16x32_bf16 v[94:97], v[152:155], v[224:227], v[94:97]
	v_mfma_f32_16x16x32_bf16 v[90:93], v[160:163], v[224:227], v[90:93]
	v_mfma_f32_16x16x32_bf16 v[78:81], v[152:155], v[232:235], v[78:81]
	v_mfma_f32_16x16x32_bf16 v[74:77], v[160:163], v[232:235], v[74:77]
	s_setprio 0
	s_setprio 1
	v_mfma_f32_16x16x32_bf16 v[118:121], v[166:169], v[202:205], v[118:121]
	v_mfma_f32_16x16x32_bf16 v[114:117], v[174:177], v[202:205], v[114:117]
	v_mfma_f32_16x16x32_bf16 v[102:105], v[166:169], v[212:215], v[102:105]
	v_mfma_f32_16x16x32_bf16 v[98:101], v[174:177], v[212:215], v[98:101]
	v_mfma_f32_16x16x32_bf16 v[86:89], v[166:169], v[220:223], v[86:89]
	v_mfma_f32_16x16x32_bf16 v[82:85], v[174:177], v[220:223], v[82:85]
	v_mfma_f32_16x16x32_bf16 v[70:73], v[166:169], v[228:231], v[70:73]
	v_mfma_f32_16x16x32_bf16 v[66:69], v[174:177], v[228:231], v[66:69]
	v_mfma_f32_16x16x32_bf16 v[118:121], v[170:173], v[208:211], v[118:121]
	v_mfma_f32_16x16x32_bf16 v[114:117], v[178:181], v[208:211], v[114:117]
	v_mfma_f32_16x16x32_bf16 v[102:105], v[170:173], v[216:219], v[102:105]
	v_mfma_f32_16x16x32_bf16 v[98:101], v[178:181], v[216:219], v[98:101]
	v_mfma_f32_16x16x32_bf16 v[86:89], v[170:173], v[224:227], v[86:89]
	v_mfma_f32_16x16x32_bf16 v[82:85], v[178:181], v[224:227], v[82:85]
	v_mfma_f32_16x16x32_bf16 v[70:73], v[170:173], v[232:235], v[70:73]
	v_mfma_f32_16x16x32_bf16 v[66:69], v[178:181], v[232:235], v[66:69]
	s_setprio 0
	s_barrier
; #define PG8_STAGE(bufoff, gbase, voff) do { _Pragma("unroll") for (int _i = 0; _i < 2; ++_i) \
;         __builtin_amdgcn_global_load_lds((const unsigned*)((const char*)(gbase) + (voff)[_i]), (PG8_LAS unsigned*)(lds + (bufoff) + ldsw + _i * 8192), 16, 0, 0); } while (0)
; #define PG8_LDA(dst, b, h) do { _Pragma("unroll") for (int m = 0; m < 4; ++m) _Pragma("unroll") for (int k = 0; k < 2; ++k) dst[m][k] = *(const PG8_LAS bf16x8*)(lds + PG8_SA(b, h) + aoff + m * 2048 + k * 1024); } while (0)
; #define PG8_LDB(dst, b, h) do { _Pragma("unroll") for (int n = 0; n < 2; ++n) _Pragma("unroll") for (int k = 0; k < 2; ++k) dst[n][k] = *(const PG8_LAS bf16x8*)(lds + PG8_SB(b, h) + boff + n * 2048 + k * 1024); } while (0)
; #define PG8_MMA(ai, bj, At, Bt) do { __builtin_amdgcn_s_setprio(1); _Pragma("unroll") for (int m = 0; m < 4; ++m) _Pragma("unroll") for (int n = 0; n < 2; ++n) _Pragma("unroll") for (int k = 0; k < 2; ++k) \
;         acc[ai][bj][m][n] = __builtin_amdgcn_mfma_f32_16x16x32_bf16(Bt[n][k], At[m][k], acc[ai][bj][m][n], 0, 0, 0); __builtin_amdgcn_s_setprio(0); } while (0)
; #define PG8_WAIT_V(n) asm volatile("s_waitcnt vmcnt(" #n ")" ::: "memory")
; #define PG8_WAIT_L(n) asm volatile("s_waitcnt lgkmcnt(" #n ")" ::: "memory")
; #define PG8_BAR __builtin_amdgcn_s_barrier()
; #define PG8_SCHED __builtin_amdgcn_sched_barrier(0)
; template <class Epi, class Sched, bool ALIGN_EPI = false, bool SP2 = false>
; __device__ __forceinline__ void gemm_phase(PG8_LAS unsigned char* lds, const Gemm g, const Sched& S, const Epi& E) {
;     ...
;             PG8_LDA(At, 0, 1); PG8_STAGE(PG8_SB(0, 0), b2, voffB); PG8_STAGE(PG8_SB(0, 1), b2 + hstep, voffB); PG8_STAGE(PG8_SA(0, 0), a2, voffA);
;             PG8_WAIT_V(8); PG8_WAIT_L(0); PG8_BAR; PG8_MMA(1, 0, At, B0); PG8_MMA(1, 1, At, B1); PG8_BAR; PG8_SCHED;
;             PG8_LDB(B0, 1, 0); PG8_LDB(B1, 1, 1); PG8_SCHED; PG8_LDA(At, 1, 0); PG8_STAGE(PG8_SA(0, 1), a2 + hstep, voffA);
;             PG8_WAIT_V(8); PG8_WAIT_L(0); PG8_BAR; PG8_MMA(0, 0, At, B0); PG8_MMA(0, 1, At, B1); PG8_BAR; PG8_SCHED;
;             PG8_LDA(At, 1, 1); PG8_STAGE(PG8_SB(1, 0), b3, voffB); PG8_STAGE(PG8_SB(1, 1), b3 + hstep, voffB); PG8_STAGE(PG8_SA(1, 0), a3, voffA);
;             PG8_WAIT_V(8); PG8_WAIT_L(0); PG8_BAR; PG8_MMA(1, 0, At, B0); PG8_MMA(1, 1, At, B1); PG8_BAR; PG8_SCHED;
	s_add_i32 s59, s59, s93
	v_lshl_add_u64 v[136:137], vcc, 0, v[0:1]
	s_mov_b32 m0, s59
	global_load_lds_dwordx4 v[136:137], off
	s_add_i32 m0, s59, 0x2000
	v_lshl_add_u64 v[144:145], vcc, 0, v[130:131]
	s_add_u32 vcc_lo, vcc_lo, s10
	s_addc_u32 vcc_hi, vcc_hi, 0
	s_add_i32 s59, s83, s93
	global_load_lds_dwordx4 v[144:145], off
	v_lshl_add_u64 v[182:183], vcc, 0, v[0:1]
	s_mov_b32 m0, s59
	v_lshl_add_u64 v[236:237], vcc, 0, v[130:131]
	global_load_lds_dwordx4 v[182:183], off
	s_add_i32 m0, s59, 0x2000
	v_lshl_add_u64 v[238:239], s[76:77], 0, v[0:1]
	global_load_lds_dwordx4 v[236:237], off
	s_mov_b32 m0, s94
	v_lshl_add_u64 v[240:241], s[76:77], 0, v[130:131]
	global_load_lds_dwordx4 v[238:239], off
	s_mov_b32 m0, s95
	s_nop 0
	global_load_lds_dwordx4 v[240:241], off
	s_waitcnt vmcnt(6)
	s_waitcnt lgkmcnt(0)
	s_barrier
	s_setprio 1
	s_waitcnt lgkmcnt(0)
	s_setprio 0
	s_setprio 1
	s_setprio 0
	s_barrier
	s_add_i32 s59, 0, 0x18000
	s_add_i32 s83, 0, 0x1c000
	v_add_u32_e32 v160, s59, v147
	v_add_u32_e32 v178, s83, v147
	ds_read_b128 v[148:151], v160
	ds_read_b128 v[152:155], v160 offset:1024
	ds_read_b128 v[156:159], v160 offset:2048
	ds_read_b128 v[160:163], v160 offset:3072
	ds_read_b128 v[166:169], v178
	ds_read_b128 v[170:173], v178 offset:1024
	ds_read_b128 v[174:177], v178 offset:2048
	ds_read_b128 v[178:181], v178 offset:3072
	s_add_u32 s76, s76, s10
	s_addc_u32 s77, s77, 0
	s_mov_b32 m0, s84
	v_lshl_add_u64 v[242:243], s[76:77], 0, v[0:1]
	ds_read_b128 v[202:205], v165 offset:32768
	ds_read_b128 v[208:211], v165 offset:33792
	ds_read_b128 v[212:215], v165 offset:34816
	ds_read_b128 v[216:219], v165 offset:35840
	ds_read_b128 v[220:223], v165 offset:36864
	ds_read_b128 v[224:227], v165 offset:37888
	ds_read_b128 v[228:231], v165 offset:38912
	ds_read_b128 v[232:235], v165 offset:39936
	v_lshl_add_u64 v[242:243], s[76:77], 0, v[130:131]
	s_mov_b32 m0, s74
	s_nop 0
	s_waitcnt vmcnt(6)
	s_waitcnt lgkmcnt(0)
	s_barrier
	s_setprio 1
	s_waitcnt lgkmcnt(0)
	v_mfma_f32_16x16x32_bf16 v[126:129], v[148:151], v[202:205], v[126:129]
	v_mfma_f32_16x16x32_bf16 v[122:125], v[156:159], v[202:205], v[122:125]
	v_mfma_f32_16x16x32_bf16 v[110:113], v[148:151], v[212:215], v[110:113]
	v_mfma_f32_16x16x32_bf16 v[106:109], v[156:159], v[212:215], v[106:109]
	v_mfma_f32_16x16x32_bf16 v[94:97], v[148:151], v[220:223], v[94:97]
	v_mfma_f32_16x16x32_bf16 v[90:93], v[156:159], v[220:223], v[90:93]
	v_mfma_f32_16x16x32_bf16 v[78:81], v[148:151], v[228:231], v[78:81]
	v_mfma_f32_16x16x32_bf16 v[74:77], v[156:159], v[228:231], v[74:77]
	v_mfma_f32_16x16x32_bf16 v[126:129], v[152:155], v[208:211], v[126:129]
	v_mfma_f32_16x16x32_bf16 v[122:125], v[160:163], v[208:211], v[122:125]
	v_mfma_f32_16x16x32_bf16 v[110:113], v[152:155], v[216:219], v[110:113]
	v_mfma_f32_16x16x32_bf16 v[106:109], v[160:163], v[216:219], v[106:109]
	v_mfma_f32_16x16x32_bf16 v[94:97], v[152:155], v[224:227], v[94:97]
	v_mfma_f32_16x16x32_bf16 v[90:93], v[160:163], v[224:227], v[90:93]
	v_mfma_f32_16x16x32_bf16 v[78:81], v[152:155], v[232:235], v[78:81]
	v_mfma_f32_16x16x32_bf16 v[74:77], v[160:163], v[232:235], v[74:77]
	s_setprio 0
	s_setprio 1
	v_mfma_f32_16x16x32_bf16 v[118:121], v[166:169], v[202:205], v[118:121]
	v_mfma_f32_16x16x32_bf16 v[114:117], v[174:177], v[202:205], v[114:117]
	v_mfma_f32_16x16x32_bf16 v[102:105], v[166:169], v[212:215], v[102:105]
	v_mfma_f32_16x16x32_bf16 v[98:101], v[174:177], v[212:215], v[98:101]
	v_mfma_f32_16x16x32_bf16 v[86:89], v[166:169], v[220:223], v[86:89]
	v_mfma_f32_16x16x32_bf16 v[82:85], v[174:177], v[220:223], v[82:85]
	v_mfma_f32_16x16x32_bf16 v[70:73], v[166:169], v[228:231], v[70:73]
	v_mfma_f32_16x16x32_bf16 v[66:69], v[174:177], v[228:231], v[66:69]
	v_mfma_f32_16x16x32_bf16 v[118:121], v[170:173], v[208:211], v[118:121]
	v_mfma_f32_16x16x32_bf16 v[114:117], v[178:181], v[208:211], v[114:117]
	v_mfma_f32_16x16x32_bf16 v[102:105], v[170:173], v[216:219], v[102:105]
	v_mfma_f32_16x16x32_bf16 v[98:101], v[178:181], v[216:219], v[98:101]
	v_mfma_f32_16x16x32_bf16 v[86:89], v[170:173], v[224:227], v[86:89]
	v_mfma_f32_16x16x32_bf16 v[82:85], v[178:181], v[224:227], v[82:85]
	v_mfma_f32_16x16x32_bf16 v[70:73], v[170:173], v[232:235], v[70:73]
	v_mfma_f32_16x16x32_bf16 v[66:69], v[178:181], v[232:235], v[66:69]
	s_setprio 0
	s_barrier
	s_add_i32 s59, s59, s93
	v_lshl_add_u64 v[136:137], v[136:137], 0, s[66:67]
	s_mov_b32 m0, s59
	global_load_lds_dwordx4 v[136:137], off
	v_lshl_add_u64 v[136:137], v[144:145], 0, s[66:67]
	s_add_i32 m0, s59, 0x2000
	s_add_i32 s59, s83, s93
	global_load_lds_dwordx4 v[136:137], off
	v_lshl_add_u64 v[136:137], v[182:183], 0, s[66:67]
	s_mov_b32 m0, s59
	s_nop 0
	global_load_lds_dwordx4 v[136:137], off
	v_lshl_add_u64 v[136:137], v[236:237], 0, s[66:67]
	s_add_i32 m0, s59, 0x2000
	s_nop 0
	global_load_lds_dwordx4 v[136:137], off
	v_lshl_add_u64 v[136:137], v[238:239], 0, s[66:67]
	s_mov_b32 m0, s73
	s_nop 0
	global_load_lds_dwordx4 v[136:137], off
	v_lshl_add_u64 v[136:137], v[240:241], 0, s[66:67]
	s_mov_b32 m0, s50
	s_nop 0
	global_load_lds_dwordx4 v[136:137], off
	s_waitcnt vmcnt(6)
	s_waitcnt lgkmcnt(0)
	s_barrier
	s_setprio 1
	s_waitcnt lgkmcnt(0)
	s_setprio 0
	s_setprio 1
	s_setprio 0
	s_barrier
	s_add_u32 s48, s48, 0x100
	s_addc_u32 s49, s49, 0
	s_add_u32 s80, s80, 0x100
	s_addc_u32 s81, s81, 0
	s_cmp_ge_u32 s82, s79
	s_mov_b32 s76, s82
	s_cbranch_scc0 .Lkr_a0
	s_branch .Lkr_exit
; #define PG8_STAGE(bufoff, gbase, voff) do { _Pragma("unroll") for (int _i = 0; _i < 2; ++_i) \
;         __builtin_amdgcn_global_load_lds((const unsigned*)((const char*)(gbase) + (voff)[_i]), (PG8_LAS unsigned*)(lds + (bufoff) + ldsw + _i * 8192), 16, 0, 0); } while (0)
; #define PG8_LDA(dst, b, h) do { _Pragma("unroll") for (int m = 0; m < 4; ++m) _Pragma("unroll") for (int k = 0; k < 2; ++k) dst[m][k] = *(const PG8_LAS bf16x8*)(lds + PG8_SA(b, h) + aoff + m * 2048 + k * 1024); } while (0)
; #define PG8_LDB(dst, b, h) do { _Pragma("unroll") for (int n = 0; n < 2; ++n) _Pragma("unroll") for (int k = 0; k < 2; ++k) dst[n][k] = *(const PG8_LAS bf16x8*)(lds + PG8_SB(b, h) + boff + n * 2048 + k * 1024); } while (0)
; #define PG8_MMA(ai, bj, At, Bt) do { __builtin_amdgcn_s_setprio(1); _Pragma("unroll") for (int m = 0; m < 4; ++m) _Pragma("unroll") for (int n = 0; n < 2; ++n) _Pragma("unroll") for (int k = 0; k < 2; ++k) \
;         acc[ai][bj][m][n] = __builtin_amdgcn_mfma_f32_16x16x32_bf16(Bt[n][k], At[m][k], acc[ai][bj][m][n], 0, 0, 0); __builtin_amdgcn_s_setprio(0); } while (0)
; #define PG8_WAIT_V(n) asm volatile("s_waitcnt vmcnt(" #n ")" ::: "memory")
; #define PG8_WAIT_L(n) asm volatile("s_waitcnt lgkmcnt(" #n ")" ::: "memory")
; #define PG8_BAR __builtin_amdgcn_s_barrier()
; #define PG8_SCHED __builtin_amdgcn_sched_barrier(0)
; template <class Epi, class Sched, bool ALIGN_EPI = false, bool SP2 = false>
; __device__ __forceinline__ void gemm_phase(PG8_LAS unsigned char* lds, const Gemm g, const Sched& S, const Epi& E) {
;     ...
;             PG8_LDB(B0, 0, 0); PG8_LDB(B1, 0, 1); PG8_SCHED; PG8_LDA(At, 0, 0); PG8_STAGE(PG8_SA(1, 1), a1 + hstep, voffA);
;             PG8_WAIT_V(8); PG8_WAIT_L(0); PG8_BAR; PG8_MMA(0, 0, At, B0); PG8_MMA(0, 1, At, B1); PG8_BAR; PG8_SCHED;
;             PG8_LDA(At, 0, 1); PG8_STAGE(PG8_SB(0, 0), b2, voffB); PG8_STAGE(PG8_SB(0, 1), b2 + hstep, voffB); PG8_STAGE(PG8_SA(0, 0), a2, voffA);
;             PG8_WAIT_V(8); PG8_WAIT_L(0); PG8_BAR; PG8_MMA(1, 0, At, B0); PG8_MMA(1, 1, At, B1); PG8_BAR; PG8_SCHED;
.Lkr_a1:
	s_add_i32 s82, s76, 2
	s_add_u32 s83, s48, 0x80
	s_addc_u32 s77, s49, 0
	s_add_i32 s59, 0, 0x10000
	s_cmp_eq_u32 s72, s76
	s_cselect_b32 s77, s9, s77
	s_cselect_b32 s76, s8, s83
	v_add_u32_e32 v136, s59, v147
	s_cselect_b32 vcc_hi, s47, s81
	s_cselect_b32 vcc_lo, s46, s80
	s_add_i32 s83, 0, 0x14000
	ds_read_b128 v[148:151], v136
	ds_read_b128 v[152:155], v136 offset:1024
	ds_read_b128 v[156:159], v136 offset:2048
	ds_read_b128 v[160:163], v136 offset:3072
	v_add_u32_e32 v136, s83, v147
	ds_read_b128 v[166:169], v136
	ds_read_b128 v[170:173], v136 offset:1024
	ds_read_b128 v[174:177], v136 offset:2048
	ds_read_b128 v[178:181], v136 offset:3072
	v_lshl_add_u64 v[136:137], s[48:49], 0, v[132:133]
	s_add_i32 m0, s94, 0xc000
	global_load_lds_dwordx4 v[136:137], off
	v_lshl_add_u64 v[136:137], s[48:49], 0, v[134:135]
	s_add_i32 m0, s94, 0xe000
	s_nop 0
	global_load_lds_dwordx4 v[136:137], off
	s_waitcnt vmcnt(6)
	s_waitcnt lgkmcnt(0)
	s_barrier
	s_setprio 1
	s_waitcnt lgkmcnt(0)
	s_setprio 0
	s_setprio 1
	s_setprio 0
	s_barrier
	s_add_i32 s59, s59, s93
	v_lshl_add_u64 v[136:137], vcc, 0, v[0:1]
	s_mov_b32 m0, s59
	ds_read_b128 v[202:205], v165 offset:16384
	ds_read_b128 v[208:211], v165 offset:17408
	ds_read_b128 v[212:215], v165 offset:18432
	ds_read_b128 v[216:219], v165 offset:19456
	ds_read_b128 v[220:223], v165 offset:20480
	ds_read_b128 v[224:227], v165 offset:21504
	ds_read_b128 v[228:231], v165 offset:22528
	ds_read_b128 v[232:235], v165 offset:23552
	global_load_lds_dwordx4 v[136:137], off
	s_add_i32 m0, s59, 0x2000
	v_lshl_add_u64 v[144:145], vcc, 0, v[130:131]
	s_add_u32 vcc_lo, vcc_lo, s10
	s_addc_u32 vcc_hi, vcc_hi, 0
	s_add_i32 s59, s83, s93
	global_load_lds_dwordx4 v[144:145], off
	v_lshl_add_u64 v[182:183], vcc, 0, v[0:1]
	s_mov_b32 m0, s59
	v_lshl_add_u64 v[236:237], vcc, 0, v[130:131]
	global_load_lds_dwordx4 v[182:183], off
	s_add_i32 m0, s59, 0x2000
	v_lshl_add_u64 v[238:239], s[76:77], 0, v[0:1]
	global_load_lds_dwordx4 v[236:237], off
	s_mov_b32 m0, s94
	v_lshl_add_u64 v[240:241], s[76:77], 0, v[130:131]
	s_mov_b32 m0, s95
	s_nop 0
	s_waitcnt vmcnt(6)
	s_waitcnt lgkmcnt(0)
	s_barrier
	s_setprio 1
	s_waitcnt lgkmcnt(0)
	v_mfma_f32_16x16x32_bf16 v[62:65], v[148:151], v[202:205], v[62:65]
	v_mfma_f32_16x16x32_bf16 v[58:61], v[156:159], v[202:205], v[58:61]
	v_mfma_f32_16x16x32_bf16 v[46:49], v[148:151], v[212:215], v[46:49]
	v_mfma_f32_16x16x32_bf16 v[42:45], v[156:159], v[212:215], v[42:45]
	v_mfma_f32_16x16x32_bf16 v[30:33], v[148:151], v[220:223], v[30:33]
	v_mfma_f32_16x16x32_bf16 v[26:29], v[156:159], v[220:223], v[26:29]
	v_mfma_f32_16x16x32_bf16 v[14:17], v[148:151], v[228:231], v[14:17]
	v_mfma_f32_16x16x32_bf16 v[10:13], v[156:159], v[228:231], v[10:13]
	v_mfma_f32_16x16x32_bf16 v[62:65], v[152:155], v[208:211], v[62:65]
	v_mfma_f32_16x16x32_bf16 v[58:61], v[160:163], v[208:211], v[58:61]
	v_mfma_f32_16x16x32_bf16 v[46:49], v[152:155], v[216:219], v[46:49]
	v_mfma_f32_16x16x32_bf16 v[42:45], v[160:163], v[216:219], v[42:45]
	v_mfma_f32_16x16x32_bf16 v[30:33], v[152:155], v[224:227], v[30:33]
	v_mfma_f32_16x16x32_bf16 v[26:29], v[160:163], v[224:227], v[26:29]
	v_mfma_f32_16x16x32_bf16 v[14:17], v[152:155], v[232:235], v[14:17]
	v_mfma_f32_16x16x32_bf16 v[10:13], v[160:163], v[232:235], v[10:13]
	s_setprio 0
	s_setprio 1
	v_mfma_f32_16x16x32_bf16 v[54:57], v[166:169], v[202:205], v[54:57]
	v_mfma_f32_16x16x32_bf16 v[50:53], v[174:177], v[202:205], v[50:53]
	v_mfma_f32_16x16x32_bf16 v[38:41], v[166:169], v[212:215], v[38:41]
	v_mfma_f32_16x16x32_bf16 v[34:37], v[174:177], v[212:215], v[34:37]
	v_mfma_f32_16x16x32_bf16 v[22:25], v[166:169], v[220:223], v[22:25]
	v_mfma_f32_16x16x32_bf16 v[18:21], v[174:177], v[220:223], v[18:21]
	v_mfma_f32_16x16x32_bf16 v[6:9], v[166:169], v[228:231], v[6:9]
	v_mfma_f32_16x16x32_bf16 v[2:5], v[174:177], v[228:231], v[2:5]
	v_mfma_f32_16x16x32_bf16 v[54:57], v[170:173], v[208:211], v[54:57]
	v_mfma_f32_16x16x32_bf16 v[50:53], v[178:181], v[208:211], v[50:53]
	v_mfma_f32_16x16x32_bf16 v[38:41], v[170:173], v[216:219], v[38:41]
	v_mfma_f32_16x16x32_bf16 v[34:37], v[178:181], v[216:219], v[34:37]
	v_mfma_f32_16x16x32_bf16 v[22:25], v[170:173], v[224:227], v[22:25]
	v_mfma_f32_16x16x32_bf16 v[18:21], v[178:181], v[224:227], v[18:21]
	v_mfma_f32_16x16x32_bf16 v[6:9], v[170:173], v[232:235], v[6:9]
	v_mfma_f32_16x16x32_bf16 v[2:5], v[178:181], v[232:235], v[2:5]
	s_setprio 0
	s_barrier
; #define PG8_STAGE(bufoff, gbase, voff) do { _Pragma("unroll") for (int _i = 0; _i < 2; ++_i) \
;         __builtin_amdgcn_global_load_lds((const unsigned*)((const char*)(gbase) + (voff)[_i]), (PG8_LAS unsigned*)(lds + (bufoff) + ldsw + _i * 8192), 16, 0, 0); } while (0)
; #define PG8_LDA(dst, b, h) do { _Pragma("unroll") for (int m = 0; m < 4; ++m) _Pragma("unroll") for (int k = 0; k < 2; ++k) dst[m][k] = *(const PG8_LAS bf16x8*)(lds + PG8_SA(b, h) + aoff + m * 2048 + k * 1024); } while (0)
; #define PG8_LDB(dst, b, h) do { _Pragma("unroll") for (int n = 0; n < 2; ++n) _Pragma("unroll") for (int k = 0; k < 2; ++k) dst[n][k] = *(const PG8_LAS bf16x8*)(lds + PG8_SB(b, h) + boff + n * 2048 + k * 1024); } while (0)
; #define PG8_MMA(ai, bj, At, Bt) do { __builtin_amdgcn_s_setprio(1); _Pragma("unroll") for (int m = 0; m < 4; ++m) _Pragma("unroll") for (int n = 0; n < 2; ++n) _Pragma("unroll") for (int k = 0; k < 2; ++k) \
;         acc[ai][bj][m][n] = __builtin_amdgcn_mfma_f32_16x16x32_bf16(Bt[n][k], At[m][k], acc[ai][bj][m][n], 0, 0, 0); __builtin_amdgcn_s_setprio(0); } while (0)
; #define PG8_WAIT_V(n) asm volatile("s_waitcnt vmcnt(" #n ")" ::: "memory")
; #define PG8_WAIT_L(n) asm volatile("s_waitcnt lgkmcnt(" #n ")" ::: "memory")
; #define PG8_BAR __builtin_amdgcn_s_barrier()
; #define PG8_SCHED __builtin_amdgcn_sched_barrier(0)
; template <class Epi, class Sched, bool ALIGN_EPI = false, bool SP2 = false>
; __device__ __forceinline__ void gemm_phase(PG8_LAS unsigned char* lds, const Gemm g, const Sched& S, const Epi& E) {
;     ...
;             PG8_LDB(B0, 1, 0); PG8_LDB(B1, 1, 1); PG8_SCHED; PG8_LDA(At, 1, 0); PG8_STAGE(PG8_SA(0, 1), a2 + hstep, voffA);
;             PG8_WAIT_V(8); PG8_WAIT_L(0); PG8_BAR; PG8_MMA(0, 0, At, B0); PG8_MMA(0, 1, At, B1); PG8_BAR; PG8_SCHED;
;             PG8_LDA(At, 1, 1); PG8_STAGE(PG8_SB(1, 0), b3, voffB); PG8_STAGE(PG8_SB(1, 1), b3 + hstep, voffB); PG8_STAGE(PG8_SA(1, 0), a3, voffA);
;             PG8_WAIT_V(8); PG8_WAIT_L(0); PG8_BAR; PG8_MMA(1, 0, At, B0); PG8_MMA(1, 1, At, B1); PG8_BAR; PG8_SCHED;
	s_add_i32 s59, 0, 0x18000
	s_add_i32 s83, 0, 0x1c000
	v_add_u32_e32 v160, s59, v147
	v_add_u32_e32 v178, s83, v147
	ds_read_b128 v[148:151], v160
	ds_read_b128 v[152:155], v160 offset:1024
	ds_read_b128 v[156:159], v160 offset:2048
	ds_read_b128 v[160:163], v160 offset:3072
	ds_read_b128 v[166:169], v178
	ds_read_b128 v[170:173], v178 offset:1024
	ds_read_b128 v[174:177], v178 offset:2048
	ds_read_b128 v[178:181], v178 offset:3072
	s_add_u32 s76, s76, s10
	s_addc_u32 s77, s77, 0
	s_mov_b32 m0, s84
	v_lshl_add_u64 v[242:243], s[76:77], 0, v[0:1]
	global_load_lds_dwordx4 v[242:243], off
	v_lshl_add_u64 v[242:243], s[76:77], 0, v[130:131]
	s_mov_b32 m0, s74
	s_nop 0
	global_load_lds_dwordx4 v[242:243], off
	s_waitcnt vmcnt(6)
	s_waitcnt lgkmcnt(0)
	s_barrier
	s_setprio 1
	s_waitcnt lgkmcnt(0)
	s_setprio 0
	s_setprio 1
	s_setprio 0
	s_barrier
	s_add_i32 s59, s59, s93
	v_lshl_add_u64 v[136:137], v[136:137], 0, s[66:67]
	s_mov_b32 m0, s59
	ds_read_b128 v[202:205], v165 offset:49152
	ds_read_b128 v[208:211], v165 offset:50176
	ds_read_b128 v[212:215], v165 offset:51200
	ds_read_b128 v[216:219], v165 offset:52224
	ds_read_b128 v[220:223], v165 offset:53248
	ds_read_b128 v[224:227], v165 offset:54272
	ds_read_b128 v[228:231], v165 offset:55296
	ds_read_b128 v[232:235], v165 offset:56320
	global_load_lds_dwordx4 v[136:137], off
	v_lshl_add_u64 v[136:137], v[144:145], 0, s[66:67]
	s_add_i32 m0, s59, 0x2000
	s_add_i32 s59, s83, s93
	global_load_lds_dwordx4 v[136:137], off
	v_lshl_add_u64 v[136:137], v[182:183], 0, s[66:67]
	s_mov_b32 m0, s59
	s_nop 0
	global_load_lds_dwordx4 v[136:137], off
	v_lshl_add_u64 v[136:137], v[236:237], 0, s[66:67]
	s_add_i32 m0, s59, 0x2000
	s_nop 0
	global_load_lds_dwordx4 v[136:137], off
	v_lshl_add_u64 v[136:137], v[238:239], 0, s[66:67]
	s_mov_b32 m0, s73
	s_nop 0
	v_lshl_add_u64 v[136:137], v[240:241], 0, s[66:67]
	s_mov_b32 m0, s50
	s_nop 0
	s_waitcnt vmcnt(6)
	s_waitcnt lgkmcnt(0)
	s_barrier
	s_setprio 1
	s_waitcnt lgkmcnt(0)
	v_mfma_f32_16x16x32_bf16 v[62:65], v[148:151], v[202:205], v[62:65]
	v_mfma_f32_16x16x32_bf16 v[58:61], v[156:159], v[202:205], v[58:61]
	v_mfma_f32_16x16x32_bf16 v[46:49], v[148:151], v[212:215], v[46:49]
	v_mfma_f32_16x16x32_bf16 v[42:45], v[156:159], v[212:215], v[42:45]
	v_mfma_f32_16x16x32_bf16 v[30:33], v[148:151], v[220:223], v[30:33]
	v_mfma_f32_16x16x32_bf16 v[26:29], v[156:159], v[220:223], v[26:29]
	v_mfma_f32_16x16x32_bf16 v[14:17], v[148:151], v[228:231], v[14:17]
	v_mfma_f32_16x16x32_bf16 v[10:13], v[156:159], v[228:231], v[10:13]
	v_mfma_f32_16x16x32_bf16 v[62:65], v[152:155], v[208:211], v[62:65]
	v_mfma_f32_16x16x32_bf16 v[58:61], v[160:163], v[208:211], v[58:61]
	v_mfma_f32_16x16x32_bf16 v[46:49], v[152:155], v[216:219], v[46:49]
	v_mfma_f32_16x16x32_bf16 v[42:45], v[160:163], v[216:219], v[42:45]
	v_mfma_f32_16x16x32_bf16 v[30:33], v[152:155], v[224:227], v[30:33]
	v_mfma_f32_16x16x32_bf16 v[26:29], v[160:163], v[224:227], v[26:29]
	v_mfma_f32_16x16x32_bf16 v[14:17], v[152:155], v[232:235], v[14:17]
	v_mfma_f32_16x16x32_bf16 v[10:13], v[160:163], v[232:235], v[10:13]
	s_setprio 0
	s_setprio 1
	v_mfma_f32_16x16x32_bf16 v[54:57], v[166:169], v[202:205], v[54:57]
	v_mfma_f32_16x16x32_bf16 v[50:53], v[174:177], v[202:205], v[50:53]
	v_mfma_f32_16x16x32_bf16 v[38:41], v[166:169], v[212:215], v[38:41]
	v_mfma_f32_16x16x32_bf16 v[34:37], v[174:177], v[212:215], v[34:37]
	v_mfma_f32_16x16x32_bf16 v[22:25], v[166:169], v[220:223], v[22:25]
	v_mfma_f32_16x16x32_bf16 v[18:21], v[174:177], v[220:223], v[18:21]
	v_mfma_f32_16x16x32_bf16 v[6:9], v[166:169], v[228:231], v[6:9]
	v_mfma_f32_16x16x32_bf16 v[2:5], v[174:177], v[228:231], v[2:5]
	v_mfma_f32_16x16x32_bf16 v[54:57], v[170:173], v[208:211], v[54:57]
	v_mfma_f32_16x16x32_bf16 v[50:53], v[178:181], v[208:211], v[50:53]
	v_mfma_f32_16x16x32_bf16 v[38:41], v[170:173], v[216:219], v[38:41]
	v_mfma_f32_16x16x32_bf16 v[34:37], v[178:181], v[216:219], v[34:37]
	v_mfma_f32_16x16x32_bf16 v[22:25], v[170:173], v[224:227], v[22:25]
	v_mfma_f32_16x16x32_bf16 v[18:21], v[178:181], v[224:227], v[18:21]
	v_mfma_f32_16x16x32_bf16 v[6:9], v[170:173], v[232:235], v[6:9]
	v_mfma_f32_16x16x32_bf16 v[2:5], v[178:181], v[232:235], v[2:5]
	s_setprio 0
	s_barrier
	s_add_u32 s48, s48, 0x100
	s_addc_u32 s49, s49, 0
	s_add_u32 s80, s80, 0x100
	s_addc_u32 s81, s81, 0
	s_cmp_ge_u32 s82, s79
	s_mov_b32 s76, s82
	s_cbranch_scc0 .Lkr_a1
.Lkr_exit:
	s_and_b64 vcc, exec, s[44:45]
	s_cbranch_vccz .LBB0_852
	s_barrier

;     __device__ __forceinline__ void operator()(const f32x4 (&acc)[2][2][4][2], const Unit& u, int wr, int wc, int fr, int fq) const {
;         const bool lat = u.pm < 64; const int mr = lat ? (u.pm >> 3) : 8;
;         const float* sp = lat ? srclat : srcctx; float* dp = lat ? dstlat : dstctx;
;         const int col0 = u.pn * 256 + wc * 32 + 8 * fq;
;         const size_t off0 = (size_t)((lat ? u.pm : u.pm - 64) * 256 + wr * 64 + fr) * DM + col0;
;         sp += off0; dp += off0;
;         const float* gp = gate + (size_t)mr * 9216 + col0;
;         f32x4 gv[2][2];
; #pragma unroll
;         for (int bj = 0; bj < 2; ++bj)
; #pragma unroll
;             for (int n = 0; n < 2; ++n) gv[bj][n] = *(const f32x4*)(gp + bj * 128 + n * 4) * scale;
; #pragma unroll
;         for (int ai = 0; ai < 2; ++ai)
; #pragma unroll
;             for (int m = 0; m < 4; ++m) {
;                 const int ro = (ai * 128 + m * 16) * DM;
;                 f32x4 s[2][2];
; #pragma unroll
;                 for (int bj = 0; bj < 2; ++bj)
; #pragma unroll
;                     for (int n = 0; n < 2; ++n) s[bj][n] = *(const f32x4*)(sp + ro + bj * 128 + n * 4);
; #pragma unroll
;                 for (int bj = 0; bj < 2; ++bj)
; #pragma unroll
;                     for (int n = 0; n < 2; ++n) *(f32x4*)(dp + ro + bj * 128 + n * 4) = s[bj][n] + gv[bj][n] * acc[ai][bj][m][n];
.LBB0_854:
	s_lshl_b32 s52, s52, 8
	s_add_i32 s59, s52, 0xffffc000
	s_and_b64 s[82:83], s[82:83], exec
	s_cselect_b32 s52, s52, s59
	s_lshl_b64 s[76:77], s[76:77], 2
	v_lshl_or_b32 v136, s62, 8, v164
	s_add_u32 s76, s75, s76
	v_ashrrev_i32_e32 v137, 31, v136
	s_addc_u32 s77, s78, s77
	v_lshl_add_u64 v[170:171], v[136:137], 2, s[76:77]
	global_load_dwordx4 v[148:151], v[170:171], off offset:16
	global_load_dwordx4 v[152:155], v[170:171], off
	v_add_u32_e32 v144, s52, v143
	v_ashrrev_i32_e32 v145, 31, v144
	v_lshlrev_b64 v[144:145], 10, v[144:145]
	v_lshl_add_u64 v[144:145], v[144:145], 0, v[136:137]
	v_lshlrev_b64 v[162:163], 2, v[144:145]
	v_lshl_add_u64 v[156:157], s[80:81], 0, v[162:163]
	v_lshl_add_u64 v[162:163], s[48:49], 0, v[162:163]
	s_mov_b64 s[48:49], 0x10000
	s_mov_b32 s52, 0x10000
	s_mov_b32 s0, 0x30000
	s_mov_b32 s61, 0xb0000
	s_waitcnt vmcnt(0)
	v_pk_mul_f32 v[136:137], s[42:43], v[150:151]
	v_pk_mul_f32 v[144:145], s[2:3], v[148:149]
	global_load_dwordx4 v[166:169], v[170:171], off offset:528
	global_load_dwordx4 v[148:151], v[170:171], off offset:512
	v_pk_mul_f32 v[158:159], s[42:43], v[154:155]
	v_pk_mul_f32 v[160:161], s[2:3], v[152:153]
	s_waitcnt vmcnt(0)
	v_pk_mul_f32 v[152:153], s[42:43], v[150:151]
	v_pk_mul_f32 v[154:155], s[2:3], v[148:149]
	v_pk_mul_f32 v[148:149], s[42:43], v[168:169]
	v_pk_mul_f32 v[150:151], s[2:3], v[166:167]
	s_cmp_eq_u32 s101, 2
	s_cbranch_scc1 .Lkr_epi_skip0
	global_load_dwordx4 v[166:169], v[156:157], off offset:16
	global_load_dwordx4 v[170:173], v[156:157], off
	global_load_dwordx4 v[174:177], v[156:157], off offset:528
	global_load_dwordx4 v[178:181], v[156:157], off offset:512
	s_waitcnt vmcnt(3)
	v_pk_fma_f32 v[124:125], v[124:125], v[136:137], v[168:169]
	s_waitcnt vmcnt(2)
	v_pk_fma_f32 v[128:129], v[128:129], v[158:159], v[172:173]
	v_pk_fma_f32 v[126:127], v[126:127], v[160:161], v[170:171]
	v_pk_fma_f32 v[122:123], v[122:123], v[144:145], v[166:167]
	s_waitcnt vmcnt(0)
	v_pk_fma_f32 v[120:121], v[120:121], v[152:153], v[180:181]
	v_pk_fma_f32 v[118:119], v[118:119], v[154:155], v[178:179]
	v_pk_fma_f32 v[116:117], v[116:117], v[148:149], v[176:177]
	v_pk_fma_f32 v[114:115], v[114:115], v[150:151], v[174:175]
	global_store_dwordx4 v[162:163], v[126:129], off
	global_store_dwordx4 v[162:163], v[122:125], off offset:16
	global_store_dwordx4 v[162:163], v[118:121], off offset:512
	global_store_dwordx4 v[162:163], v[114:117], off offset:528
	v_add_co_u32_e32 v122, vcc, s52, v156
	v_lshl_add_u64 v[118:119], v[156:157], 0, s[48:49]
	s_mov_b64 s[48:49], 0x10200
	v_addc_co_u32_e32 v123, vcc, 0, v157, vcc
	v_lshl_add_u64 v[126:127], v[156:157], 0, s[48:49]
	global_load_dwordx4 v[114:117], v[122:123], off
	s_nop 0
	global_load_dwordx4 v[118:121], v[118:119], off offset:16
	s_nop 0
	global_load_dwordx4 v[122:125], v[122:123], off offset:512
	s_nop 0
	global_load_dwordx4 v[126:129], v[126:127], off offset:16
	s_mov_b64 s[48:49], 0x20000
	s_waitcnt vmcnt(3)
	v_pk_fma_f32 v[110:111], v[110:111], v[160:161], v[114:115]
	v_add_co_u32_e32 v114, vcc, s52, v162
	v_pk_fma_f32 v[112:113], v[112:113], v[158:159], v[116:117]
	s_nop 0
	v_addc_co_u32_e32 v115, vcc, 0, v163, vcc
	s_waitcnt vmcnt(2)
	v_pk_fma_f32 v[108:109], v[108:109], v[136:137], v[120:121]
	v_pk_fma_f32 v[106:107], v[106:107], v[144:145], v[118:119]
	s_waitcnt vmcnt(1)
	v_pk_fma_f32 v[104:105], v[104:105], v[152:153], v[124:125]
	v_pk_fma_f32 v[102:103], v[102:103], v[154:155], v[122:123]
	s_waitcnt vmcnt(0)
	v_pk_fma_f32 v[100:101], v[100:101], v[148:149], v[128:129]
	v_pk_fma_f32 v[98:99], v[98:99], v[150:151], v[126:127]
	s_mov_b32 s52, 0x20000
	global_store_dwordx4 v[114:115], v[110:113], off
	global_store_dwordx4 v[114:115], v[106:109], off offset:16
	global_store_dwordx4 v[114:115], v[102:105], off offset:512
	global_store_dwordx4 v[114:115], v[98:101], off offset:528
	v_add_co_u32_e32 v106, vcc, s52, v156
	v_lshl_add_u64 v[102:103], v[156:157], 0, s[48:49]
	s_mov_b64 s[48:49], 0x20200
	v_addc_co_u32_e32 v107, vcc, 0, v157, vcc
	v_lshl_add_u64 v[110:111], v[156:157], 0, s[48:49]
	global_load_dwordx4 v[98:101], v[106:107], off
	s_nop 0
	global_load_dwordx4 v[102:105], v[102:103], off offset:16
	s_nop 0
	global_load_dwordx4 v[106:109], v[106:107], off offset:512
	s_nop 0
	global_load_dwordx4 v[110:113], v[110:111], off offset:16
	s_mov_b64 s[48:49], 0x30000
	s_waitcnt vmcnt(3)
	v_pk_fma_f32 v[94:95], v[94:95], v[160:161], v[98:99]
	v_add_co_u32_e32 v98, vcc, s52, v162
	v_pk_fma_f32 v[96:97], v[96:97], v[158:159], v[100:101]
	s_nop 0
	v_addc_co_u32_e32 v99, vcc, 0, v163, vcc
	s_waitcnt vmcnt(2)
	v_pk_fma_f32 v[92:93], v[92:93], v[136:137], v[104:105]
	v_pk_fma_f32 v[90:91], v[90:91], v[144:145], v[102:103]
	s_waitcnt vmcnt(1)
	v_pk_fma_f32 v[88:89], v[88:89], v[152:153], v[108:109]
	v_pk_fma_f32 v[86:87], v[86:87], v[154:155], v[106:107]
	s_waitcnt vmcnt(0)
	v_pk_fma_f32 v[84:85], v[84:85], v[148:149], v[112:113]
	v_pk_fma_f32 v[82:83], v[82:83], v[150:151], v[110:111]
	global_store_dwordx4 v[98:99], v[94:97], off
	global_store_dwordx4 v[98:99], v[90:93], off offset:16
	global_store_dwordx4 v[98:99], v[86:89], off offset:512
	global_store_dwordx4 v[98:99], v[82:85], off offset:528
	v_add_co_u32_e32 v90, vcc, s68, v156
	v_lshl_add_u64 v[86:87], v[156:157], 0, s[48:49]
	s_mov_b64 s[48:49], 0x30200
	v_addc_co_u32_e32 v91, vcc, 0, v157, vcc
	v_lshl_add_u64 v[94:95], v[156:157], 0, s[48:49]
	global_load_dwordx4 v[82:85], v[90:91], off
	s_nop 0
	global_load_dwordx4 v[86:89], v[86:87], off offset:16
	s_nop 0
	global_load_dwordx4 v[90:93], v[90:91], off offset:512
	s_nop 0
	global_load_dwordx4 v[94:97], v[94:95], off offset:16
	s_mov_b64 s[48:49], 0x80000
	s_mov_b32 s52, 0x80000
	s_waitcnt vmcnt(3)
	v_pk_fma_f32 v[78:79], v[78:79], v[160:161], v[82:83]
	v_add_co_u32_e32 v82, vcc, s68, v162
	v_pk_fma_f32 v[80:81], v[80:81], v[158:159], v[84:85]
	s_nop 0
	v_addc_co_u32_e32 v83, vcc, 0, v163, vcc
	s_waitcnt vmcnt(2)
	v_pk_fma_f32 v[76:77], v[76:77], v[136:137], v[88:89]
	v_pk_fma_f32 v[74:75], v[74:75], v[144:145], v[86:87]
	s_waitcnt vmcnt(1)
	v_pk_fma_f32 v[72:73], v[72:73], v[152:153], v[92:93]
	v_pk_fma_f32 v[70:71], v[70:71], v[154:155], v[90:91]
	s_waitcnt vmcnt(0)
	v_pk_fma_f32 v[68:69], v[68:69], v[148:149], v[96:97]
	v_pk_fma_f32 v[66:67], v[66:67], v[150:151], v[94:95]
	global_store_dwordx4 v[82:83], v[78:81], off
	global_store_dwordx4 v[82:83], v[74:77], off offset:16
	global_store_dwordx4 v[82:83], v[70:73], off offset:512
	global_store_dwordx4 v[82:83], v[66:69], off offset:528
	s_cmp_eq_u32 s101, 1
	s_cbranch_scc1 .Lkr_epi_skip1
	s_branch .Lkr_epi_g4
;     __device__ __forceinline__ void operator()(const f32x4 (&acc)[2][2][4][2], const Unit& u, int wr, int wc, int fr, int fq) const {
;     ...
; #pragma unroll
;         for (int ai = 0; ai < 2; ++ai)
; #pragma unroll
;             for (int m = 0; m < 4; ++m) {
;                 const int ro = (ai * 128 + m * 16) * DM;
;                 f32x4 s[2][2];
; #pragma unroll
;                 for (int bj = 0; bj < 2; ++bj)
; #pragma unroll
;                     for (int n = 0; n < 2; ++n) s[bj][n] = *(const f32x4*)(sp + ro + bj * 128 + n * 4);
; #pragma unroll
;                 for (int bj = 0; bj < 2; ++bj)
; #pragma unroll
;                     for (int n = 0; n < 2; ++n) *(f32x4*)(dp + ro + bj * 128 + n * 4) = s[bj][n] + gv[bj][n] * acc[ai][bj][m][n];
.Lkr_epi_skip0:
	s_mov_b64 s[48:49], 0x80000
	s_mov_b32 s52, 0x80000
.Lkr_epi_g4:
	v_add_co_u32_e32 v74, vcc, s52, v156
	v_lshl_add_u64 v[70:71], v[156:157], 0, s[48:49]
	s_mov_b64 s[48:49], 0x80200
	v_addc_co_u32_e32 v75, vcc, 0, v157, vcc
	v_lshl_add_u64 v[78:79], v[156:157], 0, s[48:49]
	global_load_dwordx4 v[66:69], v[74:75], off
	s_nop 0
	global_load_dwordx4 v[70:73], v[70:71], off offset:16
	s_nop 0
	global_load_dwordx4 v[74:77], v[74:75], off offset:512
	s_nop 0
	global_load_dwordx4 v[78:81], v[78:79], off offset:16
	s_mov_b64 s[48:49], 0x90000
	s_waitcnt vmcnt(3)
	v_pk_fma_f32 v[62:63], v[62:63], v[160:161], v[66:67]
	v_add_co_u32_e32 v66, vcc, s52, v162
	v_pk_fma_f32 v[64:65], v[64:65], v[158:159], v[68:69]
	s_nop 0
	v_addc_co_u32_e32 v67, vcc, 0, v163, vcc
	s_waitcnt vmcnt(2)
	v_pk_fma_f32 v[60:61], v[60:61], v[136:137], v[72:73]
	v_pk_fma_f32 v[58:59], v[58:59], v[144:145], v[70:71]
	s_waitcnt vmcnt(1)
	v_pk_fma_f32 v[56:57], v[56:57], v[152:153], v[76:77]
	v_pk_fma_f32 v[54:55], v[54:55], v[154:155], v[74:75]
	s_waitcnt vmcnt(0)
	v_pk_fma_f32 v[52:53], v[52:53], v[148:149], v[80:81]
	v_pk_fma_f32 v[50:51], v[50:51], v[150:151], v[78:79]
	s_mov_b32 s52, 0x90000
	global_store_dwordx4 v[66:67], v[62:65], off
	global_store_dwordx4 v[66:67], v[58:61], off offset:16
	global_store_dwordx4 v[66:67], v[54:57], off offset:512
	global_store_dwordx4 v[66:67], v[50:53], off offset:528
	v_add_co_u32_e32 v58, vcc, s52, v156
	v_lshl_add_u64 v[54:55], v[156:157], 0, s[48:49]
	s_mov_b64 s[48:49], 0x90200
	v_addc_co_u32_e32 v59, vcc, 0, v157, vcc
	v_lshl_add_u64 v[62:63], v[156:157], 0, s[48:49]
	global_load_dwordx4 v[50:53], v[58:59], off
	s_nop 0
	global_load_dwordx4 v[54:57], v[54:55], off offset:16
	s_nop 0
	global_load_dwordx4 v[58:61], v[58:59], off offset:512
	s_nop 0
	global_load_dwordx4 v[62:65], v[62:63], off offset:16
	s_mov_b64 s[48:49], 0xa0000
	s_waitcnt vmcnt(3)
	v_pk_fma_f32 v[46:47], v[46:47], v[160:161], v[50:51]
	v_add_co_u32_e32 v50, vcc, s52, v162
	v_pk_fma_f32 v[48:49], v[48:49], v[158:159], v[52:53]
	s_nop 0
	v_addc_co_u32_e32 v51, vcc, 0, v163, vcc
	s_waitcnt vmcnt(2)
	v_pk_fma_f32 v[44:45], v[44:45], v[136:137], v[56:57]
	v_pk_fma_f32 v[42:43], v[42:43], v[144:145], v[54:55]
	s_waitcnt vmcnt(1)
	v_pk_fma_f32 v[40:41], v[40:41], v[152:153], v[60:61]
	v_pk_fma_f32 v[38:39], v[38:39], v[154:155], v[58:59]
	s_waitcnt vmcnt(0)
	v_pk_fma_f32 v[36:37], v[36:37], v[148:149], v[64:65]
	v_pk_fma_f32 v[34:35], v[34:35], v[150:151], v[62:63]
	s_mov_b32 s52, 0xa0000
	global_store_dwordx4 v[50:51], v[46:49], off
	global_store_dwordx4 v[50:51], v[42:45], off offset:16
	global_store_dwordx4 v[50:51], v[38:41], off offset:512
	global_store_dwordx4 v[50:51], v[34:37], off offset:528
	v_add_co_u32_e32 v42, vcc, s52, v156
	v_lshl_add_u64 v[38:39], v[156:157], 0, s[48:49]
	s_mov_b64 s[48:49], 0xa0200
	v_addc_co_u32_e32 v43, vcc, 0, v157, vcc
	v_lshl_add_u64 v[46:47], v[156:157], 0, s[48:49]
	global_load_dwordx4 v[34:37], v[42:43], off
	s_nop 0
	global_load_dwordx4 v[38:41], v[38:39], off offset:16
	s_nop 0
	global_load_dwordx4 v[42:45], v[42:43], off offset:512
	s_nop 0
	global_load_dwordx4 v[46:49], v[46:47], off offset:16
	s_mov_b64 s[48:49], 0xb0000
	s_waitcnt vmcnt(3)
	v_pk_fma_f32 v[30:31], v[30:31], v[160:161], v[34:35]
	v_add_co_u32_e32 v34, vcc, s52, v162
	v_pk_fma_f32 v[32:33], v[32:33], v[158:159], v[36:37]
	s_nop 0
	v_addc_co_u32_e32 v35, vcc, 0, v163, vcc
	s_waitcnt vmcnt(2)
	v_pk_fma_f32 v[28:29], v[28:29], v[136:137], v[40:41]
	v_pk_fma_f32 v[26:27], v[26:27], v[144:145], v[38:39]
	s_waitcnt vmcnt(1)
	v_pk_fma_f32 v[24:25], v[24:25], v[152:153], v[44:45]
	v_pk_fma_f32 v[22:23], v[22:23], v[154:155], v[42:43]
	s_waitcnt vmcnt(0)
	v_pk_fma_f32 v[20:21], v[20:21], v[148:149], v[48:49]
	v_pk_fma_f32 v[18:19], v[18:19], v[150:151], v[46:47]
	s_mov_b32 s52, 0xb0000
	global_store_dwordx4 v[34:35], v[30:33], off
	global_store_dwordx4 v[34:35], v[26:29], off offset:16
	global_store_dwordx4 v[34:35], v[22:25], off offset:512
	global_store_dwordx4 v[34:35], v[18:21], off offset:528
	v_add_co_u32_e32 v26, vcc, s52, v156
	v_lshl_add_u64 v[22:23], v[156:157], 0, s[48:49]
	s_mov_b64 s[48:49], 0xb0200
	v_addc_co_u32_e32 v27, vcc, 0, v157, vcc
	v_lshl_add_u64 v[30:31], v[156:157], 0, s[48:49]
	global_load_dwordx4 v[18:21], v[26:27], off
	s_nop 0
	global_load_dwordx4 v[22:25], v[22:23], off offset:16
	s_nop 0
	global_load_dwordx4 v[26:29], v[26:27], off offset:512
	s_nop 0
	global_load_dwordx4 v[30:33], v[30:31], off offset:16
	s_mov_b64 s[48:49], -1
	s_waitcnt vmcnt(3)
	v_pk_fma_f32 v[14:15], v[14:15], v[160:161], v[18:19]
	v_add_co_u32_e32 v18, vcc, s52, v162
	v_pk_fma_f32 v[16:17], v[16:17], v[158:159], v[20:21]
	s_nop 0
	v_addc_co_u32_e32 v19, vcc, 0, v163, vcc
	s_waitcnt vmcnt(2)
	v_pk_fma_f32 v[12:13], v[12:13], v[136:137], v[24:25]
	v_pk_fma_f32 v[10:11], v[10:11], v[144:145], v[22:23]
	s_waitcnt vmcnt(1)
	v_pk_fma_f32 v[8:9], v[8:9], v[152:153], v[28:29]
	v_pk_fma_f32 v[6:7], v[6:7], v[154:155], v[26:27]
	s_waitcnt vmcnt(0)
	v_pk_fma_f32 v[4:5], v[4:5], v[148:149], v[32:33]
	v_pk_fma_f32 v[2:3], v[2:3], v[150:151], v[30:31]
	global_store_dwordx4 v[18:19], v[14:17], off
	global_store_dwordx4 v[18:19], v[10:13], off offset:16
	global_store_dwordx4 v[18:19], v[6:9], off offset:512
	global_store_dwordx4 v[18:19], v[2:5], off offset:528
	s_branch .Lkr_epi_end
.Lkr_epi_skip1:
	s_mov_b64 s[48:49], -1
.Lkr_epi_end:
	s_and_b64 vcc, exec, s[6:7]
	s_cbranch_vccnz .LBB0_841
	s_andn2_b64 vcc, exec, s[28:29]
	s_cbranch_vccnz .LBB0_840
	s_barrier
	s_branch .LBB0_840

; __global__ void __launch_bounds__(NTHREADS) mega_fwd(P p) {
;     ...
;                     const int nbusy = (RM / 256) * 4 - G;
;                     const unsigned tmask = cs == 0 ? 0x300u : (cs == 1 ? 0x022u : (cs == 2 ? 0x044u : (cs == 3 ? 0xC88u : 0u)));
;                     if (tmask && nbusy > 0 && nbusy < G && (int)blockIdx.x >= nbusy) { __syncthreads(); run_transposes(q, lds, wave, lane, tmask, ((int)blockIdx.x - nbusy) * 8 + wave, (G - nbusy) * 8); }
;                     else if (tmask && !(nbusy > 0 && nbusy < G)) { __syncthreads(); run_transposes(q, lds, wave, lane, tmask, (int)blockIdx.x * 8 + wave, G * 8); }
.LBB0_867:
	s_sub_i32 s34, s64, s38
	s_lshl_b32 s31, s34, 1
	s_cmp_lt_i32 s34, 1
	s_cbranch_scc1 .Lnb_done
	s_cmp_gt_u32 s31, s38
	s_cbranch_scc1 .Lnb_done
	s_mov_b32 s34, s31
.Lnb_done:
	s_ashr_i32 s31, s28, 6
	s_cmp_lg_u32 s30, 0
	s_cselect_b64 s[2:3], -1, 0
	s_cmp_gt_i32 s34, 0
	s_cselect_b64 s[6:7], -1, 0
	s_cmp_gt_i32 s38, s34
	s_cselect_b64 s[8:9], -1, 0
	s_cmp_ge_i32 s90, s34
	s_cselect_b64 s[10:11], -1, 0
	s_and_b64 s[6:7], s[8:9], s[6:7]
	s_and_b64 s[8:9], s[6:7], s[10:11]
	s_and_b64 s[8:9], s[2:3], s[8:9]
	v_and_b32_e32 v20, 63, v146
	s_andn2_b64 vcc, exec, s[8:9]
	s_mov_b64 s[8:9], -1
	s_cbranch_vccz .LBB0_899
	s_xor_b64 s[2:3], s[2:3], -1
	s_or_b64 s[2:3], s[2:3], s[6:7]
	s_and_b64 vcc, exec, s[2:3]
	s_cbranch_vccnz .LBB0_898
	v_lshlrev_b32_e32 v4, 3, v20
	s_mul_i32 s2, s31, 0x2100
	v_lshrrev_b32_e32 v24, 3, v20
	v_and_b32_e32 v4, 56, v4
	s_add_i32 s2, s2, 0
	v_mul_u32_u24_e32 v5, 0x84, v4
	v_lshlrev_b32_e32 v6, 2, v24
	v_lshrrev_b32_e32 v22, 5, v20
	v_add3_u32 v25, s2, v5, v6
	v_lshrrev_b32_e32 v5, 2, v146
	v_and_b32_e32 v29, 4, v5
	v_mul_u32_u24_e32 v5, 33, v22
	v_and_b32_e32 v21, 31, v146
	v_lshlrev_b32_e32 v5, 2, v5
	v_lshlrev_b32_e32 v0, 2, v20
	v_lshlrev_b32_e32 v2, 2, v21
	v_add_u32_e32 v6, s2, v5
	v_add_u32_e32 v3, s2, v2
	v_add_u32_e32 v30, v6, v2
	v_or_b32_e32 v2, 0x1080, v0
	v_add_u32_e32 v32, v6, v2
	v_bfe_i32 v2, v146, 4, 1
	v_and_b32_e32 v33, 0xb00, v2
	v_lshlrev_b32_e32 v2, 2, v22
	s_movk_i32 s3, 0x84
	v_add3_u32 v35, s2, v0, v2
	v_readlane_b32 s2, v253, 55
	v_lshlrev_b32_e32 v0, 1, v4
	v_mad_u32_u24 v23, v22, s3, v3
	s_add_i32 s35, s2, s31
	v_lshl_add_u64 v[12:13], s[26:27], 0, v[0:1]
	s_mov_b64 s[2:3], 0x4e00000
	v_add_u32_e32 v31, v3, v5
	v_lshl_add_u64 v[2:3], v[12:13], 0, s[2:3]
	s_mov_b64 s[2:3], 0x4c00000
	v_lshl_add_u64 v[4:5], v[12:13], 0, s[2:3]
	s_mov_b64 s[2:3], 0x4400000
	v_lshl_add_u64 v[6:7], v[12:13], 0, s[2:3]
	s_mov_b64 s[2:3], 0x5100000
	v_lshl_add_u64 v[8:9], v[12:13], 0, s[2:3]
	s_mov_b64 s[2:3], 0x2e00000
	v_lshl_add_u64 v[10:11], v[12:13], 0, s[2:3]
	s_mov_b64 s[2:3], 0x200000
	v_or_b32_e32 v26, 8, v24
	v_or_b32_e32 v27, 16, v24
	v_or_b32_e32 v28, 24, v24
	v_and_b32_e32 v34, 3, v146
	v_lshl_add_u64 v[12:13], v[12:13], 0, s[2:3]
	v_lshlrev_b32_e32 v36, 1, v21
	s_mov_b32 s40, 0
	s_mov_b32 s41, 0
	s_barrier
	s_branch .LBB0_872

; __global__ void __launch_bounds__(NTHREADS) mega_fwd(P p) {
;     extern __shared__ __attribute__((aligned(16))) unsigned char lds[];
	.amdhsa_kernel _Z8mega_fwd1P
		.amdhsa_group_segment_fixed_size 0
		.amdhsa_private_segment_fixed_size 0
		.amdhsa_kernarg_size 432
		.amdhsa_user_sgpr_count 2
		.amdhsa_user_sgpr_dispatch_ptr 0
		.amdhsa_user_sgpr_queue_ptr 0
		.amdhsa_user_sgpr_kernarg_segment_ptr 1
		.amdhsa_user_sgpr_dispatch_id 0
		.amdhsa_user_sgpr_kernarg_preload_length 0
		.amdhsa_user_sgpr_kernarg_preload_offset 0
		.amdhsa_user_sgpr_private_segment_size 0
		.amdhsa_uses_dynamic_stack 0
		.amdhsa_enable_private_segment 0
		.amdhsa_system_sgpr_workgroup_id_x 1
		.amdhsa_system_sgpr_workgroup_id_y 0
		.amdhsa_system_sgpr_workgroup_id_z 0
		.amdhsa_system_sgpr_workgroup_info 0
		.amdhsa_system_vgpr_workitem_id 2
		.amdhsa_next_free_vgpr 256
		.amdhsa_next_free_sgpr 102
		.amdhsa_accum_offset 256
		.amdhsa_reserve_vcc 1
		.amdhsa_float_round_mode_32 0
		.amdhsa_float_round_mode_16_64 0
		.amdhsa_float_denorm_mode_32 3
		.amdhsa_float_denorm_mode_16_64 3
		.amdhsa_dx10_clamp 1
		.amdhsa_ieee_mode 1
		.amdhsa_fp16_overflow 0
		.amdhsa_tg_split 0
		.amdhsa_exception_fp_ieee_invalid_op 0
		.amdhsa_exception_fp_denorm_src 0
		.amdhsa_exception_fp_ieee_div_zero 0
		.amdhsa_exception_fp_ieee_overflow 0
		.amdhsa_exception_fp_ieee_underflow 0
		.amdhsa_exception_fp_ieee_inexact 0
		.amdhsa_exception_int_div_zero 0
	.end_amdhsa_kernel

; __global__ void __launch_bounds__(NTHREADS) mega_fwd(P p) {
;     extern __shared__ __attribute__((aligned(16))) unsigned char lds[];
amdhsa.kernels:
  - .agpr_count:     0
    .args:
      - .offset:         0
        .size:           176
        .value_kind:     by_value
      - .offset:         176
        .size:           4
        .value_kind:     hidden_block_count_x
      - .offset:         180
        .size:           4
        .value_kind:     hidden_block_count_y
      - .offset:         184
        .size:           4
        .value_kind:     hidden_block_count_z
      - .offset:         188
        .size:           2
        .value_kind:     hidden_group_size_x
      - .offset:         190
        .size:           2
        .value_kind:     hidden_group_size_y
      - .offset:         192
        .size:           2
        .value_kind:     hidden_group_size_z
      - .offset:         194
        .size:           2
        .value_kind:     hidden_remainder_x
      - .offset:         196
        .size:           2
        .value_kind:     hidden_remainder_y
      - .offset:         198
        .size:           2
        .value_kind:     hidden_remainder_z
      - .offset:         216
        .size:           8
        .value_kind:     hidden_global_offset_x
      - .offset:         224
        .size:           8
        .value_kind:     hidden_global_offset_y
      - .offset:         232
        .size:           8
        .value_kind:     hidden_global_offset_z
      - .offset:         240
        .size:           2
        .value_kind:     hidden_grid_dims
      - .offset:         264
        .size:           8
        .value_kind:     hidden_multigrid_sync_arg
      - .offset:         296
        .size:           4
        .value_kind:     hidden_dynamic_lds_size
    .group_segment_fixed_size: 0
    .kernarg_segment_align: 8
    .kernarg_segment_size: 432
    .language:       OpenCL C
    .language_version:
      - 2
      - 0
    .max_flat_workgroup_size: 512
    .name:           _Z8mega_fwd1P
    .private_segment_fixed_size: 0
    .sgpr_count:     108
    .sgpr_spill_count: 194
    .symbol:         _Z8mega_fwd1P.kd
    .uniform_work_group_size: 1
    .uses_dynamic_stack: false
    .vgpr_count:     256
    .vgpr_spill_count: 0
    .wavefront_size: 64
